# K-loop handoff: setprio before barrier, redundant lgkmcnt removed, barrier before setprio0; first-iteration vmcnt relaxed after epilogue stores (G1,G2,G6); XCC census loads batched
# speedup vs baseline: 1.0155x; 1.0155x over previous
; __device__ __forceinline__ unsigned xb_ld(unsigned* p)              { return __hip_atomic_load(p, __ATOMIC_RELAXED, __HIP_MEMORY_SCOPE_AGENT); }
; __global__ void __launch_bounds__(512, 2) fwd_megakernel(Args a_unused) {
;     ...
;     {
;         unsigned* ctl = (unsigned*)((KArgs*)__builtin_amdgcn_kernarg_segment_ptr())->ws;
;         bool even = (G % 8) == 0;
; #pragma unroll
;         for (int j = 0; j < 8; ++j) even = even && (xb_ld(&ctl[3584 + 64 * j]) == (unsigned)(G / 8));
;         vcu = even ? (int)(bst[2] * 8u + xbar.x) : (int)blockIdx.x;
;         vcu = __builtin_amdgcn_readfirstlane(vcu);
;         xlocal = even;
;     }
.LBB0_81:
	s_or_b64 exec, exec, s[4:5]
	s_and_b32 s3, s52, 7
	s_cmp_lg_u32 s3, 0
	s_mov_b64 s[4:5], 0
	s_barrier
	s_cbranch_scc1 .LBB0_90
	v_mov_b32_e32 v0, 0x3000
	global_load_dword v1, v0, s[54:55] offset:2048 sc1
	global_load_dword v2, v0, s[54:55] offset:2304 sc1
	global_load_dword v3, v0, s[54:55] offset:2560 sc1
	global_load_dword v4, v0, s[54:55] offset:2816 sc1
	global_load_dword v5, v0, s[54:55] offset:3072 sc1
	global_load_dword v6, v0, s[54:55] offset:3328 sc1
	global_load_dword v7, v0, s[54:55] offset:3584 sc1
	global_load_dword v9, v0, s[54:55] offset:3840 sc1
	s_ashr_i32 s3, s52, 31
	s_lshr_b32 s3, s3, 29
	s_add_i32 s3, s52, s3
	s_ashr_i32 s3, s3, 3
	s_waitcnt vmcnt(0)
	v_cmp_eq_u32_e32 vcc, s3, v1
	s_and_b64 s[4:5], vcc, exec
	v_cmp_eq_u32_e32 vcc, s3, v2
	s_and_b64 s[4:5], s[4:5], vcc
	v_cmp_eq_u32_e32 vcc, s3, v3
	s_and_b64 s[4:5], s[4:5], vcc
	v_cmp_eq_u32_e32 vcc, s3, v4
	s_and_b64 s[4:5], s[4:5], vcc
	v_cmp_eq_u32_e32 vcc, s3, v5
	s_and_b64 s[4:5], s[4:5], vcc
	v_cmp_eq_u32_e32 vcc, s3, v6
	s_and_b64 s[4:5], s[4:5], vcc
	v_cmp_eq_u32_e32 vcc, s3, v7
	s_and_b64 s[4:5], s[4:5], vcc
	v_cmp_eq_u32_e32 vcc, s3, v9
	s_and_b64 s[4:5], s[4:5], vcc
	s_cmp_eq_u64 s[4:5], exec
	s_cselect_b64 s[4:5], -1, 0

; __device__ __forceinline__ int lane_id() { int l; asm volatile("v_mbcnt_lo_u32_b32 %0, -1, 0\n\tv_mbcnt_hi_u32_b32 %0, -1, %0" : "=v"(l)); return l; }
; #define PG8_STAGE(bufoff, gbase, voff) do { _Pragma("unroll") for (int _i = 0; _i < 2; ++_i) \
;         __builtin_amdgcn_global_load_lds((const unsigned*)((const char*)(gbase) + (voff)[_i]), (LAS unsigned*)(lds + (bufoff) + ldsw + _i * 8192), 16, 0, 0); } while (0)
; #define PG8_WAIT_V(n) asm volatile("s_waitcnt vmcnt(" #n ")" ::: "memory")
;     int tid = wave_s * 64 + lane_id(); asm volatile("" : "+v"(tid));
;     const int wid = __builtin_amdgcn_readfirstlane(tid >> 6), lane = tid & 63, wr = wid >> 2, wc = wid & 3, fr = lane & 15, fq = lane >> 4;
;     const int K = g.K, nt = K / BK, lda = g.lda;
;     unsigned voffA[2], voffB[2];
; #pragma unroll
;     for (int i = 0; i < 2; ++i) { int R, C; stage_rc(tid * 16 + i * 8192, R, C); const int Rb = Epi::PERM ? ((R & ~31) + perm32(R & 31)) : R;
;         voffA[i] = (unsigned)(R * lda + C) * 2u; voffB[i] = (unsigned)(Rb * K + C) * 2u; }
;     const size_t kstep = (size_t)(BK * 2);
;     const size_t hstepA = (size_t)HALF * lda * 2, hstepB = (size_t)HALF * K * 2;
;     const size_t tstepA = 2 * hstepA, tstepB = 2 * hstepB;
;     const unsigned ldsw = (unsigned)wid * 1024u;
;     const int aoff = lds_byte(wr * 64 + fr, fq * 8), boff = lds_byte(wc * 32 + fr, fq * 8);
;     ...
;     Unit cur, nxt; int ui = 0;
;     if (!S.next(0, cur)) return;
;     f32x4 acc[2][2][4][2];
; #pragma unroll
;     for (int a = 0; a < 2; ++a)
; #pragma unroll
;         for (int b = 0; b < 2; ++b)
; #pragma unroll
;             for (int m = 0; m < 4; ++m)
; #pragma unroll
;                 for (int n = 0; n < 2; ++n) acc[a][b][m][n] = (f32x4){0.f, 0.f, 0.f, 0.f};
;     bf16x8 At[4][2], B0[2][2], B1[2][2];
;     const char* cA = (const char*)g.A + (size_t)cur.pm * tstepA + (size_t)((cur.pn >> g.ash) * g.amul) * 2; const char* cB = (const char*)g.Bt + (size_t)cur.pn * tstepB;
;     PG8_STAGE(PG8_SB(0, 0), cB, voffB); PG8_STAGE(PG8_SB(0, 1), cB + hstepB, voffB); PG8_STAGE(PG8_SA(0, 0), cA, voffA); PG8_STAGE(PG8_SA(0, 1), cA + hstepA, voffA);
;     if (wr == 1) PG8_BAR;
;     PG8_WAIT_V(2); PG8_BAR;
;     PG8_STAGE(PG8_SB(1, 0), cB + kstep, voffB); PG8_STAGE(PG8_SA(1, 0), cA + kstep, voffA); PG8_STAGE(PG8_SB(1, 1), cB + hstepB + kstep, voffB);
;     PG8_WAIT_V(6); PG8_BAR;
.LBB0_106:
	s_add_u32 s28, s26, 0x12800000
	v_readlane_b32 s10, v254, 57
	s_addc_u32 s29, s27, 0
	s_mul_i32 s8, s10, 0xe000
	v_readlane_b32 s11, v254, 58
	s_waitcnt lgkmcnt(0)
	s_add_u32 s6, s6, s8
	s_addc_u32 s7, s7, 0
	s_lshl_b32 s8, s10, 18
	s_mov_b32 s9, s11
	s_lshl_b64 s[8:9], s[8:9], 2
	s_add_u32 s8, s26, s8
	s_addc_u32 s9, s27, s9
	s_add_u32 s8, s8, 0x36c00000
	v_readlane_b32 s10, v254, 56
	s_addc_u32 s9, s9, 0
	s_lshl_b32 s82, s10, 8
	s_add_u32 s10, s6, 0xa000
	s_addc_u32 s11, s7, 0
	s_add_u32 s12, s6, 0xc000
	s_addc_u32 s13, s7, 0
	s_add_u32 s14, s26, 0x26800000
	s_addc_u32 s15, s27, 0
	s_add_u32 s18, s26, 0x2a800000
	s_addc_u32 s19, s27, 0
	s_add_u32 s20, s6, 0x6000
	s_addc_u32 s21, s7, 0
	s_add_u32 s44, s6, 0x8000
	s_addc_u32 s45, s7, 0
	s_add_u32 s46, s26, 0x1e800000
	s_addc_u32 s47, s27, 0
	s_and_b32 s24, s24, 3
	s_add_i32 m0, s56, 0x18000
	v_lshl_add_u64 v[8:9], v[8:9], 0, s[34:35]
	s_lshl_b32 s36, s23, 13
	s_lshl_b32 s37, s24, 12
	s_waitcnt vmcnt(2)
	s_barrier
	global_load_lds_dwordx4 v[8:9], off
	v_lshl_add_u64 v[6:7], v[6:7], 0, s[34:35]
	s_add_i32 m0, s56, 0x1a000
	s_add_i32 s81, s56, 0x8000
	s_add_i32 s60, s56, 0xa000
	global_load_lds_dwordx4 v[6:7], off
	v_lshl_add_u64 v[2:3], v[2:3], 0, s[34:35]
	s_mov_b32 m0, s81
	s_add_u32 s26, s62, 0x80080
	global_load_lds_dwordx4 v[2:3], off
	v_lshl_add_u64 v[2:3], v[4:5], 0, s[34:35]
	s_mov_b32 m0, s60
	s_addc_u32 s27, s63, 0
	global_load_lds_dwordx4 v[2:3], off
	s_add_i32 m0, s56, 0x1c000
	v_lshl_add_u64 v[2:3], s[26:27], 0, v[150:151]
	global_load_lds_dwordx4 v[2:3], off
	v_lshl_add_u64 v[2:3], s[26:27], 0, v[146:147]
	s_add_i32 m0, s56, 0x1e000
	s_cmpk_lt_u32 s22, 0x100
	global_load_lds_dwordx4 v[2:3], off
	v_bfe_u32 v3, v10, 4, 2
	v_and_b32_e32 v2, 15, v10
	v_lshlrev_b32_e32 v4, 3, v3
	v_lshlrev_b32_e32 v3, 4, v3
	v_lshl_or_b32 v5, v2, 6, v3
	s_cselect_b64 s[48:49], -1, 0
	s_and_b32 s22, s22, 0xffffff00
	v_lshl_or_b32 v3, s24, 6, v3
	v_lshl_or_b32 v172, s23, 6, v2
	v_lshlrev_b32_e32 v6, 2, v2
	v_or3_b32 v177, v3, s22, v2
	v_lshlrev_b32_e32 v2, 15, v14
	v_and_b32_e32 v2, 0xffff0000, v2
	v_lshl_add_u32 v2, v13, 12, v2
	v_and_b32_e32 v3, 1, v14
	v_and_b32_e32 v7, 32, v6
	s_movk_i32 s23, 0x100
	s_add_i32 s22, s22, 0
	v_lshl_or_b32 v2, v3, 6, v2
	v_bitop3_b32 v8, v5, s36, v7 bitop3:0xde
	v_bitop3_b32 v173, v5, s37, v7 bitop3:0xde
	v_cmp_gt_i32_e64 s[36:37], s23, v177
	s_add_i32 s23, s22, 0x22100
	s_add_i32 s22, s22, 0x22300
	v_lshl_add_u32 v154, v15, 1, v2
	v_lshlrev_b32_e32 v2, 15, v0
	v_add_u32_e32 v179, s23, v6
	v_add_u32_e32 v180, s22, v6
	v_and_b32_e32 v2, 0xffff0000, v2
	v_readlane_b32 s22, v254, 7
	s_waitcnt vmcnt(6)
	v_lshl_add_u32 v2, v11, 12, v2
	v_and_b32_e32 v0, 1, v0
	v_readlane_b32 s23, v254, 8
	v_lshl_or_b32 v174, s24, 5, v4
	v_lshl_or_b32 v0, v0, 6, v2
	s_mov_b32 s88, s22
	v_readlane_b32 s22, v254, 3
	v_or_b32_e32 v175, 0xffffec00, v174
	v_or_b32_e32 v176, 0xfffff400, v174
	s_mov_b32 s61, 0
	v_cmp_eq_u32_e64 s[38:39], 0, v177
	v_lshl_add_u32 v178, v177, 2, s0
	v_mov_b32_e32 v155, v1
	v_lshl_add_u32 v156, v12, 1, v0
	v_mov_b32_e32 v157, v1
	v_add_u32_e32 v181, 0, v8
	s_mov_b32 s64, s22
	s_barrier
	v_readlane_b32 s23, v254, 4
	s_mov_b32 s100, 0
	s_branch .LBB0_109
.Lcw_g1_p1:
	s_waitcnt vmcnt(14)
	s_branch .Lcw_g1_c1
.Lcw_g1_p2:
	s_waitcnt vmcnt(20)
	s_mov_b32 s100, 0
	s_branch .Lcw_g1_c2

; #define PG8_BAR __builtin_amdgcn_s_barrier()
;     ...
;         const bool has_next = S.next(ui + 1, nxt);
;         const char* nA = has_next ? (const char*)g.A + (size_t)nxt.pm * tstepA + (size_t)((nxt.pn >> g.ash) * g.amul) * 2 : cA; const char* nB = has_next ? (const char*)g.Bt + (size_t)nxt.pn * tstepB : cB;
;         PG8_KLOOP();
;         if (wr == 0) PG8_BAR;
;         E(acc, cur, wr, wc, fr, fq);
;         if (!has_next) break;
; #pragma unroll
;         for (int a = 0; a < 2; ++a)
; #pragma unroll
;             for (int b = 0; b < 2; ++b)
; #pragma unroll
;                 for (int m = 0; m < 4; ++m)
; #pragma unroll
;                     for (int n = 0; n < 2; ++n) acc[a][b][m][n] = (f32x4){0.f, 0.f, 0.f, 0.f};
;         cur = nxt; cA = nA; cB = nB; ++ui;
;         if (wr == 1) PG8_BAR;
.LBB0_108:
	s_mov_b32 s100, 1
	s_andn2_b64 vcc, exec, s[16:17]
	s_mov_b32 s88, s50
	s_mov_b32 s64, s74
	s_mov_b64 s[62:63], s[90:91]
	s_mov_b64 s[16:17], s[26:27]
	s_cbranch_vccz .LBB0_131

.LBB0_112:
	s_add_u32 s16, vcc_lo, 0xfff80080
	s_addc_u32 s17, vcc_hi, -1
	s_add_i32 s24, 0, 0x10000
	s_cmp_eq_u32 s96, 28
	s_cselect_b32 s23, s65, s17
	s_cselect_b32 s22, s75, s16
	v_add_u32_e32 v0, s24, v173
	s_cselect_b32 s17, s51, s63
	s_cselect_b32 s16, s89, s62
	s_add_i32 s97, 0, 0x14000
	ds_read_b128 v[130:133], v0
	ds_read_b128 v[134:137], v0 offset:1024
	ds_read_b128 v[138:141], v0 offset:2048
	ds_read_b128 v[142:145], v0 offset:3072
	v_add_u32_e32 v0, s97, v173
	s_waitcnt lgkmcnt(0)
	ds_read_b128 v[158:161], v0
	ds_read_b128 v[162:165], v0 offset:1024
	ds_read_b128 v[166:169], v0 offset:2048
	ds_read_b128 v[182:185], v0 offset:3072
	v_lshl_add_u64 v[170:171], vcc, 0, v[154:155]
	s_add_i32 m0, s56, 0xc000
	ds_read_b128 v[186:189], v181
	ds_read_b128 v[190:193], v181 offset:1024
	ds_read_b128 v[194:197], v181 offset:2048
	ds_read_b128 v[198:201], v181 offset:3072
	ds_read_b128 v[202:205], v181 offset:4096
	ds_read_b128 v[206:209], v181 offset:5120
	ds_read_b128 v[210:213], v181 offset:6144
	ds_read_b128 v[214:217], v181 offset:7168
	global_load_lds_dwordx4 v[170:171], off
	v_lshl_add_u64 v[170:171], vcc, 0, v[156:157]
	s_add_i32 m0, s56, 0xe000
	s_nop 0
	global_load_lds_dwordx4 v[170:171], off
	s_cmp_lg_u32 s100, 0
	s_cbranch_scc1 .Lcw_g1_p1
	s_waitcnt vmcnt(8)
.Lcw_g1_c1:
	s_waitcnt lgkmcnt(0)
	s_setprio 1
	s_barrier
	v_mfma_f32_16x16x32_bf16 v[126:129], v[130:133], v[186:189], v[126:129]
	v_mfma_f32_16x16x32_bf16 v[122:125], v[138:141], v[186:189], v[122:125]
	v_mfma_f32_16x16x32_bf16 v[110:113], v[130:133], v[194:197], v[110:113]
	v_mfma_f32_16x16x32_bf16 v[106:109], v[138:141], v[194:197], v[106:109]
	v_mfma_f32_16x16x32_bf16 v[94:97], v[130:133], v[202:205], v[94:97]
	v_mfma_f32_16x16x32_bf16 v[90:93], v[138:141], v[202:205], v[90:93]
	v_mfma_f32_16x16x32_bf16 v[78:81], v[130:133], v[210:213], v[78:81]
	v_mfma_f32_16x16x32_bf16 v[74:77], v[138:141], v[210:213], v[74:77]
	v_mfma_f32_16x16x32_bf16 v[126:129], v[134:137], v[190:193], v[126:129]
	v_mfma_f32_16x16x32_bf16 v[122:125], v[142:145], v[190:193], v[122:125]
	v_mfma_f32_16x16x32_bf16 v[110:113], v[134:137], v[198:201], v[110:113]
	v_mfma_f32_16x16x32_bf16 v[106:109], v[142:145], v[198:201], v[106:109]
	v_mfma_f32_16x16x32_bf16 v[94:97], v[134:137], v[206:209], v[94:97]
	v_mfma_f32_16x16x32_bf16 v[90:93], v[142:145], v[206:209], v[90:93]
	v_mfma_f32_16x16x32_bf16 v[78:81], v[134:137], v[214:217], v[78:81]
	v_mfma_f32_16x16x32_bf16 v[74:77], v[142:145], v[214:217], v[74:77]
	s_setprio 0
	s_setprio 1
	v_mfma_f32_16x16x32_bf16 v[118:121], v[158:161], v[186:189], v[118:121]
	v_mfma_f32_16x16x32_bf16 v[114:117], v[166:169], v[186:189], v[114:117]
	v_mfma_f32_16x16x32_bf16 v[102:105], v[158:161], v[194:197], v[102:105]
	v_mfma_f32_16x16x32_bf16 v[98:101], v[166:169], v[194:197], v[98:101]
	v_mfma_f32_16x16x32_bf16 v[86:89], v[158:161], v[202:205], v[86:89]
	v_mfma_f32_16x16x32_bf16 v[82:85], v[166:169], v[202:205], v[82:85]
	v_mfma_f32_16x16x32_bf16 v[70:73], v[158:161], v[210:213], v[70:73]
	v_mfma_f32_16x16x32_bf16 v[66:69], v[166:169], v[210:213], v[66:69]
	v_mfma_f32_16x16x32_bf16 v[118:121], v[162:165], v[190:193], v[118:121]
	v_mfma_f32_16x16x32_bf16 v[114:117], v[182:185], v[190:193], v[114:117]
	v_mfma_f32_16x16x32_bf16 v[102:105], v[162:165], v[198:201], v[102:105]
	v_mfma_f32_16x16x32_bf16 v[98:101], v[182:185], v[198:201], v[98:101]
	v_mfma_f32_16x16x32_bf16 v[86:89], v[162:165], v[206:209], v[86:89]
	v_mfma_f32_16x16x32_bf16 v[82:85], v[182:185], v[206:209], v[82:85]
	v_mfma_f32_16x16x32_bf16 v[70:73], v[162:165], v[214:217], v[70:73]
	v_mfma_f32_16x16x32_bf16 v[66:69], v[182:185], v[214:217], v[66:69]
	s_barrier
	s_setprio 0
	s_add_i32 s24, s24, s77
	v_lshl_add_u64 v[170:171], s[16:17], 0, v[150:151]
	s_mov_b32 m0, s24
	ds_read_b128 v[186:189], v181 offset:16384
	ds_read_b128 v[190:193], v181 offset:17408
	ds_read_b128 v[194:197], v181 offset:18432
	ds_read_b128 v[198:201], v181 offset:19456
	ds_read_b128 v[202:205], v181 offset:20480
	ds_read_b128 v[206:209], v181 offset:21504
	ds_read_b128 v[210:213], v181 offset:22528
	ds_read_b128 v[214:217], v181 offset:23552
	global_load_lds_dwordx4 v[170:171], off
	s_add_i32 m0, s24, 0x2000
	s_add_u32 s66, s16, 0x80000
	v_lshl_add_u64 v[218:219], s[16:17], 0, v[146:147]
	s_addc_u32 s67, s17, 0
	s_add_i32 s24, s97, s77
	global_load_lds_dwordx4 v[218:219], off
	v_lshl_add_u64 v[220:221], s[66:67], 0, v[150:151]
	s_mov_b32 m0, s24
	v_lshl_add_u64 v[222:223], s[22:23], 0, v[148:149]
	global_load_lds_dwordx4 v[220:221], off
	v_lshl_add_u64 v[220:221], s[66:67], 0, v[146:147]
	s_add_i32 m0, s24, 0x2000
	s_nop 0
	global_load_lds_dwordx4 v[220:221], off
	v_lshl_add_u64 v[220:221], s[22:23], 0, v[152:153]
	s_mov_b32 m0, s56
	s_nop 0
	global_load_lds_dwordx4 v[220:221], off
	s_mov_b32 m0, s57
	s_nop 0
	global_load_lds_dwordx4 v[222:223], off
	s_cmp_lg_u32 s100, 0
	s_cbranch_scc1 .Lcw_g1_p2
	s_waitcnt vmcnt(8)
.Lcw_g1_c2:
	s_waitcnt lgkmcnt(0)
	s_setprio 1
	s_barrier
	v_mfma_f32_16x16x32_bf16 v[62:65], v[130:133], v[186:189], v[62:65]
	v_mfma_f32_16x16x32_bf16 v[58:61], v[138:141], v[186:189], v[58:61]
	v_mfma_f32_16x16x32_bf16 v[46:49], v[130:133], v[194:197], v[46:49]
	v_mfma_f32_16x16x32_bf16 v[42:45], v[138:141], v[194:197], v[42:45]
	v_mfma_f32_16x16x32_bf16 v[30:33], v[130:133], v[202:205], v[30:33]
	v_mfma_f32_16x16x32_bf16 v[26:29], v[138:141], v[202:205], v[26:29]
	v_mfma_f32_16x16x32_bf16 v[14:17], v[130:133], v[210:213], v[14:17]
	v_mfma_f32_16x16x32_bf16 v[10:13], v[138:141], v[210:213], v[10:13]
	v_mfma_f32_16x16x32_bf16 v[62:65], v[134:137], v[190:193], v[62:65]
	v_mfma_f32_16x16x32_bf16 v[58:61], v[142:145], v[190:193], v[58:61]
	v_mfma_f32_16x16x32_bf16 v[46:49], v[134:137], v[198:201], v[46:49]
	v_mfma_f32_16x16x32_bf16 v[42:45], v[142:145], v[198:201], v[42:45]
	v_mfma_f32_16x16x32_bf16 v[30:33], v[134:137], v[206:209], v[30:33]
	v_mfma_f32_16x16x32_bf16 v[26:29], v[142:145], v[206:209], v[26:29]
	v_mfma_f32_16x16x32_bf16 v[14:17], v[134:137], v[214:217], v[14:17]
	v_mfma_f32_16x16x32_bf16 v[10:13], v[142:145], v[214:217], v[10:13]
	s_setprio 0
	s_setprio 1
	v_mfma_f32_16x16x32_bf16 v[54:57], v[158:161], v[186:189], v[54:57]
	v_mfma_f32_16x16x32_bf16 v[50:53], v[166:169], v[186:189], v[50:53]
	v_mfma_f32_16x16x32_bf16 v[38:41], v[158:161], v[194:197], v[38:41]
	v_mfma_f32_16x16x32_bf16 v[34:37], v[166:169], v[194:197], v[34:37]
	v_mfma_f32_16x16x32_bf16 v[22:25], v[158:161], v[202:205], v[22:25]
	v_mfma_f32_16x16x32_bf16 v[18:21], v[166:169], v[202:205], v[18:21]
	v_mfma_f32_16x16x32_bf16 v[6:9], v[158:161], v[210:213], v[6:9]
	v_mfma_f32_16x16x32_bf16 v[2:5], v[166:169], v[210:213], v[2:5]
	v_mfma_f32_16x16x32_bf16 v[54:57], v[162:165], v[190:193], v[54:57]
	v_mfma_f32_16x16x32_bf16 v[50:53], v[182:185], v[190:193], v[50:53]
	v_mfma_f32_16x16x32_bf16 v[38:41], v[162:165], v[198:201], v[38:41]
	v_mfma_f32_16x16x32_bf16 v[34:37], v[182:185], v[198:201], v[34:37]
	v_mfma_f32_16x16x32_bf16 v[22:25], v[162:165], v[206:209], v[22:25]
	v_mfma_f32_16x16x32_bf16 v[18:21], v[182:185], v[206:209], v[18:21]
	v_mfma_f32_16x16x32_bf16 v[6:9], v[162:165], v[214:217], v[6:9]
	v_mfma_f32_16x16x32_bf16 v[2:5], v[182:185], v[214:217], v[2:5]
	s_barrier
	s_setprio 0
	s_add_i32 s24, 0, 0x18000
	v_add_u32_e32 v0, s24, v173
	s_add_i32 s66, 0, 0x1c000
	ds_read_b128 v[130:133], v0
	ds_read_b128 v[134:137], v0 offset:1024
	ds_read_b128 v[138:141], v0 offset:2048
	ds_read_b128 v[142:145], v0 offset:3072
	v_add_u32_e32 v0, s66, v173
	ds_read_b128 v[158:161], v0
	ds_read_b128 v[162:165], v0 offset:1024
	ds_read_b128 v[166:169], v0 offset:2048
	ds_read_b128 v[182:185], v0 offset:3072
	s_add_u32 s22, s22, 0x80000
	s_addc_u32 s23, s23, 0
	s_mov_b32 m0, s42
	v_lshl_add_u64 v[224:225], s[22:23], 0, v[152:153]
	ds_read_b128 v[186:189], v181 offset:32768
	ds_read_b128 v[190:193], v181 offset:33792
	ds_read_b128 v[194:197], v181 offset:34816
	ds_read_b128 v[198:201], v181 offset:35840
	ds_read_b128 v[202:205], v181 offset:36864
	ds_read_b128 v[206:209], v181 offset:37888
	ds_read_b128 v[210:213], v181 offset:38912
	ds_read_b128 v[214:217], v181 offset:39936
	global_load_lds_dwordx4 v[224:225], off
	v_lshl_add_u64 v[224:225], s[22:23], 0, v[148:149]
	s_mov_b32 m0, s43
	s_nop 0
	global_load_lds_dwordx4 v[224:225], off
	s_waitcnt vmcnt(8)
	s_waitcnt lgkmcnt(0)
	s_setprio 1
	s_barrier
	v_mfma_f32_16x16x32_bf16 v[126:129], v[130:133], v[186:189], v[126:129]
	v_mfma_f32_16x16x32_bf16 v[122:125], v[138:141], v[186:189], v[122:125]
	v_mfma_f32_16x16x32_bf16 v[110:113], v[130:133], v[194:197], v[110:113]
	v_mfma_f32_16x16x32_bf16 v[106:109], v[138:141], v[194:197], v[106:109]
	v_mfma_f32_16x16x32_bf16 v[94:97], v[130:133], v[202:205], v[94:97]
	v_mfma_f32_16x16x32_bf16 v[90:93], v[138:141], v[202:205], v[90:93]
	v_mfma_f32_16x16x32_bf16 v[78:81], v[130:133], v[210:213], v[78:81]
	v_mfma_f32_16x16x32_bf16 v[74:77], v[138:141], v[210:213], v[74:77]
	v_mfma_f32_16x16x32_bf16 v[126:129], v[134:137], v[190:193], v[126:129]
	v_mfma_f32_16x16x32_bf16 v[122:125], v[142:145], v[190:193], v[122:125]
	v_mfma_f32_16x16x32_bf16 v[110:113], v[134:137], v[198:201], v[110:113]
	v_mfma_f32_16x16x32_bf16 v[106:109], v[142:145], v[198:201], v[106:109]
	v_mfma_f32_16x16x32_bf16 v[94:97], v[134:137], v[206:209], v[94:97]
	v_mfma_f32_16x16x32_bf16 v[90:93], v[142:145], v[206:209], v[90:93]
	v_mfma_f32_16x16x32_bf16 v[78:81], v[134:137], v[214:217], v[78:81]
	v_mfma_f32_16x16x32_bf16 v[74:77], v[142:145], v[214:217], v[74:77]
	s_setprio 0
	s_setprio 1
	v_mfma_f32_16x16x32_bf16 v[118:121], v[158:161], v[186:189], v[118:121]
	v_mfma_f32_16x16x32_bf16 v[114:117], v[166:169], v[186:189], v[114:117]
	v_mfma_f32_16x16x32_bf16 v[102:105], v[158:161], v[194:197], v[102:105]
	v_mfma_f32_16x16x32_bf16 v[98:101], v[166:169], v[194:197], v[98:101]
	v_mfma_f32_16x16x32_bf16 v[86:89], v[158:161], v[202:205], v[86:89]
	v_mfma_f32_16x16x32_bf16 v[82:85], v[166:169], v[202:205], v[82:85]
	v_mfma_f32_16x16x32_bf16 v[70:73], v[158:161], v[210:213], v[70:73]
	v_mfma_f32_16x16x32_bf16 v[66:69], v[166:169], v[210:213], v[66:69]
	v_mfma_f32_16x16x32_bf16 v[118:121], v[162:165], v[190:193], v[118:121]
	v_mfma_f32_16x16x32_bf16 v[114:117], v[182:185], v[190:193], v[114:117]
	v_mfma_f32_16x16x32_bf16 v[102:105], v[162:165], v[198:201], v[102:105]
	v_mfma_f32_16x16x32_bf16 v[98:101], v[182:185], v[198:201], v[98:101]
	v_mfma_f32_16x16x32_bf16 v[86:89], v[162:165], v[206:209], v[86:89]
	v_mfma_f32_16x16x32_bf16 v[82:85], v[182:185], v[206:209], v[82:85]
	v_mfma_f32_16x16x32_bf16 v[70:73], v[162:165], v[214:217], v[70:73]
	v_mfma_f32_16x16x32_bf16 v[66:69], v[182:185], v[214:217], v[66:69]
	s_barrier
; #define PG8_BAR __builtin_amdgcn_s_barrier()
;     ...
;     for (;;) {
;         if constexpr (NSEG > 1) {
;             const char* nA = (const char*)g.A2 + (size_t)cur.pm * tstepA + (size_t)((cur.pn >> g.ash) * g.amul) * 2; const char* nB = (const char*)g.Bt2 + (size_t)cur.pn * tstepB;
;             PG8_KLOOP();
;             if (wr == 0) PG8_BAR;
;             E.mid(acc, cur, wr, wc, fr, fq);
;             cA = nA; cB = nB;
;             if (wr == 1) PG8_BAR;
;         }
;         const bool has_next = S.next(ui + 1, nxt);
;         const char* nA = has_next ? (const char*)g.A + (size_t)nxt.pm * tstepA + (size_t)((nxt.pn >> g.ash) * g.amul) * 2 : cA; const char* nB = has_next ? (const char*)g.Bt + (size_t)nxt.pn * tstepB : cB;
;         PG8_KLOOP();
;         if (wr == 0) PG8_BAR;
	s_setprio 0
	s_add_i32 s22, s24, s77
	v_lshl_add_u64 v[170:171], v[170:171], 0, s[34:35]
	s_mov_b32 m0, s22
	ds_read_b128 v[186:189], v181 offset:49152
	ds_read_b128 v[190:193], v181 offset:50176
	ds_read_b128 v[194:197], v181 offset:51200
	ds_read_b128 v[198:201], v181 offset:52224
	ds_read_b128 v[202:205], v181 offset:53248
	ds_read_b128 v[206:209], v181 offset:54272
	ds_read_b128 v[210:213], v181 offset:55296
	ds_read_b128 v[214:217], v181 offset:56320
	global_load_lds_dwordx4 v[170:171], off
	s_add_i32 m0, s22, 0x2000
	s_add_u32 s16, s16, 0x80080
	v_lshl_add_u64 v[170:171], v[218:219], 0, s[34:35]
	s_addc_u32 s17, s17, 0
	s_add_i32 s22, s66, s77
	global_load_lds_dwordx4 v[170:171], off
	v_lshl_add_u64 v[170:171], s[16:17], 0, v[150:151]
	s_mov_b32 m0, s22
	s_nop 0
	global_load_lds_dwordx4 v[170:171], off
	v_lshl_add_u64 v[170:171], s[16:17], 0, v[146:147]
	s_add_i32 m0, s22, 0x2000
	s_nop 0
	global_load_lds_dwordx4 v[170:171], off
	v_lshl_add_u64 v[170:171], v[220:221], 0, s[34:35]
	s_mov_b32 m0, s81
	s_nop 0
	global_load_lds_dwordx4 v[170:171], off
	v_lshl_add_u64 v[170:171], v[222:223], 0, s[34:35]
	s_mov_b32 m0, s60
	s_nop 0
	global_load_lds_dwordx4 v[170:171], off
	s_waitcnt vmcnt(8)
	s_waitcnt lgkmcnt(0)
	s_setprio 1
	s_barrier
	v_mfma_f32_16x16x32_bf16 v[62:65], v[130:133], v[186:189], v[62:65]
	v_mfma_f32_16x16x32_bf16 v[58:61], v[138:141], v[186:189], v[58:61]
	v_mfma_f32_16x16x32_bf16 v[46:49], v[130:133], v[194:197], v[46:49]
	v_mfma_f32_16x16x32_bf16 v[42:45], v[138:141], v[194:197], v[42:45]
	v_mfma_f32_16x16x32_bf16 v[30:33], v[130:133], v[202:205], v[30:33]
	v_mfma_f32_16x16x32_bf16 v[26:29], v[138:141], v[202:205], v[26:29]
	v_mfma_f32_16x16x32_bf16 v[14:17], v[130:133], v[210:213], v[14:17]
	v_mfma_f32_16x16x32_bf16 v[10:13], v[138:141], v[210:213], v[10:13]
	v_mfma_f32_16x16x32_bf16 v[62:65], v[134:137], v[190:193], v[62:65]
	v_mfma_f32_16x16x32_bf16 v[58:61], v[142:145], v[190:193], v[58:61]
	v_mfma_f32_16x16x32_bf16 v[46:49], v[134:137], v[198:201], v[46:49]
	v_mfma_f32_16x16x32_bf16 v[42:45], v[142:145], v[198:201], v[42:45]
	v_mfma_f32_16x16x32_bf16 v[30:33], v[134:137], v[206:209], v[30:33]
	v_mfma_f32_16x16x32_bf16 v[26:29], v[142:145], v[206:209], v[26:29]
	v_mfma_f32_16x16x32_bf16 v[14:17], v[134:137], v[214:217], v[14:17]
	v_mfma_f32_16x16x32_bf16 v[10:13], v[142:145], v[214:217], v[10:13]
	s_setprio 0
	s_setprio 1
	v_mfma_f32_16x16x32_bf16 v[54:57], v[158:161], v[186:189], v[54:57]
	v_mfma_f32_16x16x32_bf16 v[50:53], v[166:169], v[186:189], v[50:53]
	v_mfma_f32_16x16x32_bf16 v[38:41], v[158:161], v[194:197], v[38:41]
	v_mfma_f32_16x16x32_bf16 v[34:37], v[166:169], v[194:197], v[34:37]
	v_mfma_f32_16x16x32_bf16 v[22:25], v[158:161], v[202:205], v[22:25]
	v_mfma_f32_16x16x32_bf16 v[18:21], v[166:169], v[202:205], v[18:21]
	v_mfma_f32_16x16x32_bf16 v[6:9], v[158:161], v[210:213], v[6:9]
	v_mfma_f32_16x16x32_bf16 v[2:5], v[166:169], v[210:213], v[2:5]
	v_mfma_f32_16x16x32_bf16 v[54:57], v[162:165], v[190:193], v[54:57]
	v_mfma_f32_16x16x32_bf16 v[50:53], v[182:185], v[190:193], v[50:53]
	v_mfma_f32_16x16x32_bf16 v[38:41], v[162:165], v[198:201], v[38:41]
	v_mfma_f32_16x16x32_bf16 v[34:37], v[182:185], v[198:201], v[34:37]
	v_mfma_f32_16x16x32_bf16 v[22:25], v[162:165], v[206:209], v[22:25]
	v_mfma_f32_16x16x32_bf16 v[18:21], v[182:185], v[206:209], v[18:21]
	v_mfma_f32_16x16x32_bf16 v[6:9], v[162:165], v[214:217], v[6:9]
	v_mfma_f32_16x16x32_bf16 v[2:5], v[182:185], v[214:217], v[2:5]
	s_barrier
	s_setprio 0
	s_add_i32 s96, s96, 2
	s_add_u32 vcc_lo, vcc_lo, 0x100
	s_addc_u32 vcc_hi, vcc_hi, 0
	s_add_u32 s62, s62, 0x100
	s_addc_u32 s63, s63, 0
	s_cmp_gt_u32 s96, 29
	s_cbranch_scc0 .LBB0_112
	s_and_b64 vcc, exec, s[48:49]
	s_cbranch_vccz .LBB0_115
	s_barrier

; __device__ __forceinline__ int lane_id() { int l; asm volatile("v_mbcnt_lo_u32_b32 %0, -1, 0\n\tv_mbcnt_hi_u32_b32 %0, -1, %0" : "=v"(l)); return l; }
; #define PG8_STAGE(bufoff, gbase, voff) do { _Pragma("unroll") for (int _i = 0; _i < 2; ++_i) \
;         __builtin_amdgcn_global_load_lds((const unsigned*)((const char*)(gbase) + (voff)[_i]), (LAS unsigned*)(lds + (bufoff) + ldsw + _i * 8192), 16, 0, 0); } while (0)
; #define PG8_WAIT_V(n) asm volatile("s_waitcnt vmcnt(" #n ")" ::: "memory")
;     int tid = wave_s * 64 + lane_id(); asm volatile("" : "+v"(tid));
;     const int wid = __builtin_amdgcn_readfirstlane(tid >> 6), lane = tid & 63, wr = wid >> 2, wc = wid & 3, fr = lane & 15, fq = lane >> 4;
;     const int K = g.K, nt = K / BK, lda = g.lda;
;     unsigned voffA[2], voffB[2];
; #pragma unroll
;     for (int i = 0; i < 2; ++i) { int R, C; stage_rc(tid * 16 + i * 8192, R, C); const int Rb = Epi::PERM ? ((R & ~31) + perm32(R & 31)) : R;
;         voffA[i] = (unsigned)(R * lda + C) * 2u; voffB[i] = (unsigned)(Rb * K + C) * 2u; }
;     const size_t kstep = (size_t)(BK * 2);
;     const size_t hstepA = (size_t)HALF * lda * 2, hstepB = (size_t)HALF * K * 2;
;     const size_t tstepA = 2 * hstepA, tstepB = 2 * hstepB;
;     const unsigned ldsw = (unsigned)wid * 1024u;
;     const int aoff = lds_byte(wr * 64 + fr, fq * 8), boff = lds_byte(wc * 32 + fr, fq * 8);
;     ...
;     Unit cur, nxt; int ui = 0;
;     if (!S.next(0, cur)) return;
;     f32x4 acc[2][2][4][2];
; #pragma unroll
;     for (int a = 0; a < 2; ++a)
; #pragma unroll
;         for (int b = 0; b < 2; ++b)
; #pragma unroll
;             for (int m = 0; m < 4; ++m)
; #pragma unroll
;                 for (int n = 0; n < 2; ++n) acc[a][b][m][n] = (f32x4){0.f, 0.f, 0.f, 0.f};
;     bf16x8 At[4][2], B0[2][2], B1[2][2];
;     const char* cA = (const char*)g.A + (size_t)cur.pm * tstepA + (size_t)((cur.pn >> g.ash) * g.amul) * 2; const char* cB = (const char*)g.Bt + (size_t)cur.pn * tstepB;
;     PG8_STAGE(PG8_SB(0, 0), cB, voffB); PG8_STAGE(PG8_SB(0, 1), cB + hstepB, voffB); PG8_STAGE(PG8_SA(0, 0), cA, voffA); PG8_STAGE(PG8_SA(0, 1), cA + hstepA, voffA);
;     if (wr == 1) PG8_BAR;
;     PG8_WAIT_V(2); PG8_BAR;
;     PG8_STAGE(PG8_SB(1, 0), cB + kstep, voffB); PG8_STAGE(PG8_SA(1, 0), cA + kstep, voffA); PG8_STAGE(PG8_SB(1, 1), cB + hstepB + kstep, voffB);
;     PG8_WAIT_V(6); PG8_BAR;
.LBB0_276:
	s_add_u32 s6, s14, 0x22800000
	s_addc_u32 s7, s15, 0
	s_add_u32 s8, s14, 0x32800000
	s_addc_u32 s9, s15, 0
	s_lshl_b64 s[20:21], s[40:41], 2
	s_waitcnt lgkmcnt(0)
	s_add_u32 s10, s10, s20
	s_addc_u32 s11, s11, s21
	s_add_u32 s12, s12, s20
	s_addc_u32 s13, s13, s21
	s_add_u32 s14, s14, s20
	s_addc_u32 s15, s15, s21
	s_add_u32 s14, s14, 0x100000
	v_lshrrev_b32_e32 v12, 1, v10
	s_addc_u32 s15, s15, 0
	v_and_b32_e32 v12, 24, v12
	s_lshl_b32 s17, s17, 5
	v_and_b32_e32 v11, 15, v10
	v_lshlrev_b32_e32 v13, 1, v12
	v_lshlrev_b32_e32 v10, 2, v10
	s_and_b32 s20, s17, 0x60
	s_add_i32 m0, s56, 0x18000
	v_lshl_add_u64 v[8:9], v[8:9], 0, s[34:35]
	v_lshl_or_b32 v198, s18, 6, v11
	v_lshl_or_b32 v11, v11, 6, v13
	s_lshl_b32 s18, s18, 13
	v_and_b32_e32 v10, 32, v10
	s_lshl_b32 s17, s20, 7
	s_waitcnt vmcnt(2)
	s_barrier
	global_load_lds_dwordx4 v[8:9], off
	v_lshl_add_u64 v[6:7], v[6:7], 0, s[34:35]
	s_add_i32 m0, s56, 0x1a000
	s_add_i32 s76, s56, 0x8000
	s_add_i32 s77, s56, 0xa000
	v_bitop3_b32 v13, v11, s18, v10 bitop3:0xde
	global_load_lds_dwordx4 v[6:7], off
	v_lshl_add_u64 v[2:3], v[2:3], 0, s[34:35]
	s_mov_b32 m0, s76
	s_add_u32 s18, s48, 0x10080
	global_load_lds_dwordx4 v[2:3], off
	v_lshl_add_u64 v[2:3], v[4:5], 0, s[34:35]
	s_mov_b32 m0, s77
	s_addc_u32 s19, s49, 0
	global_load_lds_dwordx4 v[2:3], off
	s_add_i32 m0, s56, 0x1c000
	v_lshl_add_u64 v[2:3], s[18:19], 0, v[0:1]
	global_load_lds_dwordx4 v[2:3], off
	v_lshl_add_u64 v[2:3], s[18:19], 0, v[182:183]
	s_add_i32 m0, s56, 0x1e000
	v_readlane_b32 s18, v254, 17
	global_load_lds_dwordx4 v[2:3], off
	s_waitcnt vmcnt(6)
	v_readlane_b32 s19, v254, 18
	s_cmpk_lt_u32 s16, 0x100
	s_mov_b32 s37, s18
	v_readlane_b32 s18, v254, 13
	v_bitop3_b32 v199, v11, s17, v10 bitop3:0xde
	s_cselect_b64 s[16:17], -1, 0
	v_or_b32_e32 v200, s20, v12
	s_mov_b32 s81, 0
	v_add_u32_e32 v201, 0, v13
	s_mov_b32 s36, s18
	s_barrier
	v_readlane_b32 s19, v254, 14
	s_mov_b32 s100, 0
	s_branch .LBB0_279
.Lcw_g2_p1:
	s_waitcnt vmcnt(18)
	s_branch .Lcw_g2_c1
.Lcw_g2_p2:
	s_waitcnt vmcnt(24)
	s_mov_b32 s100, 0
	s_branch .Lcw_g2_c2

; #define PG8_BAR __builtin_amdgcn_s_barrier()
;     ...
;         const bool has_next = S.next(ui + 1, nxt);
;         const char* nA = has_next ? (const char*)g.A + (size_t)nxt.pm * tstepA + (size_t)((nxt.pn >> g.ash) * g.amul) * 2 : cA; const char* nB = has_next ? (const char*)g.Bt + (size_t)nxt.pn * tstepB : cB;
;         PG8_KLOOP();
;         if (wr == 0) PG8_BAR;
;         E(acc, cur, wr, wc, fr, fq);
;         if (!has_next) break;
; #pragma unroll
;         for (int a = 0; a < 2; ++a)
; #pragma unroll
;             for (int b = 0; b < 2; ++b)
; #pragma unroll
;                 for (int m = 0; m < 4; ++m)
; #pragma unroll
;                     for (int n = 0; n < 2; ++n) acc[a][b][m][n] = (f32x4){0.f, 0.f, 0.f, 0.f};
;         cur = nxt; cA = nA; cB = nB; ++ui;
;         if (wr == 1) PG8_BAR;
.LBB0_278:
	s_mov_b32 s100, 1
	s_andn2_b64 vcc, exec, s[22:23]
	s_mov_b32 s37, s18
	s_mov_b32 s36, s20
	s_mov_b64 s[48:49], s[44:45]
	s_mov_b64 s[50:51], s[42:43]
	s_cbranch_vccz .LBB0_294

.LBB0_288:
	s_add_u32 s24, s50, s90
	s_addc_u32 s26, s51, s91
	s_add_u32 s27, s24, 0x100
	s_addc_u32 s46, s26, 0
	s_and_b64 s[22:23], s[74:75], exec
	s_cselect_b32 vcc_hi, s43, s46
	s_cselect_b32 vcc_lo, s42, s27
	s_add_u32 s22, s48, s90
	s_addc_u32 s23, s49, s91
	s_add_u32 s27, s22, 0x100
	s_addc_u32 s46, s23, 0
	s_add_i32 s63, 0, 0x10000
	s_and_b64 s[22:23], s[74:75], exec
	s_cselect_b32 s75, s19, s46
	s_cselect_b32 s74, s21, s27
	s_add_i32 s66, 0, 0x14000
	s_add_u32 s22, s24, 0x80080
	s_addc_u32 s23, s26, 0
	s_add_i32 s96, s63, s29
	s_add_i32 m0, s56, 0xc000
	s_add_i32 s67, s56, 0xe000
	s_add_i32 s82, s96, 0x2000
	s_add_u32 s90, s74, 0x10000
	v_add_u32_e32 v82, s63, v199
	v_add_u32_e32 v126, s66, v199
	s_addc_u32 s91, s75, 0
	s_add_i32 s89, s66, s29
	ds_read_b128 v[66:69], v82
	ds_read_b128 v[70:73], v82 offset:1024
	ds_read_b128 v[78:81], v82 offset:2048
	ds_read_b128 v[82:85], v82 offset:3072
	ds_read_b128 v[86:89], v126
	ds_read_b128 v[90:93], v126 offset:1024
	ds_read_b128 v[106:109], v126 offset:2048
	ds_read_b128 v[126:129], v126 offset:3072
	s_add_i32 s88, s89, 0x2000
	s_add_i32 s65, 0, 0x18000
	s_add_i32 s64, 0, 0x1c000
	s_add_u32 s26, vcc_lo, 0x80000
	s_addc_u32 s27, vcc_hi, 0
	s_add_i32 s47, s65, s29
	s_add_i32 s46, s47, 0x2000
	s_add_u32 s62, s74, 0x10080
	s_addc_u32 s63, s75, 0
	s_add_i32 s97, s64, s29
	s_add_i32 s24, s97, 0x2000
	v_lshl_add_u64 v[196:197], s[22:23], 0, v[186:187]
	ds_read_b128 v[146:149], v201
	ds_read_b128 v[162:165], v201 offset:1024
	ds_read_b128 v[170:173], v201 offset:2048
	ds_read_b128 v[174:177], v201 offset:3072
	ds_read_b128 v[178:181], v201 offset:4096
	ds_read_b128 v[188:191], v201 offset:5120
	ds_read_b128 v[192:195], v201 offset:6144
	ds_read_b128 v[202:205], v201 offset:7168
	global_load_lds_dwordx4 v[196:197], off
	v_lshl_add_u64 v[196:197], s[22:23], 0, v[184:185]
	s_mov_b32 m0, s67
	s_nop 0
	global_load_lds_dwordx4 v[196:197], off
	s_cmp_lg_u32 s100, 0
	s_cbranch_scc1 .Lcw_g2_p1
	s_waitcnt vmcnt(8)
.Lcw_g2_c1:
	s_waitcnt lgkmcnt(0)
	s_setprio 1
	s_barrier
	v_mfma_f32_16x16x32_bf16 v[166:169], v[66:69], v[146:149], v[166:169]
	v_mfma_f32_16x16x32_bf16 v[154:157], v[78:81], v[146:149], v[154:157]
	v_mfma_f32_16x16x32_bf16 v[142:145], v[66:69], v[170:173], v[142:145]
	v_mfma_f32_16x16x32_bf16 v[134:137], v[78:81], v[170:173], v[134:137]
	v_mfma_f32_16x16x32_bf16 v[122:125], v[66:69], v[178:181], v[122:125]
	v_mfma_f32_16x16x32_bf16 v[114:117], v[78:81], v[178:181], v[114:117]
	v_mfma_f32_16x16x32_bf16 v[102:105], v[66:69], v[192:195], v[102:105]
	v_mfma_f32_16x16x32_bf16 v[94:97], v[78:81], v[192:195], v[94:97]
	v_mfma_f32_16x16x32_bf16 v[166:169], v[70:73], v[162:165], v[166:169]
	v_mfma_f32_16x16x32_bf16 v[154:157], v[82:85], v[162:165], v[154:157]
	v_mfma_f32_16x16x32_bf16 v[142:145], v[70:73], v[174:177], v[142:145]
	v_mfma_f32_16x16x32_bf16 v[134:137], v[82:85], v[174:177], v[134:137]
	v_mfma_f32_16x16x32_bf16 v[122:125], v[70:73], v[188:191], v[122:125]
	v_mfma_f32_16x16x32_bf16 v[114:117], v[82:85], v[188:191], v[114:117]
	v_mfma_f32_16x16x32_bf16 v[102:105], v[70:73], v[202:205], v[102:105]
	v_mfma_f32_16x16x32_bf16 v[94:97], v[82:85], v[202:205], v[94:97]
	s_setprio 0
	s_setprio 1
	v_mfma_f32_16x16x32_bf16 v[158:161], v[86:89], v[146:149], v[158:161]
	v_mfma_f32_16x16x32_bf16 v[138:141], v[86:89], v[170:173], v[138:141]
	v_mfma_f32_16x16x32_bf16 v[130:133], v[106:109], v[170:173], v[130:133]
	v_mfma_f32_16x16x32_bf16 v[118:121], v[86:89], v[178:181], v[118:121]
	v_mfma_f32_16x16x32_bf16 v[110:113], v[106:109], v[178:181], v[110:113]
	v_mfma_f32_16x16x32_bf16 v[98:101], v[86:89], v[192:195], v[98:101]
	v_mfma_f32_16x16x32_bf16 v[74:77], v[106:109], v[192:195], v[74:77]
	v_mfma_f32_16x16x32_bf16 v[158:161], v[90:93], v[162:165], v[158:161]
	v_mfma_f32_16x16x32_bf16 v[146:149], v[106:109], v[146:149], v[150:153]
	v_mfma_f32_16x16x32_bf16 v[138:141], v[90:93], v[174:177], v[138:141]
	v_mfma_f32_16x16x32_bf16 v[130:133], v[126:129], v[174:177], v[130:133]
	v_mfma_f32_16x16x32_bf16 v[118:121], v[90:93], v[188:191], v[118:121]
	v_mfma_f32_16x16x32_bf16 v[110:113], v[126:129], v[188:191], v[110:113]
	v_mfma_f32_16x16x32_bf16 v[98:101], v[90:93], v[202:205], v[98:101]
	v_mfma_f32_16x16x32_bf16 v[74:77], v[126:129], v[202:205], v[74:77]
	v_mfma_f32_16x16x32_bf16 v[146:149], v[126:129], v[162:165], v[146:149]
	s_barrier
	s_setprio 0
	s_mov_b32 m0, s96
	v_lshl_add_u64 v[196:197], s[74:75], 0, v[0:1]
	ds_read_b128 v[150:153], v201 offset:16384
	ds_read_b128 v[162:165], v201 offset:17408
	ds_read_b128 v[170:173], v201 offset:18432
	ds_read_b128 v[174:177], v201 offset:19456
	ds_read_b128 v[178:181], v201 offset:20480
	ds_read_b128 v[188:191], v201 offset:21504
	ds_read_b128 v[192:195], v201 offset:22528
	ds_read_b128 v[202:205], v201 offset:23552
	global_load_lds_dwordx4 v[196:197], off
	v_lshl_add_u64 v[206:207], s[74:75], 0, v[182:183]
	s_mov_b32 m0, s82
	v_lshl_add_u64 v[208:209], s[90:91], 0, v[0:1]
	global_load_lds_dwordx4 v[206:207], off
	s_mov_b32 m0, s89
	v_lshl_add_u64 v[210:211], vcc, 0, v[184:185]
	global_load_lds_dwordx4 v[208:209], off
	v_lshl_add_u64 v[208:209], s[90:91], 0, v[182:183]
	s_mov_b32 m0, s88
	s_nop 0
	global_load_lds_dwordx4 v[208:209], off
	v_lshl_add_u64 v[208:209], vcc, 0, v[186:187]
	s_mov_b32 m0, s56
	s_nop 0
	global_load_lds_dwordx4 v[208:209], off
	s_mov_b32 m0, s57
	s_nop 0
	global_load_lds_dwordx4 v[210:211], off
	s_cmp_lg_u32 s100, 0
	s_cbranch_scc1 .Lcw_g2_p2
	s_waitcnt vmcnt(8)
.Lcw_g2_c2:
	s_waitcnt lgkmcnt(0)
	s_setprio 1
	s_barrier
	v_mfma_f32_16x16x32_bf16 v[62:65], v[66:69], v[150:153], v[62:65]
	v_mfma_f32_16x16x32_bf16 v[54:57], v[78:81], v[150:153], v[54:57]
	v_mfma_f32_16x16x32_bf16 v[46:49], v[66:69], v[170:173], v[46:49]
	v_mfma_f32_16x16x32_bf16 v[38:41], v[78:81], v[170:173], v[38:41]
	v_mfma_f32_16x16x32_bf16 v[30:33], v[66:69], v[178:181], v[30:33]
	v_mfma_f32_16x16x32_bf16 v[22:25], v[78:81], v[178:181], v[22:25]
	v_mfma_f32_16x16x32_bf16 v[14:17], v[66:69], v[192:195], v[14:17]
	v_mfma_f32_16x16x32_bf16 v[6:9], v[78:81], v[192:195], v[6:9]
	v_mfma_f32_16x16x32_bf16 v[62:65], v[70:73], v[162:165], v[62:65]
	v_mfma_f32_16x16x32_bf16 v[54:57], v[82:85], v[162:165], v[54:57]
	v_mfma_f32_16x16x32_bf16 v[46:49], v[70:73], v[174:177], v[46:49]
	v_mfma_f32_16x16x32_bf16 v[38:41], v[82:85], v[174:177], v[38:41]
	v_mfma_f32_16x16x32_bf16 v[30:33], v[70:73], v[188:191], v[30:33]
	v_mfma_f32_16x16x32_bf16 v[22:25], v[82:85], v[188:191], v[22:25]
	v_mfma_f32_16x16x32_bf16 v[14:17], v[70:73], v[202:205], v[14:17]
	v_mfma_f32_16x16x32_bf16 v[6:9], v[82:85], v[202:205], v[6:9]
	s_setprio 0
	s_setprio 1
	v_mfma_f32_16x16x32_bf16 v[58:61], v[86:89], v[150:153], v[58:61]
	v_mfma_f32_16x16x32_bf16 v[50:53], v[106:109], v[150:153], v[50:53]
	v_mfma_f32_16x16x32_bf16 v[42:45], v[86:89], v[170:173], v[42:45]
	v_mfma_f32_16x16x32_bf16 v[34:37], v[106:109], v[170:173], v[34:37]
	v_mfma_f32_16x16x32_bf16 v[26:29], v[86:89], v[178:181], v[26:29]
	v_mfma_f32_16x16x32_bf16 v[18:21], v[106:109], v[178:181], v[18:21]
	v_mfma_f32_16x16x32_bf16 v[10:13], v[86:89], v[192:195], v[10:13]
	v_mfma_f32_16x16x32_bf16 v[2:5], v[106:109], v[192:195], v[2:5]
	v_mfma_f32_16x16x32_bf16 v[58:61], v[90:93], v[162:165], v[58:61]
	v_mfma_f32_16x16x32_bf16 v[50:53], v[126:129], v[162:165], v[50:53]
	v_mfma_f32_16x16x32_bf16 v[42:45], v[90:93], v[174:177], v[42:45]
	v_mfma_f32_16x16x32_bf16 v[34:37], v[126:129], v[174:177], v[34:37]
	v_mfma_f32_16x16x32_bf16 v[26:29], v[90:93], v[188:191], v[26:29]
	v_mfma_f32_16x16x32_bf16 v[18:21], v[126:129], v[188:191], v[18:21]
	v_mfma_f32_16x16x32_bf16 v[10:13], v[90:93], v[202:205], v[10:13]
	v_mfma_f32_16x16x32_bf16 v[2:5], v[126:129], v[202:205], v[2:5]
	s_barrier
	s_setprio 0
	v_add_u32_e32 v82, s65, v199
	v_add_u32_e32 v126, s64, v199
	ds_read_b128 v[66:69], v82
	ds_read_b128 v[70:73], v82 offset:1024
	ds_read_b128 v[78:81], v82 offset:2048
	ds_read_b128 v[82:85], v82 offset:3072
	ds_read_b128 v[86:89], v126
	ds_read_b128 v[90:93], v126 offset:1024
	ds_read_b128 v[106:109], v126 offset:2048
	ds_read_b128 v[126:129], v126 offset:3072
	s_mov_b32 m0, s60
	v_lshl_add_u64 v[212:213], s[26:27], 0, v[186:187]
	ds_read_b128 v[150:153], v201 offset:32768
	ds_read_b128 v[162:165], v201 offset:33792
	ds_read_b128 v[170:173], v201 offset:34816
	ds_read_b128 v[174:177], v201 offset:35840
	ds_read_b128 v[178:181], v201 offset:36864
	ds_read_b128 v[188:191], v201 offset:37888
	ds_read_b128 v[192:195], v201 offset:38912
	ds_read_b128 v[202:205], v201 offset:39936
	global_load_lds_dwordx4 v[212:213], off
	v_lshl_add_u64 v[212:213], s[26:27], 0, v[184:185]
	s_mov_b32 m0, s61
	s_nop 0
	global_load_lds_dwordx4 v[212:213], off
	s_waitcnt vmcnt(8)
	s_waitcnt lgkmcnt(0)
	s_setprio 1
	s_barrier
	v_mfma_f32_16x16x32_bf16 v[166:169], v[66:69], v[150:153], v[166:169]
	v_mfma_f32_16x16x32_bf16 v[154:157], v[78:81], v[150:153], v[154:157]
	v_mfma_f32_16x16x32_bf16 v[142:145], v[66:69], v[170:173], v[142:145]
	v_mfma_f32_16x16x32_bf16 v[134:137], v[78:81], v[170:173], v[134:137]
	v_mfma_f32_16x16x32_bf16 v[122:125], v[66:69], v[178:181], v[122:125]
	v_mfma_f32_16x16x32_bf16 v[114:117], v[78:81], v[178:181], v[114:117]
	v_mfma_f32_16x16x32_bf16 v[102:105], v[66:69], v[192:195], v[102:105]
	v_mfma_f32_16x16x32_bf16 v[94:97], v[78:81], v[192:195], v[94:97]
	v_mfma_f32_16x16x32_bf16 v[166:169], v[70:73], v[162:165], v[166:169]
	v_mfma_f32_16x16x32_bf16 v[154:157], v[82:85], v[162:165], v[154:157]
	v_mfma_f32_16x16x32_bf16 v[142:145], v[70:73], v[174:177], v[142:145]
	v_mfma_f32_16x16x32_bf16 v[134:137], v[82:85], v[174:177], v[134:137]
	v_mfma_f32_16x16x32_bf16 v[122:125], v[70:73], v[188:191], v[122:125]
	v_mfma_f32_16x16x32_bf16 v[114:117], v[82:85], v[188:191], v[114:117]
	v_mfma_f32_16x16x32_bf16 v[102:105], v[70:73], v[202:205], v[102:105]
	v_mfma_f32_16x16x32_bf16 v[94:97], v[82:85], v[202:205], v[94:97]
	s_setprio 0
	s_setprio 1
	v_mfma_f32_16x16x32_bf16 v[158:161], v[86:89], v[150:153], v[158:161]
	v_mfma_f32_16x16x32_bf16 v[146:149], v[106:109], v[150:153], v[146:149]
	v_mfma_f32_16x16x32_bf16 v[138:141], v[86:89], v[170:173], v[138:141]
	v_mfma_f32_16x16x32_bf16 v[130:133], v[106:109], v[170:173], v[130:133]
	v_mfma_f32_16x16x32_bf16 v[118:121], v[86:89], v[178:181], v[118:121]
	v_mfma_f32_16x16x32_bf16 v[110:113], v[106:109], v[178:181], v[110:113]
	v_mfma_f32_16x16x32_bf16 v[98:101], v[86:89], v[192:195], v[98:101]
	v_mfma_f32_16x16x32_bf16 v[74:77], v[106:109], v[192:195], v[74:77]
	v_mfma_f32_16x16x32_bf16 v[158:161], v[90:93], v[162:165], v[158:161]
	v_mfma_f32_16x16x32_bf16 v[150:153], v[126:129], v[162:165], v[146:149]
	v_mfma_f32_16x16x32_bf16 v[138:141], v[90:93], v[174:177], v[138:141]
	v_mfma_f32_16x16x32_bf16 v[130:133], v[126:129], v[174:177], v[130:133]
	v_mfma_f32_16x16x32_bf16 v[118:121], v[90:93], v[188:191], v[118:121]
	v_mfma_f32_16x16x32_bf16 v[110:113], v[126:129], v[188:191], v[110:113]
	v_mfma_f32_16x16x32_bf16 v[98:101], v[90:93], v[202:205], v[98:101]
	v_mfma_f32_16x16x32_bf16 v[74:77], v[126:129], v[202:205], v[74:77]
	s_barrier
; #define PG8_BAR __builtin_amdgcn_s_barrier()
;     ...
;     for (;;) {
;         if constexpr (NSEG > 1) {
;             const char* nA = (const char*)g.A2 + (size_t)cur.pm * tstepA + (size_t)((cur.pn >> g.ash) * g.amul) * 2; const char* nB = (const char*)g.Bt2 + (size_t)cur.pn * tstepB;
;             PG8_KLOOP();
;             if (wr == 0) PG8_BAR;
;             E.mid(acc, cur, wr, wc, fr, fq);
;             cA = nA; cB = nB;
;             if (wr == 1) PG8_BAR;
;         }
;         const bool has_next = S.next(ui + 1, nxt);
;         const char* nA = has_next ? (const char*)g.A + (size_t)nxt.pm * tstepA + (size_t)((nxt.pn >> g.ash) * g.amul) * 2 : cA; const char* nB = has_next ? (const char*)g.Bt + (size_t)nxt.pn * tstepB : cB;
;         PG8_KLOOP();
;         if (wr == 0) PG8_BAR;
	s_setprio 0
	s_mov_b32 m0, s47
	v_lshl_add_u64 v[196:197], v[196:197], 0, s[34:35]
	ds_read_b128 v[146:149], v201 offset:49152
	ds_read_b128 v[162:165], v201 offset:50176
	ds_read_b128 v[170:173], v201 offset:51200
	ds_read_b128 v[174:177], v201 offset:52224
	ds_read_b128 v[178:181], v201 offset:53248
	ds_read_b128 v[188:191], v201 offset:54272
	ds_read_b128 v[192:195], v201 offset:55296
	ds_read_b128 v[202:205], v201 offset:56320
	global_load_lds_dwordx4 v[196:197], off
	v_lshl_add_u64 v[196:197], v[206:207], 0, s[34:35]
	s_mov_b32 m0, s46
	s_nop 0
	global_load_lds_dwordx4 v[196:197], off
	v_lshl_add_u64 v[196:197], s[62:63], 0, v[0:1]
	s_mov_b32 m0, s97
	s_nop 0
	global_load_lds_dwordx4 v[196:197], off
	v_lshl_add_u64 v[196:197], s[62:63], 0, v[182:183]
	s_mov_b32 m0, s24
	s_nop 0
	global_load_lds_dwordx4 v[196:197], off
	v_lshl_add_u64 v[196:197], v[208:209], 0, s[34:35]
	s_mov_b32 m0, s76
	s_nop 0
	global_load_lds_dwordx4 v[196:197], off
	v_lshl_add_u64 v[196:197], v[210:211], 0, s[34:35]
	s_mov_b32 m0, s77
	s_nop 0
	global_load_lds_dwordx4 v[196:197], off
	s_waitcnt vmcnt(8)
	s_waitcnt lgkmcnt(0)
	s_setprio 1
	s_barrier
	v_mfma_f32_16x16x32_bf16 v[62:65], v[66:69], v[146:149], v[62:65]
	v_mfma_f32_16x16x32_bf16 v[54:57], v[78:81], v[146:149], v[54:57]
	v_mfma_f32_16x16x32_bf16 v[46:49], v[66:69], v[170:173], v[46:49]
	v_mfma_f32_16x16x32_bf16 v[38:41], v[78:81], v[170:173], v[38:41]
	v_mfma_f32_16x16x32_bf16 v[30:33], v[66:69], v[178:181], v[30:33]
	v_mfma_f32_16x16x32_bf16 v[22:25], v[78:81], v[178:181], v[22:25]
	v_mfma_f32_16x16x32_bf16 v[14:17], v[66:69], v[192:195], v[14:17]
	v_mfma_f32_16x16x32_bf16 v[6:9], v[78:81], v[192:195], v[6:9]
	v_mfma_f32_16x16x32_bf16 v[62:65], v[70:73], v[162:165], v[62:65]
	v_mfma_f32_16x16x32_bf16 v[54:57], v[82:85], v[162:165], v[54:57]
	v_mfma_f32_16x16x32_bf16 v[46:49], v[70:73], v[174:177], v[46:49]
	v_mfma_f32_16x16x32_bf16 v[38:41], v[82:85], v[174:177], v[38:41]
	v_mfma_f32_16x16x32_bf16 v[30:33], v[70:73], v[188:191], v[30:33]
	v_mfma_f32_16x16x32_bf16 v[22:25], v[82:85], v[188:191], v[22:25]
	v_mfma_f32_16x16x32_bf16 v[14:17], v[70:73], v[202:205], v[14:17]
	v_mfma_f32_16x16x32_bf16 v[6:9], v[82:85], v[202:205], v[6:9]
	s_setprio 0
	s_setprio 1
	v_mfma_f32_16x16x32_bf16 v[58:61], v[86:89], v[146:149], v[58:61]
	v_mfma_f32_16x16x32_bf16 v[50:53], v[106:109], v[146:149], v[50:53]
	v_mfma_f32_16x16x32_bf16 v[42:45], v[86:89], v[170:173], v[42:45]
	v_mfma_f32_16x16x32_bf16 v[34:37], v[106:109], v[170:173], v[34:37]
	v_mfma_f32_16x16x32_bf16 v[26:29], v[86:89], v[178:181], v[26:29]
	v_mfma_f32_16x16x32_bf16 v[18:21], v[106:109], v[178:181], v[18:21]
	v_mfma_f32_16x16x32_bf16 v[10:13], v[86:89], v[192:195], v[10:13]
	v_mfma_f32_16x16x32_bf16 v[2:5], v[106:109], v[192:195], v[2:5]
	v_mfma_f32_16x16x32_bf16 v[58:61], v[90:93], v[162:165], v[58:61]
	v_mfma_f32_16x16x32_bf16 v[50:53], v[126:129], v[162:165], v[50:53]
	v_mfma_f32_16x16x32_bf16 v[42:45], v[90:93], v[174:177], v[42:45]
	v_mfma_f32_16x16x32_bf16 v[34:37], v[126:129], v[174:177], v[34:37]
	v_mfma_f32_16x16x32_bf16 v[26:29], v[90:93], v[188:191], v[26:29]
	v_mfma_f32_16x16x32_bf16 v[18:21], v[126:129], v[188:191], v[18:21]
	v_mfma_f32_16x16x32_bf16 v[10:13], v[90:93], v[202:205], v[10:13]
	v_mfma_f32_16x16x32_bf16 v[2:5], v[126:129], v[202:205], v[2:5]
	s_barrier
	s_setprio 0
	s_andn2_b64 vcc, exec, s[40:41]
	s_mov_b64 s[74:75], -1
	s_mov_b64 s[40:41], 0
	s_mov_b64 s[90:91], 0x100
	s_cbranch_vccz .LBB0_288
	s_and_b64 vcc, exec, s[16:17]
	s_cbranch_vccz .LBB0_291
	s_barrier

; __device__ __forceinline__ float bf_lo(unsigned w) { return __uint_as_float(w << 16); }
; __device__ __forceinline__ float bf_hi(unsigned w) { return __uint_as_float(w & 0xffff0000u); }
; __global__ void __launch_bounds__(512, 2) fwd_megakernel(Args a_unused) {
;     ...
;             for (int item = gt; item < (M / 64) * (D / 4); item += NGT) {
;                 const int grp = item & 511, chunk = item >> 9, t0 = chunk * 64, c0 = grp * 4;
;                 f32x4 h = {0.f, 0.f, 0.f, 0.f}, P = {0.f, 0.f, 0.f, 0.f};
; #pragma unroll 8
;                 for (int t = 0; t < 64; ++t) {
;                     const size_t off = (size_t)(t0 + t) * D + c0;
;                     const u32x2 lw = *(const u32x2*)(Zxa + off), bw = *(const u32x2*)(Bb + off);
;                     const f32x4 la = {bf_lo(lw.x), bf_hi(lw.x), bf_lo(lw.y), bf_hi(lw.y)}, bv = {bf_lo(bw.x), bf_hi(bw.x), bf_lo(bw.y), bf_hi(bw.y)};
;                     f32x4 av; av.x = __builtin_amdgcn_exp2f(la.x); av.y = __builtin_amdgcn_exp2f(la.y); av.z = __builtin_amdgcn_exp2f(la.z); av.w = __builtin_amdgcn_exp2f(la.w);
;                     h = av * h + bv; P += la;
;                 }
.LBB0_375:
	v_ashrrev_i32_e32 v6, 9, v16
	v_lshlrev_b32_e32 v2, 6, v6
	v_ashrrev_i32_e32 v3, 31, v2
	v_lshlrev_b32_e32 v0, 1, v17
	v_lshlrev_b64 v[2:3], 12, v[2:3]
	s_movk_i32 s12, 0xff8
	v_and_or_b32 v2, v0, s12, v2
	v_lshl_add_u64 v[8:9], s[4:5], 0, v[2:3]
	v_mov_b32_e32 v2, 0
	s_mov_b64 s[12:13], 0
	v_mov_b32_e32 v3, v2
	v_mov_b32_e32 v4, v2
	v_mov_b32_e32 v5, v2
	v_mov_b32_e32 v12, v2
	v_mov_b32_e32 v13, v2
	v_mov_b32_e32 v10, v2
	v_mov_b32_e32 v11, v2
.LBB0_376:
	v_lshl_add_u64 v[14:15], v[8:9], 0, s[12:13]
	v_add_co_u32_e32 v18, vcc, 0x22800000, v14
	s_mov_b32 s14, 0x22802000
	s_nop 0
	v_addc_co_u32_e32 v19, vcc, 0, v15, vcc
	global_load_dwordx2 v[18:19], v[18:19], off
	v_add_co_u32_e32 v20, vcc, 0x32800000, v14
	s_add_u32 s12, s12, 0x8000
	s_nop 0
	v_addc_co_u32_e32 v21, vcc, 0, v15, vcc
	global_load_dwordx2 v[20:21], v[20:21], off
	s_addc_u32 s13, s13, 0
	s_cmp_eq_u32 s12, 0x40000
	s_waitcnt vmcnt(1)
	v_lshlrev_b32_e32 v22, 16, v18
	v_and_b32_e32 v23, 0xffff0000, v18
	v_lshlrev_b32_e32 v18, 16, v19
	v_and_b32_e32 v19, 0xffff0000, v19
	v_exp_f32_e32 v28, v18
	v_exp_f32_e32 v29, v19
	v_pk_add_f32 v[10:11], v[10:11], v[18:19]
	v_add_co_u32_e32 v18, vcc, s14, v14
	s_waitcnt vmcnt(0)
	v_lshlrev_b32_e32 v24, 16, v20
	v_and_b32_e32 v25, 0xffff0000, v20
	v_lshlrev_b32_e32 v20, 16, v21
	v_and_b32_e32 v21, 0xffff0000, v21
	v_addc_co_u32_e32 v19, vcc, 0, v15, vcc
	v_pk_fma_f32 v[4:5], v[4:5], v[28:29], v[20:21]
	global_load_dwordx2 v[20:21], v[18:19], off offset:-4096
	v_exp_f32_e32 v26, v22
	v_exp_f32_e32 v27, v23
	s_mov_b32 s14, 0x32802000
	v_pk_add_f32 v[12:13], v[12:13], v[22:23]
	v_add_co_u32_e32 v22, vcc, s14, v14
	v_pk_fma_f32 v[2:3], v[2:3], v[26:27], v[24:25]
	s_nop 0
	v_addc_co_u32_e32 v23, vcc, 0, v15, vcc
	global_load_dwordx2 v[24:25], v[22:23], off offset:-4096
	s_mov_b32 s14, 0x22804000
	s_waitcnt vmcnt(1)
	v_lshlrev_b32_e32 v26, 16, v20
	v_and_b32_e32 v27, 0xffff0000, v20
	v_lshlrev_b32_e32 v20, 16, v21
	v_and_b32_e32 v21, 0xffff0000, v21
	v_exp_f32_e32 v32, v20
	v_exp_f32_e32 v33, v21
	v_pk_add_f32 v[10:11], v[10:11], v[20:21]
	global_load_dwordx2 v[18:19], v[18:19], off
	s_nop 0
	global_load_dwordx2 v[20:21], v[22:23], off
	v_exp_f32_e32 v30, v26
	v_exp_f32_e32 v31, v27
	s_waitcnt vmcnt(2)
	v_lshlrev_b32_e32 v28, 16, v24
	v_and_b32_e32 v29, 0xffff0000, v24
	v_lshlrev_b32_e32 v24, 16, v25
	v_pk_fma_f32 v[2:3], v[2:3], v[30:31], v[28:29]
	v_and_b32_e32 v25, 0xffff0000, v25
	v_pk_fma_f32 v[4:5], v[4:5], v[32:33], v[24:25]
	v_pk_add_f32 v[12:13], v[12:13], v[26:27]
	s_waitcnt vmcnt(1)
	v_lshlrev_b32_e32 v22, 16, v18
	v_and_b32_e32 v23, 0xffff0000, v18
	v_lshlrev_b32_e32 v18, 16, v19
	v_and_b32_e32 v19, 0xffff0000, v19
	v_exp_f32_e32 v28, v18
	v_exp_f32_e32 v29, v19
	v_pk_add_f32 v[10:11], v[10:11], v[18:19]
	v_add_co_u32_e32 v18, vcc, s14, v14
	s_waitcnt vmcnt(0)
	v_lshlrev_b32_e32 v24, 16, v20
	v_and_b32_e32 v25, 0xffff0000, v20
	v_lshlrev_b32_e32 v20, 16, v21
	v_and_b32_e32 v21, 0xffff0000, v21
	v_addc_co_u32_e32 v19, vcc, 0, v15, vcc
	v_pk_fma_f32 v[4:5], v[4:5], v[28:29], v[20:21]
	global_load_dwordx2 v[20:21], v[18:19], off offset:-4096
	v_exp_f32_e32 v26, v22
	v_exp_f32_e32 v27, v23
	s_mov_b32 s14, 0x32804000
	v_pk_add_f32 v[12:13], v[12:13], v[22:23]
	v_add_co_u32_e32 v22, vcc, s14, v14
	v_pk_fma_f32 v[2:3], v[2:3], v[26:27], v[24:25]
	s_nop 0
	v_addc_co_u32_e32 v23, vcc, 0, v15, vcc
	global_load_dwordx2 v[24:25], v[22:23], off offset:-4096
	s_mov_b32 s14, 0x22806000
	s_waitcnt vmcnt(1)
	v_lshlrev_b32_e32 v26, 16, v20
	v_and_b32_e32 v27, 0xffff0000, v20
	v_lshlrev_b32_e32 v20, 16, v21
	v_and_b32_e32 v21, 0xffff0000, v21
	v_exp_f32_e32 v32, v20
	v_exp_f32_e32 v33, v21
	v_pk_add_f32 v[10:11], v[10:11], v[20:21]
	global_load_dwordx2 v[18:19], v[18:19], off
	s_nop 0
	global_load_dwordx2 v[20:21], v[22:23], off
	v_exp_f32_e32 v30, v26
	v_exp_f32_e32 v31, v27
	s_waitcnt vmcnt(2)
; __device__ __forceinline__ float bf_lo(unsigned w) { return __uint_as_float(w << 16); }
; __device__ __forceinline__ float bf_hi(unsigned w) { return __uint_as_float(w & 0xffff0000u); }
; __global__ void __launch_bounds__(512, 2) fwd_megakernel(Args a_unused) {
;     ...
;                 for (int t = 0; t < 64; ++t) {
;                     const size_t off = (size_t)(t0 + t) * D + c0;
;                     const u32x2 lw = *(const u32x2*)(Zxa + off), bw = *(const u32x2*)(Bb + off);
;                     const f32x4 la = {bf_lo(lw.x), bf_hi(lw.x), bf_lo(lw.y), bf_hi(lw.y)}, bv = {bf_lo(bw.x), bf_hi(bw.x), bf_lo(bw.y), bf_hi(bw.y)};
;                     f32x4 av; av.x = __builtin_amdgcn_exp2f(la.x); av.y = __builtin_amdgcn_exp2f(la.y); av.z = __builtin_amdgcn_exp2f(la.z); av.w = __builtin_amdgcn_exp2f(la.w);
;                     h = av * h + bv; P += la;
;                 }
;                 f32x4 Av; Av.x = __builtin_amdgcn_exp2f(P.x); Av.y = __builtin_amdgcn_exp2f(P.y); Av.z = __builtin_amdgcn_exp2f(P.z); Av.w = __builtin_amdgcn_exp2f(P.w);
;                 *(f32x4*)(AggA + (size_t)chunk * D + c0) = Av; *(f32x4*)(AggB + (size_t)chunk * D + c0) = h;
;             }
	v_lshlrev_b32_e32 v28, 16, v24
	v_and_b32_e32 v29, 0xffff0000, v24
	v_lshlrev_b32_e32 v24, 16, v25
	v_pk_fma_f32 v[2:3], v[2:3], v[30:31], v[28:29]
	v_and_b32_e32 v25, 0xffff0000, v25
	v_pk_fma_f32 v[4:5], v[4:5], v[32:33], v[24:25]
	v_pk_add_f32 v[12:13], v[12:13], v[26:27]
	s_waitcnt vmcnt(1)
	v_lshlrev_b32_e32 v22, 16, v18
	v_and_b32_e32 v23, 0xffff0000, v18
	v_lshlrev_b32_e32 v18, 16, v19
	v_and_b32_e32 v19, 0xffff0000, v19
	v_exp_f32_e32 v28, v18
	v_exp_f32_e32 v29, v19
	v_pk_add_f32 v[10:11], v[10:11], v[18:19]
	v_add_co_u32_e32 v18, vcc, s14, v14
	s_waitcnt vmcnt(0)
	v_lshlrev_b32_e32 v24, 16, v20
	v_and_b32_e32 v25, 0xffff0000, v20
	v_lshlrev_b32_e32 v20, 16, v21
	v_and_b32_e32 v21, 0xffff0000, v21
	v_addc_co_u32_e32 v19, vcc, 0, v15, vcc
	v_pk_fma_f32 v[4:5], v[4:5], v[28:29], v[20:21]
	global_load_dwordx2 v[20:21], v[18:19], off offset:-4096
	v_exp_f32_e32 v26, v22
	v_exp_f32_e32 v27, v23
	s_mov_b32 s14, 0x32806000
	v_pk_add_f32 v[12:13], v[12:13], v[22:23]
	v_add_co_u32_e32 v22, vcc, s14, v14
	v_pk_fma_f32 v[2:3], v[2:3], v[26:27], v[24:25]
	s_nop 0
	v_addc_co_u32_e32 v23, vcc, 0, v15, vcc
	global_load_dwordx2 v[24:25], v[22:23], off offset:-4096
	s_mov_b32 s14, 0x22807000
	s_waitcnt vmcnt(1)
	v_lshlrev_b32_e32 v26, 16, v20
	v_and_b32_e32 v27, 0xffff0000, v20
	v_lshlrev_b32_e32 v20, 16, v21
	v_and_b32_e32 v21, 0xffff0000, v21
	v_exp_f32_e32 v32, v20
	v_exp_f32_e32 v33, v21
	v_pk_add_f32 v[10:11], v[10:11], v[20:21]
	global_load_dwordx2 v[18:19], v[18:19], off
	s_nop 0
	global_load_dwordx2 v[20:21], v[22:23], off
	v_exp_f32_e32 v30, v26
	v_exp_f32_e32 v31, v27
	s_waitcnt vmcnt(2)
	v_lshlrev_b32_e32 v28, 16, v24
	v_and_b32_e32 v29, 0xffff0000, v24
	v_pk_add_f32 v[12:13], v[12:13], v[26:27]
	v_pk_fma_f32 v[2:3], v[2:3], v[30:31], v[28:29]
	v_lshlrev_b32_e32 v24, 16, v25
	v_and_b32_e32 v25, 0xffff0000, v25
	v_pk_fma_f32 v[4:5], v[4:5], v[32:33], v[24:25]
	s_waitcnt vmcnt(1)
	v_lshlrev_b32_e32 v22, 16, v18
	v_and_b32_e32 v23, 0xffff0000, v18
	v_lshlrev_b32_e32 v18, 16, v19
	v_and_b32_e32 v19, 0xffff0000, v19
	v_exp_f32_e32 v28, v18
	v_pk_add_f32 v[10:11], v[10:11], v[18:19]
	v_add_co_u32_e32 v18, vcc, s14, v14
	v_exp_f32_e32 v29, v19
	s_nop 0
	v_addc_co_u32_e32 v19, vcc, 0, v15, vcc
	global_load_dwordx2 v[18:19], v[18:19], off
	s_mov_b32 s14, 0x32807000
	v_add_co_u32_e32 v14, vcc, s14, v14
	v_exp_f32_e32 v26, v22
	s_nop 0
	v_addc_co_u32_e32 v15, vcc, 0, v15, vcc
	global_load_dwordx2 v[14:15], v[14:15], off
	v_exp_f32_e32 v27, v23
	s_waitcnt vmcnt(2)
	v_lshlrev_b32_e32 v24, 16, v20
	v_and_b32_e32 v25, 0xffff0000, v20
	v_lshlrev_b32_e32 v20, 16, v21
	v_and_b32_e32 v21, 0xffff0000, v21
	v_pk_fma_f32 v[4:5], v[4:5], v[28:29], v[20:21]
	v_pk_fma_f32 v[2:3], v[2:3], v[26:27], v[24:25]
	v_pk_add_f32 v[12:13], v[12:13], v[22:23]
	s_waitcnt vmcnt(1)
	v_lshlrev_b32_e32 v20, 16, v18
	v_and_b32_e32 v21, 0xffff0000, v18
	v_lshlrev_b32_e32 v18, 16, v19
	v_and_b32_e32 v19, 0xffff0000, v19
	v_exp_f32_e32 v24, v20
	v_exp_f32_e32 v25, v21
	v_exp_f32_e32 v26, v18
	v_exp_f32_e32 v27, v19
	s_waitcnt vmcnt(0)
	v_lshlrev_b32_e32 v22, 16, v14
	v_and_b32_e32 v23, 0xffff0000, v14
	v_lshlrev_b32_e32 v14, 16, v15
	v_and_b32_e32 v15, 0xffff0000, v15
	v_pk_fma_f32 v[4:5], v[4:5], v[26:27], v[14:15]
	v_pk_fma_f32 v[2:3], v[2:3], v[24:25], v[22:23]
	v_pk_add_f32 v[10:11], v[10:11], v[18:19]
	v_pk_add_f32 v[12:13], v[12:13], v[20:21]
	s_cbranch_scc0 .LBB0_376
	v_exp_f32_e32 v8, v12
	v_exp_f32_e32 v9, v13
	v_exp_f32_e32 v10, v10
	v_exp_f32_e32 v11, v11
	v_ashrrev_i32_e32 v7, 31, v6
	v_lshlrev_b64 v[6:7], 13, v[6:7]
	v_lshlrev_b32_e32 v0, 4, v16
	v_add_u32_e32 v16, s78, v16
	v_lshl_add_u64 v[12:13], s[6:7], 0, v[6:7]
	v_and_b32_e32 v0, 0x1ff0, v0
	v_lshl_add_u64 v[6:7], s[8:9], 0, v[6:7]
	v_cmp_lt_i32_e32 vcc, s25, v16
	v_lshl_add_u64 v[12:13], v[12:13], 0, v[0:1]
	v_lshl_add_u64 v[6:7], v[6:7], 0, v[0:1]
	s_or_b64 s[10:11], vcc, s[10:11]
	v_add_u32_e32 v17, s80, v17
	global_store_dwordx4 v[12:13], v[8:11], off
	global_store_dwordx4 v[6:7], v[2:5], off
	s_andn2_b64 exec, exec, s[10:11]
	s_cbranch_execnz .LBB0_375

.LBB0_526:
	s_add_u32 s22, s13, s20
	s_addc_u32 s23, s15, s21
	s_add_u32 s22, s22, 0x1e800100
	s_addc_u32 s23, s23, 0
	s_add_u32 s24, s40, s20
	s_addc_u32 s26, s41, s21
	s_add_i32 s47, 0, 0x10000
	s_cmpk_eq_i32 s20, 0xf00
	s_cselect_b32 s23, s90, s23
	s_cselect_b32 s22, s89, s22
	s_cselect_b32 s27, s88, s26
	s_cselect_b32 s26, s82, s24
	s_add_i32 s97, 0, 0x14000
	v_add_u32_e32 v233, s47, v230
	v_add_u32_e32 v234, s97, v230
	ds_read_b128 v[134:137], v233
	ds_read_b128 v[138:141], v233 offset:1024
	ds_read_b128 v[142:145], v233 offset:2048
	ds_read_b128 v[146:149], v233 offset:3072
	ds_read_b128 v[150:153], v234
	ds_read_b128 v[154:157], v234 offset:1024
	ds_read_b128 v[158:161], v234 offset:2048
	ds_read_b128 v[162:165], v234 offset:3072
	s_add_i32 s91, s46, 0xc000
	v_lshl_add_u64 v[212:213], v[130:131], 0, s[20:21]
	s_mov_b32 m0, s91
	s_add_i32 s48, s46, 0xe000
	ds_read_b128 v[166:169], v232
	ds_read_b128 v[170:173], v232 offset:1024
	ds_read_b128 v[174:177], v232 offset:2048
	ds_read_b128 v[178:181], v232 offset:3072
	ds_read_b128 v[182:185], v232 offset:4096
	ds_read_b128 v[186:189], v232 offset:5120
	ds_read_b128 v[190:193], v232 offset:6144
	ds_read_b128 v[208:211], v232 offset:7168
	global_load_lds_dwordx4 v[212:213], off
	v_lshl_add_u64 v[212:213], v[132:133], 0, s[20:21]
	s_mov_b32 m0, s48
	s_nop 0
	global_load_lds_dwordx4 v[212:213], off
	s_waitcnt vmcnt(8)
	s_waitcnt lgkmcnt(0)
	s_setprio 1
	s_barrier
	v_mfma_f32_16x16x32_bf16 v[94:97], v[134:137], v[166:169], v[94:97]
	v_mfma_f32_16x16x32_bf16 v[102:105], v[142:145], v[166:169], v[102:105]
	v_mfma_f32_16x16x32_bf16 v[122:125], v[134:137], v[174:177], v[122:125]
	v_mfma_f32_16x16x32_bf16 v[126:129], v[142:145], v[174:177], v[126:129]
	v_mfma_f32_16x16x32_bf16 v[106:109], v[134:137], v[182:185], v[106:109]
	v_mfma_f32_16x16x32_bf16 v[90:93], v[142:145], v[182:185], v[90:93]
	v_mfma_f32_16x16x32_bf16 v[82:85], v[134:137], v[190:193], v[82:85]
	v_mfma_f32_16x16x32_bf16 v[74:77], v[142:145], v[190:193], v[74:77]
	v_mfma_f32_16x16x32_bf16 v[94:97], v[138:141], v[170:173], v[94:97]
	v_mfma_f32_16x16x32_bf16 v[102:105], v[146:149], v[170:173], v[102:105]
	v_mfma_f32_16x16x32_bf16 v[122:125], v[138:141], v[178:181], v[122:125]
	v_mfma_f32_16x16x32_bf16 v[126:129], v[146:149], v[178:181], v[126:129]
	v_mfma_f32_16x16x32_bf16 v[106:109], v[138:141], v[186:189], v[106:109]
	v_mfma_f32_16x16x32_bf16 v[90:93], v[146:149], v[186:189], v[90:93]
	v_mfma_f32_16x16x32_bf16 v[82:85], v[138:141], v[208:211], v[82:85]
	v_mfma_f32_16x16x32_bf16 v[74:77], v[146:149], v[208:211], v[74:77]
	s_setprio 0
	s_setprio 1
	v_mfma_f32_16x16x32_bf16 v[110:113], v[150:153], v[166:169], v[110:113]
	v_mfma_f32_16x16x32_bf16 v[118:121], v[158:161], v[166:169], v[118:121]
	v_mfma_f32_16x16x32_bf16 v[114:117], v[150:153], v[174:177], v[114:117]
	v_mfma_f32_16x16x32_bf16 v[98:101], v[158:161], v[174:177], v[98:101]
	v_mfma_f32_16x16x32_bf16 v[86:89], v[150:153], v[182:185], v[86:89]
	v_mfma_f32_16x16x32_bf16 v[78:81], v[158:161], v[182:185], v[78:81]
	v_mfma_f32_16x16x32_bf16 v[70:73], v[150:153], v[190:193], v[70:73]
	v_mfma_f32_16x16x32_bf16 v[66:69], v[158:161], v[190:193], v[66:69]
	v_mfma_f32_16x16x32_bf16 v[110:113], v[154:157], v[170:173], v[110:113]
	v_mfma_f32_16x16x32_bf16 v[118:121], v[162:165], v[170:173], v[118:121]
	v_mfma_f32_16x16x32_bf16 v[114:117], v[154:157], v[178:181], v[114:117]
	v_mfma_f32_16x16x32_bf16 v[98:101], v[162:165], v[178:181], v[98:101]
	v_mfma_f32_16x16x32_bf16 v[86:89], v[154:157], v[186:189], v[86:89]
	v_mfma_f32_16x16x32_bf16 v[78:81], v[162:165], v[186:189], v[78:81]
	v_mfma_f32_16x16x32_bf16 v[70:73], v[154:157], v[208:211], v[70:73]
	v_mfma_f32_16x16x32_bf16 v[66:69], v[162:165], v[208:211], v[66:69]
	s_barrier
	s_setprio 0
	s_add_i32 s47, s47, s39
	s_add_i32 s96, s47, 0x2000
	v_lshl_add_u64 v[212:213], s[26:27], 0, v[0:1]
	s_mov_b32 m0, s47
	s_add_u32 s36, s26, 0x80000
	ds_read_b128 v[166:169], v232 offset:16384
	ds_read_b128 v[170:173], v232 offset:17408
	ds_read_b128 v[174:177], v232 offset:18432
	ds_read_b128 v[178:181], v232 offset:19456
	ds_read_b128 v[182:185], v232 offset:20480
	ds_read_b128 v[186:189], v232 offset:21504
	ds_read_b128 v[190:193], v232 offset:22528
	ds_read_b128 v[208:211], v232 offset:23552
	global_load_lds_dwordx4 v[212:213], off
	v_lshl_add_u64 v[214:215], s[26:27], 0, v[194:195]
	s_mov_b32 m0, s96
	s_addc_u32 s37, s27, 0
	s_add_i32 s97, s97, s39
	global_load_lds_dwordx4 v[214:215], off
	v_lshl_add_u64 v[216:217], s[36:37], 0, v[0:1]
	s_mov_b32 m0, s97
	v_lshl_add_u64 v[218:219], s[22:23], 0, v[196:197]
	global_load_lds_dwordx4 v[216:217], off
	v_lshl_add_u64 v[216:217], s[36:37], 0, v[194:195]
	s_add_i32 s36, s97, 0x2000
	s_mov_b32 m0, s36
	s_nop 0
	global_load_lds_dwordx4 v[216:217], off
	v_lshl_add_u64 v[216:217], s[22:23], 0, v[198:199]
	s_mov_b32 m0, s46
	s_nop 0
	global_load_lds_dwordx4 v[216:217], off
	s_mov_b32 m0, s49
	s_nop 0
	global_load_lds_dwordx4 v[218:219], off
	s_waitcnt vmcnt(8)
	s_waitcnt lgkmcnt(0)
	s_setprio 1
	s_barrier
	v_mfma_f32_16x16x32_bf16 v[62:65], v[134:137], v[166:169], v[62:65]
	v_mfma_f32_16x16x32_bf16 v[58:61], v[142:145], v[166:169], v[58:61]
	v_mfma_f32_16x16x32_bf16 v[50:53], v[134:137], v[174:177], v[50:53]
	v_mfma_f32_16x16x32_bf16 v[42:45], v[142:145], v[174:177], v[42:45]
	v_mfma_f32_16x16x32_bf16 v[34:37], v[134:137], v[182:185], v[34:37]
	v_mfma_f32_16x16x32_bf16 v[26:29], v[142:145], v[182:185], v[26:29]
	v_mfma_f32_16x16x32_bf16 v[18:21], v[134:137], v[190:193], v[18:21]
	v_mfma_f32_16x16x32_bf16 v[10:13], v[142:145], v[190:193], v[10:13]
	v_mfma_f32_16x16x32_bf16 v[62:65], v[138:141], v[170:173], v[62:65]
	v_mfma_f32_16x16x32_bf16 v[58:61], v[146:149], v[170:173], v[58:61]
	v_mfma_f32_16x16x32_bf16 v[50:53], v[138:141], v[178:181], v[50:53]
	v_mfma_f32_16x16x32_bf16 v[42:45], v[146:149], v[178:181], v[42:45]
	v_mfma_f32_16x16x32_bf16 v[34:37], v[138:141], v[186:189], v[34:37]
	v_mfma_f32_16x16x32_bf16 v[26:29], v[146:149], v[186:189], v[26:29]
	v_mfma_f32_16x16x32_bf16 v[18:21], v[138:141], v[208:211], v[18:21]
	v_mfma_f32_16x16x32_bf16 v[10:13], v[146:149], v[208:211], v[10:13]
	s_setprio 0
	s_setprio 1
	v_mfma_f32_16x16x32_bf16 v[54:57], v[150:153], v[166:169], v[54:57]
	v_mfma_f32_16x16x32_bf16 v[46:49], v[158:161], v[166:169], v[46:49]
	v_mfma_f32_16x16x32_bf16 v[38:41], v[150:153], v[174:177], v[38:41]
	v_mfma_f32_16x16x32_bf16 v[30:33], v[158:161], v[174:177], v[30:33]
	v_mfma_f32_16x16x32_bf16 v[22:25], v[150:153], v[182:185], v[22:25]
	v_mfma_f32_16x16x32_bf16 v[14:17], v[158:161], v[182:185], v[14:17]
	v_mfma_f32_16x16x32_bf16 v[6:9], v[150:153], v[190:193], v[6:9]
	v_mfma_f32_16x16x32_bf16 v[2:5], v[158:161], v[190:193], v[2:5]
	v_mfma_f32_16x16x32_bf16 v[54:57], v[154:157], v[170:173], v[54:57]
	v_mfma_f32_16x16x32_bf16 v[46:49], v[162:165], v[170:173], v[46:49]
	v_mfma_f32_16x16x32_bf16 v[38:41], v[154:157], v[178:181], v[38:41]
	v_mfma_f32_16x16x32_bf16 v[30:33], v[162:165], v[178:181], v[30:33]
	v_mfma_f32_16x16x32_bf16 v[22:25], v[154:157], v[186:189], v[22:25]
	v_mfma_f32_16x16x32_bf16 v[14:17], v[162:165], v[186:189], v[14:17]
	v_mfma_f32_16x16x32_bf16 v[6:9], v[154:157], v[208:211], v[6:9]
	v_mfma_f32_16x16x32_bf16 v[2:5], v[162:165], v[208:211], v[2:5]
	s_barrier
	s_setprio 0
	s_add_i32 s37, 0, 0x18000
	s_add_i32 s24, 0, 0x1c000
	v_add_u32_e32 v235, s37, v230
	v_add_u32_e32 v236, s24, v230
	ds_read_b128 v[134:137], v235
	ds_read_b128 v[138:141], v235 offset:1024
	ds_read_b128 v[142:145], v235 offset:2048
	ds_read_b128 v[146:149], v235 offset:3072
	ds_read_b128 v[150:153], v236
	ds_read_b128 v[154:157], v236 offset:1024
	ds_read_b128 v[158:161], v236 offset:2048
	ds_read_b128 v[162:165], v236 offset:3072
	s_add_u32 s22, s22, 0x80000
	s_addc_u32 s23, s23, 0
	s_mov_b32 m0, s50
	v_lshl_add_u64 v[220:221], s[22:23], 0, v[198:199]
	ds_read_b128 v[166:169], v232 offset:32768
	ds_read_b128 v[170:173], v232 offset:33792
	ds_read_b128 v[174:177], v232 offset:34816
	ds_read_b128 v[178:181], v232 offset:35840
	ds_read_b128 v[182:185], v232 offset:36864
	ds_read_b128 v[186:189], v232 offset:37888
	ds_read_b128 v[190:193], v232 offset:38912
	ds_read_b128 v[208:211], v232 offset:39936
	global_load_lds_dwordx4 v[220:221], off
	v_lshl_add_u64 v[220:221], s[22:23], 0, v[196:197]
	s_mov_b32 m0, s51
	s_nop 0
	global_load_lds_dwordx4 v[220:221], off
	s_waitcnt vmcnt(8)
	s_waitcnt lgkmcnt(0)
	s_setprio 1
	s_barrier
	v_mfma_f32_16x16x32_bf16 v[94:97], v[134:137], v[166:169], v[94:97]
	v_mfma_f32_16x16x32_bf16 v[102:105], v[142:145], v[166:169], v[102:105]
	v_mfma_f32_16x16x32_bf16 v[122:125], v[134:137], v[174:177], v[122:125]
	v_mfma_f32_16x16x32_bf16 v[126:129], v[142:145], v[174:177], v[126:129]
	v_mfma_f32_16x16x32_bf16 v[106:109], v[134:137], v[182:185], v[106:109]
	v_mfma_f32_16x16x32_bf16 v[90:93], v[142:145], v[182:185], v[90:93]
	v_mfma_f32_16x16x32_bf16 v[82:85], v[134:137], v[190:193], v[82:85]
	v_mfma_f32_16x16x32_bf16 v[74:77], v[142:145], v[190:193], v[74:77]
	v_mfma_f32_16x16x32_bf16 v[94:97], v[138:141], v[170:173], v[94:97]
	v_mfma_f32_16x16x32_bf16 v[102:105], v[146:149], v[170:173], v[102:105]
	v_mfma_f32_16x16x32_bf16 v[122:125], v[138:141], v[178:181], v[122:125]
	v_mfma_f32_16x16x32_bf16 v[126:129], v[146:149], v[178:181], v[126:129]
	v_mfma_f32_16x16x32_bf16 v[106:109], v[138:141], v[186:189], v[106:109]
	v_mfma_f32_16x16x32_bf16 v[90:93], v[146:149], v[186:189], v[90:93]
	v_mfma_f32_16x16x32_bf16 v[82:85], v[138:141], v[208:211], v[82:85]
	v_mfma_f32_16x16x32_bf16 v[74:77], v[146:149], v[208:211], v[74:77]
	s_setprio 0
	s_setprio 1
	v_mfma_f32_16x16x32_bf16 v[110:113], v[150:153], v[166:169], v[110:113]
	v_mfma_f32_16x16x32_bf16 v[118:121], v[158:161], v[166:169], v[118:121]
	v_mfma_f32_16x16x32_bf16 v[114:117], v[150:153], v[174:177], v[114:117]
	v_mfma_f32_16x16x32_bf16 v[98:101], v[158:161], v[174:177], v[98:101]
	v_mfma_f32_16x16x32_bf16 v[86:89], v[150:153], v[182:185], v[86:89]
	v_mfma_f32_16x16x32_bf16 v[78:81], v[158:161], v[182:185], v[78:81]
	v_mfma_f32_16x16x32_bf16 v[70:73], v[150:153], v[190:193], v[70:73]
	v_mfma_f32_16x16x32_bf16 v[66:69], v[158:161], v[190:193], v[66:69]
	v_mfma_f32_16x16x32_bf16 v[110:113], v[154:157], v[170:173], v[110:113]
	v_mfma_f32_16x16x32_bf16 v[118:121], v[162:165], v[170:173], v[118:121]
	v_mfma_f32_16x16x32_bf16 v[114:117], v[154:157], v[178:181], v[114:117]
	v_mfma_f32_16x16x32_bf16 v[98:101], v[162:165], v[178:181], v[98:101]
	v_mfma_f32_16x16x32_bf16 v[86:89], v[154:157], v[186:189], v[86:89]
	v_mfma_f32_16x16x32_bf16 v[78:81], v[162:165], v[186:189], v[78:81]
	v_mfma_f32_16x16x32_bf16 v[70:73], v[154:157], v[208:211], v[70:73]
	v_mfma_f32_16x16x32_bf16 v[66:69], v[162:165], v[208:211], v[66:69]
	s_barrier
; #define PG8_BAR __builtin_amdgcn_s_barrier()
;     ...
;     for (;;) {
;         if constexpr (NSEG > 1) {
;             const char* nA = (const char*)g.A2 + (size_t)cur.pm * tstepA + (size_t)((cur.pn >> g.ash) * g.amul) * 2; const char* nB = (const char*)g.Bt2 + (size_t)cur.pn * tstepB;
;             PG8_KLOOP();
;             if (wr == 0) PG8_BAR;
	s_setprio 0
	s_add_i32 s37, s37, s39
	s_add_i32 s64, s37, 0x2000
	v_lshl_add_u64 v[212:213], v[212:213], 0, s[34:35]
	s_mov_b32 m0, s37
	s_add_u32 s22, s26, 0x80080
	ds_read_b128 v[166:169], v232 offset:49152
	ds_read_b128 v[170:173], v232 offset:50176
	ds_read_b128 v[174:177], v232 offset:51200
	ds_read_b128 v[178:181], v232 offset:52224
	ds_read_b128 v[182:185], v232 offset:53248
	ds_read_b128 v[186:189], v232 offset:54272
	ds_read_b128 v[190:193], v232 offset:55296
	ds_read_b128 v[208:211], v232 offset:56320
	global_load_lds_dwordx4 v[212:213], off
	v_lshl_add_u64 v[212:213], v[214:215], 0, s[34:35]
	s_mov_b32 m0, s64
	s_addc_u32 s23, s27, 0
	s_add_i32 s26, s24, s39
	global_load_lds_dwordx4 v[212:213], off
	v_lshl_add_u64 v[212:213], s[22:23], 0, v[0:1]
	s_mov_b32 m0, s26
	s_add_i32 s27, s26, 0x2000
	global_load_lds_dwordx4 v[212:213], off
	v_lshl_add_u64 v[212:213], s[22:23], 0, v[194:195]
	s_mov_b32 m0, s27
	s_nop 0
	global_load_lds_dwordx4 v[212:213], off
	v_lshl_add_u64 v[212:213], v[216:217], 0, s[34:35]
	s_mov_b32 m0, s62
	s_nop 0
	global_load_lds_dwordx4 v[212:213], off
	v_lshl_add_u64 v[212:213], v[218:219], 0, s[34:35]
	s_mov_b32 m0, s63
	s_nop 0
	global_load_lds_dwordx4 v[212:213], off
	s_waitcnt vmcnt(8)
	s_waitcnt lgkmcnt(0)
	s_setprio 1
	s_barrier
	v_mfma_f32_16x16x32_bf16 v[62:65], v[134:137], v[166:169], v[62:65]
	v_mfma_f32_16x16x32_bf16 v[58:61], v[142:145], v[166:169], v[58:61]
	v_mfma_f32_16x16x32_bf16 v[50:53], v[134:137], v[174:177], v[50:53]
	v_mfma_f32_16x16x32_bf16 v[42:45], v[142:145], v[174:177], v[42:45]
	v_mfma_f32_16x16x32_bf16 v[34:37], v[134:137], v[182:185], v[34:37]
	v_mfma_f32_16x16x32_bf16 v[26:29], v[142:145], v[182:185], v[26:29]
	v_mfma_f32_16x16x32_bf16 v[18:21], v[134:137], v[190:193], v[18:21]
	v_mfma_f32_16x16x32_bf16 v[10:13], v[142:145], v[190:193], v[10:13]
	v_mfma_f32_16x16x32_bf16 v[62:65], v[138:141], v[170:173], v[62:65]
	v_mfma_f32_16x16x32_bf16 v[58:61], v[146:149], v[170:173], v[58:61]
	v_mfma_f32_16x16x32_bf16 v[50:53], v[138:141], v[178:181], v[50:53]
	v_mfma_f32_16x16x32_bf16 v[42:45], v[146:149], v[178:181], v[42:45]
	v_mfma_f32_16x16x32_bf16 v[34:37], v[138:141], v[186:189], v[34:37]
	v_mfma_f32_16x16x32_bf16 v[26:29], v[146:149], v[186:189], v[26:29]
	v_mfma_f32_16x16x32_bf16 v[18:21], v[138:141], v[208:211], v[18:21]
	v_mfma_f32_16x16x32_bf16 v[10:13], v[146:149], v[208:211], v[10:13]
	s_setprio 0
	s_setprio 1
	v_mfma_f32_16x16x32_bf16 v[54:57], v[150:153], v[166:169], v[54:57]
	v_mfma_f32_16x16x32_bf16 v[46:49], v[158:161], v[166:169], v[46:49]
	v_mfma_f32_16x16x32_bf16 v[38:41], v[150:153], v[174:177], v[38:41]
	v_mfma_f32_16x16x32_bf16 v[30:33], v[158:161], v[174:177], v[30:33]
	v_mfma_f32_16x16x32_bf16 v[22:25], v[150:153], v[182:185], v[22:25]
	v_mfma_f32_16x16x32_bf16 v[14:17], v[158:161], v[182:185], v[14:17]
	v_mfma_f32_16x16x32_bf16 v[6:9], v[150:153], v[190:193], v[6:9]
	v_mfma_f32_16x16x32_bf16 v[2:5], v[158:161], v[190:193], v[2:5]
	v_mfma_f32_16x16x32_bf16 v[54:57], v[154:157], v[170:173], v[54:57]
	v_mfma_f32_16x16x32_bf16 v[46:49], v[162:165], v[170:173], v[46:49]
	v_mfma_f32_16x16x32_bf16 v[38:41], v[154:157], v[178:181], v[38:41]
	v_mfma_f32_16x16x32_bf16 v[30:33], v[162:165], v[178:181], v[30:33]
	v_mfma_f32_16x16x32_bf16 v[22:25], v[154:157], v[186:189], v[22:25]
	v_mfma_f32_16x16x32_bf16 v[14:17], v[162:165], v[186:189], v[14:17]
	v_mfma_f32_16x16x32_bf16 v[6:9], v[154:157], v[208:211], v[6:9]
	v_mfma_f32_16x16x32_bf16 v[2:5], v[162:165], v[208:211], v[2:5]
	s_barrier
	s_setprio 0
	s_add_i32 s42, s42, 2
	s_add_u32 s20, s20, 0x100
	s_addc_u32 s21, s21, 0
	s_cmp_gt_u32 s42, 29
	s_cbranch_scc0 .LBB0_526
	s_and_b64 vcc, exec, s[10:11]
	s_cbranch_vccz .LBB0_529
	s_barrier

.LBB0_538:
	ds_read_b128 v[134:137], v233
	ds_read_b128 v[138:141], v233 offset:1024
	ds_read_b128 v[142:145], v233 offset:2048
	ds_read_b128 v[146:149], v233 offset:3072
	ds_read_b128 v[150:153], v234
	ds_read_b128 v[154:157], v234 offset:1024
	ds_read_b128 v[158:161], v234 offset:2048
	ds_read_b128 v[162:165], v234 offset:3072
	s_add_u32 s18, s88, s16
	s_addc_u32 s19, s89, s17
	s_add_u32 s18, s18, 0x1a800100
	s_addc_u32 s19, s19, 0
	s_add_u32 s24, s90, s16
	s_addc_u32 s66, vcc_lo, s17
	s_cmpk_eq_i32 s16, 0xf00
	s_cselect_b32 s23, s15, s19
	s_cselect_b32 s22, s65, s18
	s_cselect_b32 s19, s13, s66
	s_cselect_b32 s18, s82, s24
	s_mov_b32 m0, s91
	v_lshl_add_u64 v[242:243], v[18:19], 0, s[16:17]
	ds_read_b128 v[166:169], v232
	ds_read_b128 v[170:173], v232 offset:1024
	ds_read_b128 v[174:177], v232 offset:2048
	ds_read_b128 v[178:181], v232 offset:3072
	ds_read_b128 v[182:185], v232 offset:4096
	ds_read_b128 v[186:189], v232 offset:5120
	ds_read_b128 v[190:193], v232 offset:6144
	ds_read_b128 v[238:241], v232 offset:7168
	global_load_lds_dwordx4 v[242:243], off
	v_lshl_add_u64 v[242:243], v[20:21], 0, s[16:17]
	s_mov_b32 m0, s48
	s_nop 0
	global_load_lds_dwordx4 v[242:243], off
	s_waitcnt vmcnt(8)
	s_waitcnt lgkmcnt(0)
	s_setprio 1
	s_barrier
	v_mfma_f32_16x16x32_bf16 v[94:97], v[134:137], v[166:169], v[94:97]
	v_mfma_f32_16x16x32_bf16 v[102:105], v[142:145], v[166:169], v[102:105]
	v_mfma_f32_16x16x32_bf16 v[122:125], v[134:137], v[174:177], v[122:125]
	v_mfma_f32_16x16x32_bf16 v[126:129], v[142:145], v[174:177], v[126:129]
	v_mfma_f32_16x16x32_bf16 v[98:101], v[134:137], v[182:185], v[98:101]
	v_mfma_f32_16x16x32_bf16 v[106:109], v[142:145], v[182:185], v[106:109]
	v_mfma_f32_16x16x32_bf16 v[78:81], v[134:137], v[190:193], v[78:81]
	v_mfma_f32_16x16x32_bf16 v[82:85], v[142:145], v[190:193], v[82:85]
	v_mfma_f32_16x16x32_bf16 v[94:97], v[138:141], v[170:173], v[94:97]
	v_mfma_f32_16x16x32_bf16 v[102:105], v[146:149], v[170:173], v[102:105]
	v_mfma_f32_16x16x32_bf16 v[122:125], v[138:141], v[178:181], v[122:125]
	v_mfma_f32_16x16x32_bf16 v[126:129], v[146:149], v[178:181], v[126:129]
	v_mfma_f32_16x16x32_bf16 v[98:101], v[138:141], v[186:189], v[98:101]
	v_mfma_f32_16x16x32_bf16 v[106:109], v[146:149], v[186:189], v[106:109]
	v_mfma_f32_16x16x32_bf16 v[78:81], v[138:141], v[238:241], v[78:81]
	v_mfma_f32_16x16x32_bf16 v[82:85], v[146:149], v[238:241], v[82:85]
	s_setprio 0
	s_setprio 1
	v_mfma_f32_16x16x32_bf16 v[110:113], v[150:153], v[166:169], v[110:113]
	v_mfma_f32_16x16x32_bf16 v[118:121], v[158:161], v[166:169], v[118:121]
	v_mfma_f32_16x16x32_bf16 v[114:117], v[150:153], v[174:177], v[114:117]
	v_mfma_f32_16x16x32_bf16 v[130:133], v[158:161], v[174:177], v[130:133]
	v_mfma_f32_16x16x32_bf16 v[86:89], v[150:153], v[182:185], v[86:89]
	v_mfma_f32_16x16x32_bf16 v[90:93], v[158:161], v[182:185], v[90:93]
	v_mfma_f32_16x16x32_bf16 v[70:73], v[150:153], v[190:193], v[70:73]
	v_mfma_f32_16x16x32_bf16 v[74:77], v[158:161], v[190:193], v[74:77]
	v_mfma_f32_16x16x32_bf16 v[110:113], v[154:157], v[170:173], v[110:113]
	v_mfma_f32_16x16x32_bf16 v[118:121], v[162:165], v[170:173], v[118:121]
	v_mfma_f32_16x16x32_bf16 v[114:117], v[154:157], v[178:181], v[114:117]
	v_mfma_f32_16x16x32_bf16 v[130:133], v[162:165], v[178:181], v[130:133]
	v_mfma_f32_16x16x32_bf16 v[86:89], v[154:157], v[186:189], v[86:89]
	v_mfma_f32_16x16x32_bf16 v[90:93], v[162:165], v[186:189], v[90:93]
	v_mfma_f32_16x16x32_bf16 v[70:73], v[154:157], v[238:241], v[70:73]
	v_mfma_f32_16x16x32_bf16 v[74:77], v[162:165], v[238:241], v[74:77]
	s_barrier
	s_setprio 0
	s_mov_b32 m0, s47
	v_lshl_add_u64 v[242:243], s[18:19], 0, v[0:1]
	s_add_u32 s66, s18, 0x80000
	ds_read_b128 v[166:169], v232 offset:16384
	ds_read_b128 v[170:173], v232 offset:17408
	ds_read_b128 v[174:177], v232 offset:18432
	ds_read_b128 v[178:181], v232 offset:19456
	ds_read_b128 v[182:185], v232 offset:20480
	ds_read_b128 v[186:189], v232 offset:21504
	ds_read_b128 v[190:193], v232 offset:22528
	ds_read_b128 v[238:241], v232 offset:23552
	global_load_lds_dwordx4 v[242:243], off
	v_lshl_add_u64 v[244:245], s[18:19], 0, v[194:195]
	s_mov_b32 m0, s96
	s_addc_u32 s67, s19, 0
	global_load_lds_dwordx4 v[244:245], off
	v_lshl_add_u64 v[246:247], s[66:67], 0, v[0:1]
	s_mov_b32 m0, s97
	v_lshl_add_u64 v[248:249], s[22:23], 0, v[196:197]
	global_load_lds_dwordx4 v[246:247], off
	v_lshl_add_u64 v[246:247], s[66:67], 0, v[194:195]
	s_mov_b32 m0, s36
	s_nop 0
	global_load_lds_dwordx4 v[246:247], off
	v_lshl_add_u64 v[246:247], s[22:23], 0, v[198:199]
	s_mov_b32 m0, s46
	s_nop 0
	global_load_lds_dwordx4 v[246:247], off
	s_mov_b32 m0, s49
	s_nop 0
	global_load_lds_dwordx4 v[248:249], off
	s_waitcnt vmcnt(8)
	s_waitcnt lgkmcnt(0)
	s_setprio 1
	s_barrier
	v_mfma_f32_16x16x32_bf16 v[62:65], v[134:137], v[166:169], v[62:65]
	v_mfma_f32_16x16x32_bf16 v[66:69], v[142:145], v[166:169], v[66:69]
	v_mfma_f32_16x16x32_bf16 v[46:49], v[134:137], v[174:177], v[46:49]
	v_mfma_f32_16x16x32_bf16 v[50:53], v[142:145], v[174:177], v[50:53]
	v_mfma_f32_16x16x32_bf16 v[30:33], v[134:137], v[182:185], v[30:33]
	v_mfma_f32_16x16x32_bf16 v[34:37], v[142:145], v[182:185], v[34:37]
	v_mfma_f32_16x16x32_bf16 v[14:17], v[134:137], v[190:193], v[14:17]
	v_mfma_f32_16x16x32_bf16 v[10:13], v[142:145], v[190:193], v[10:13]
	v_mfma_f32_16x16x32_bf16 v[62:65], v[138:141], v[170:173], v[62:65]
	v_mfma_f32_16x16x32_bf16 v[66:69], v[146:149], v[170:173], v[66:69]
	v_mfma_f32_16x16x32_bf16 v[46:49], v[138:141], v[178:181], v[46:49]
	v_mfma_f32_16x16x32_bf16 v[50:53], v[146:149], v[178:181], v[50:53]
	v_mfma_f32_16x16x32_bf16 v[30:33], v[138:141], v[186:189], v[30:33]
	v_mfma_f32_16x16x32_bf16 v[34:37], v[146:149], v[186:189], v[34:37]
	v_mfma_f32_16x16x32_bf16 v[14:17], v[138:141], v[238:241], v[14:17]
	v_mfma_f32_16x16x32_bf16 v[10:13], v[146:149], v[238:241], v[10:13]
	s_setprio 0
	s_setprio 1
	v_mfma_f32_16x16x32_bf16 v[54:57], v[150:153], v[166:169], v[54:57]
	v_mfma_f32_16x16x32_bf16 v[58:61], v[158:161], v[166:169], v[58:61]
	v_mfma_f32_16x16x32_bf16 v[38:41], v[150:153], v[174:177], v[38:41]
	v_mfma_f32_16x16x32_bf16 v[42:45], v[158:161], v[174:177], v[42:45]
	v_mfma_f32_16x16x32_bf16 v[22:25], v[150:153], v[182:185], v[22:25]
	v_mfma_f32_16x16x32_bf16 v[26:29], v[158:161], v[182:185], v[26:29]
	v_mfma_f32_16x16x32_bf16 v[6:9], v[150:153], v[190:193], v[6:9]
	v_mfma_f32_16x16x32_bf16 v[2:5], v[158:161], v[190:193], v[2:5]
	v_mfma_f32_16x16x32_bf16 v[54:57], v[154:157], v[170:173], v[54:57]
	v_mfma_f32_16x16x32_bf16 v[58:61], v[162:165], v[170:173], v[58:61]
	v_mfma_f32_16x16x32_bf16 v[38:41], v[154:157], v[178:181], v[38:41]
	v_mfma_f32_16x16x32_bf16 v[42:45], v[162:165], v[178:181], v[42:45]
	v_mfma_f32_16x16x32_bf16 v[22:25], v[154:157], v[186:189], v[22:25]
	v_mfma_f32_16x16x32_bf16 v[26:29], v[162:165], v[186:189], v[26:29]
	v_mfma_f32_16x16x32_bf16 v[6:9], v[154:157], v[238:241], v[6:9]
	v_mfma_f32_16x16x32_bf16 v[2:5], v[162:165], v[238:241], v[2:5]
	s_barrier
	s_setprio 0
	ds_read_b128 v[134:137], v235
	ds_read_b128 v[138:141], v235 offset:1024
	ds_read_b128 v[142:145], v235 offset:2048
	ds_read_b128 v[146:149], v235 offset:3072
	ds_read_b128 v[150:153], v236
	ds_read_b128 v[154:157], v236 offset:1024
	ds_read_b128 v[158:161], v236 offset:2048
	ds_read_b128 v[162:165], v236 offset:3072
	s_add_u32 s22, s22, 0x80000
	s_addc_u32 s23, s23, 0
	s_mov_b32 m0, s50
	v_lshl_add_u64 v[250:251], s[22:23], 0, v[198:199]
	ds_read_b128 v[166:169], v232 offset:32768
	ds_read_b128 v[170:173], v232 offset:33792
	ds_read_b128 v[174:177], v232 offset:34816
	ds_read_b128 v[178:181], v232 offset:35840
	ds_read_b128 v[182:185], v232 offset:36864
	ds_read_b128 v[186:189], v232 offset:37888
	ds_read_b128 v[190:193], v232 offset:38912
	ds_read_b128 v[238:241], v232 offset:39936
	global_load_lds_dwordx4 v[250:251], off
	v_lshl_add_u64 v[250:251], s[22:23], 0, v[196:197]
	s_mov_b32 m0, s51
	s_nop 0
	global_load_lds_dwordx4 v[250:251], off
	s_waitcnt vmcnt(8)
	s_waitcnt lgkmcnt(0)
	s_setprio 1
	s_barrier
	v_mfma_f32_16x16x32_bf16 v[94:97], v[134:137], v[166:169], v[94:97]
	v_mfma_f32_16x16x32_bf16 v[102:105], v[142:145], v[166:169], v[102:105]
	v_mfma_f32_16x16x32_bf16 v[122:125], v[134:137], v[174:177], v[122:125]
	v_mfma_f32_16x16x32_bf16 v[126:129], v[142:145], v[174:177], v[126:129]
	v_mfma_f32_16x16x32_bf16 v[98:101], v[134:137], v[182:185], v[98:101]
	v_mfma_f32_16x16x32_bf16 v[106:109], v[142:145], v[182:185], v[106:109]
	v_mfma_f32_16x16x32_bf16 v[78:81], v[134:137], v[190:193], v[78:81]
	v_mfma_f32_16x16x32_bf16 v[82:85], v[142:145], v[190:193], v[82:85]
	v_mfma_f32_16x16x32_bf16 v[94:97], v[138:141], v[170:173], v[94:97]
	v_mfma_f32_16x16x32_bf16 v[102:105], v[146:149], v[170:173], v[102:105]
	v_mfma_f32_16x16x32_bf16 v[122:125], v[138:141], v[178:181], v[122:125]
	v_mfma_f32_16x16x32_bf16 v[126:129], v[146:149], v[178:181], v[126:129]
	v_mfma_f32_16x16x32_bf16 v[98:101], v[138:141], v[186:189], v[98:101]
	v_mfma_f32_16x16x32_bf16 v[106:109], v[146:149], v[186:189], v[106:109]
	v_mfma_f32_16x16x32_bf16 v[78:81], v[138:141], v[238:241], v[78:81]
	v_mfma_f32_16x16x32_bf16 v[82:85], v[146:149], v[238:241], v[82:85]
	s_setprio 0
	s_setprio 1
	v_mfma_f32_16x16x32_bf16 v[110:113], v[150:153], v[166:169], v[110:113]
	v_mfma_f32_16x16x32_bf16 v[118:121], v[158:161], v[166:169], v[118:121]
	v_mfma_f32_16x16x32_bf16 v[114:117], v[150:153], v[174:177], v[114:117]
	v_mfma_f32_16x16x32_bf16 v[130:133], v[158:161], v[174:177], v[130:133]
	v_mfma_f32_16x16x32_bf16 v[86:89], v[150:153], v[182:185], v[86:89]
	v_mfma_f32_16x16x32_bf16 v[90:93], v[158:161], v[182:185], v[90:93]
	v_mfma_f32_16x16x32_bf16 v[70:73], v[150:153], v[190:193], v[70:73]
	v_mfma_f32_16x16x32_bf16 v[74:77], v[158:161], v[190:193], v[74:77]
	v_mfma_f32_16x16x32_bf16 v[110:113], v[154:157], v[170:173], v[110:113]
	v_mfma_f32_16x16x32_bf16 v[118:121], v[162:165], v[170:173], v[118:121]
	v_mfma_f32_16x16x32_bf16 v[114:117], v[154:157], v[178:181], v[114:117]
	v_mfma_f32_16x16x32_bf16 v[130:133], v[162:165], v[178:181], v[130:133]
	v_mfma_f32_16x16x32_bf16 v[86:89], v[154:157], v[186:189], v[86:89]
	v_mfma_f32_16x16x32_bf16 v[90:93], v[162:165], v[186:189], v[90:93]
	v_mfma_f32_16x16x32_bf16 v[70:73], v[154:157], v[238:241], v[70:73]
	v_mfma_f32_16x16x32_bf16 v[74:77], v[162:165], v[238:241], v[74:77]
	s_barrier
; #define PG8_BAR __builtin_amdgcn_s_barrier()
;     ...
;         PG8_KLOOP();
;         if (wr == 0) PG8_BAR;
	s_setprio 0
	s_mov_b32 m0, s37
	v_lshl_add_u64 v[242:243], v[242:243], 0, s[34:35]
	s_add_u32 s18, s18, 0x80080
	ds_read_b128 v[166:169], v232 offset:49152
	ds_read_b128 v[170:173], v232 offset:50176
	ds_read_b128 v[174:177], v232 offset:51200
	ds_read_b128 v[178:181], v232 offset:52224
	ds_read_b128 v[182:185], v232 offset:53248
	ds_read_b128 v[186:189], v232 offset:54272
	ds_read_b128 v[190:193], v232 offset:55296
	ds_read_b128 v[238:241], v232 offset:56320
	global_load_lds_dwordx4 v[242:243], off
	v_lshl_add_u64 v[242:243], v[244:245], 0, s[34:35]
	s_mov_b32 m0, s64
	s_addc_u32 s19, s19, 0
	global_load_lds_dwordx4 v[242:243], off
	v_lshl_add_u64 v[242:243], s[18:19], 0, v[0:1]
	s_mov_b32 m0, s26
	s_nop 0
	global_load_lds_dwordx4 v[242:243], off
	v_lshl_add_u64 v[242:243], s[18:19], 0, v[194:195]
	s_mov_b32 m0, s27
	s_nop 0
	global_load_lds_dwordx4 v[242:243], off
	v_lshl_add_u64 v[242:243], v[246:247], 0, s[34:35]
	s_mov_b32 m0, s62
	s_nop 0
	global_load_lds_dwordx4 v[242:243], off
	v_lshl_add_u64 v[242:243], v[248:249], 0, s[34:35]
	s_mov_b32 m0, s63
	s_nop 0
	global_load_lds_dwordx4 v[242:243], off
	s_waitcnt vmcnt(8)
	s_waitcnt lgkmcnt(0)
	s_setprio 1
	s_barrier
	v_mfma_f32_16x16x32_bf16 v[62:65], v[134:137], v[166:169], v[62:65]
	v_mfma_f32_16x16x32_bf16 v[66:69], v[142:145], v[166:169], v[66:69]
	v_mfma_f32_16x16x32_bf16 v[46:49], v[134:137], v[174:177], v[46:49]
	v_mfma_f32_16x16x32_bf16 v[50:53], v[142:145], v[174:177], v[50:53]
	v_mfma_f32_16x16x32_bf16 v[30:33], v[134:137], v[182:185], v[30:33]
	v_mfma_f32_16x16x32_bf16 v[34:37], v[142:145], v[182:185], v[34:37]
	v_mfma_f32_16x16x32_bf16 v[14:17], v[134:137], v[190:193], v[14:17]
	v_mfma_f32_16x16x32_bf16 v[10:13], v[142:145], v[190:193], v[10:13]
	v_mfma_f32_16x16x32_bf16 v[62:65], v[138:141], v[170:173], v[62:65]
	v_mfma_f32_16x16x32_bf16 v[66:69], v[146:149], v[170:173], v[66:69]
	v_mfma_f32_16x16x32_bf16 v[46:49], v[138:141], v[178:181], v[46:49]
	v_mfma_f32_16x16x32_bf16 v[50:53], v[146:149], v[178:181], v[50:53]
	v_mfma_f32_16x16x32_bf16 v[30:33], v[138:141], v[186:189], v[30:33]
	v_mfma_f32_16x16x32_bf16 v[34:37], v[146:149], v[186:189], v[34:37]
	v_mfma_f32_16x16x32_bf16 v[14:17], v[138:141], v[238:241], v[14:17]
	v_mfma_f32_16x16x32_bf16 v[10:13], v[146:149], v[238:241], v[10:13]
	s_setprio 0
	s_setprio 1
	v_mfma_f32_16x16x32_bf16 v[54:57], v[150:153], v[166:169], v[54:57]
	v_mfma_f32_16x16x32_bf16 v[58:61], v[158:161], v[166:169], v[58:61]
	v_mfma_f32_16x16x32_bf16 v[38:41], v[150:153], v[174:177], v[38:41]
	v_mfma_f32_16x16x32_bf16 v[42:45], v[158:161], v[174:177], v[42:45]
	v_mfma_f32_16x16x32_bf16 v[22:25], v[150:153], v[182:185], v[22:25]
	v_mfma_f32_16x16x32_bf16 v[26:29], v[158:161], v[182:185], v[26:29]
	v_mfma_f32_16x16x32_bf16 v[6:9], v[150:153], v[190:193], v[6:9]
	v_mfma_f32_16x16x32_bf16 v[2:5], v[158:161], v[190:193], v[2:5]
	v_mfma_f32_16x16x32_bf16 v[54:57], v[154:157], v[170:173], v[54:57]
	v_mfma_f32_16x16x32_bf16 v[58:61], v[162:165], v[170:173], v[58:61]
	v_mfma_f32_16x16x32_bf16 v[38:41], v[154:157], v[178:181], v[38:41]
	v_mfma_f32_16x16x32_bf16 v[42:45], v[162:165], v[178:181], v[42:45]
	v_mfma_f32_16x16x32_bf16 v[22:25], v[154:157], v[186:189], v[22:25]
	v_mfma_f32_16x16x32_bf16 v[26:29], v[162:165], v[186:189], v[26:29]
	v_mfma_f32_16x16x32_bf16 v[6:9], v[154:157], v[238:241], v[6:9]
	v_mfma_f32_16x16x32_bf16 v[2:5], v[162:165], v[238:241], v[2:5]
	s_barrier
	s_setprio 0
	s_add_i32 vcc_hi, vcc_hi, 2
	s_add_u32 s16, s16, 0x100
	s_addc_u32 s17, s17, 0
	s_cmp_gt_u32 vcc_hi, 29
	s_cbranch_scc0 .LBB0_538
	s_and_b64 vcc, exec, s[10:11]
	s_cbranch_vccz .LBB0_541
	s_barrier

.LBB0_646:
	s_add_u32 s22, s90, 0xfff80080
	s_addc_u32 s23, s91, -1
	s_add_i32 s24, 0, 0x10000
	s_cmp_eq_u32 s47, 28
	s_cselect_b32 s23, s9, s23
	s_cselect_b32 s22, s21, s22
	s_cselect_b32 s27, s19, s46
	s_cselect_b32 s26, s36, s37
	s_add_i32 s64, 0, 0x14000
	v_add_u32_e32 v142, s24, v225
	v_add_u32_e32 v158, s64, v225
	ds_read_b128 v[130:133], v142
	ds_read_b128 v[134:137], v142 offset:1024
	ds_read_b128 v[138:141], v142 offset:2048
	ds_read_b128 v[142:145], v142 offset:3072
	ds_read_b128 v[146:149], v158
	ds_read_b128 v[150:153], v158 offset:1024
	ds_read_b128 v[154:157], v158 offset:2048
	ds_read_b128 v[158:161], v158 offset:3072
	v_lshl_add_u64 v[204:205], s[90:91], 0, v[200:201]
	s_add_i32 m0, s56, 0xc000
	ds_read_b128 v[162:165], v232
	ds_read_b128 v[166:169], v232 offset:1024
	ds_read_b128 v[170:173], v232 offset:2048
	ds_read_b128 v[174:177], v232 offset:3072
	ds_read_b128 v[178:181], v232 offset:4096
	ds_read_b128 v[182:185], v232 offset:5120
	ds_read_b128 v[186:189], v232 offset:6144
	ds_read_b128 v[190:193], v232 offset:7168
	global_load_lds_dwordx4 v[204:205], off
	v_lshl_add_u64 v[204:205], s[90:91], 0, v[202:203]
	s_add_i32 m0, s56, 0xe000
	s_nop 0
	global_load_lds_dwordx4 v[204:205], off
	s_waitcnt vmcnt(8)
	s_waitcnt lgkmcnt(0)
	s_setprio 1
	s_barrier
	v_mfma_f32_16x16x32_bf16 v[126:129], v[130:133], v[162:165], v[126:129]
	v_mfma_f32_16x16x32_bf16 v[122:125], v[138:141], v[162:165], v[122:125]
	v_mfma_f32_16x16x32_bf16 v[110:113], v[130:133], v[170:173], v[110:113]
	v_mfma_f32_16x16x32_bf16 v[106:109], v[138:141], v[170:173], v[106:109]
	v_mfma_f32_16x16x32_bf16 v[94:97], v[130:133], v[178:181], v[94:97]
	v_mfma_f32_16x16x32_bf16 v[90:93], v[138:141], v[178:181], v[90:93]
	v_mfma_f32_16x16x32_bf16 v[78:81], v[130:133], v[186:189], v[78:81]
	v_mfma_f32_16x16x32_bf16 v[74:77], v[138:141], v[186:189], v[74:77]
	v_mfma_f32_16x16x32_bf16 v[126:129], v[134:137], v[166:169], v[126:129]
	v_mfma_f32_16x16x32_bf16 v[122:125], v[142:145], v[166:169], v[122:125]
	v_mfma_f32_16x16x32_bf16 v[110:113], v[134:137], v[174:177], v[110:113]
	v_mfma_f32_16x16x32_bf16 v[106:109], v[142:145], v[174:177], v[106:109]
	v_mfma_f32_16x16x32_bf16 v[94:97], v[134:137], v[182:185], v[94:97]
	v_mfma_f32_16x16x32_bf16 v[90:93], v[142:145], v[182:185], v[90:93]
	v_mfma_f32_16x16x32_bf16 v[78:81], v[134:137], v[190:193], v[78:81]
	v_mfma_f32_16x16x32_bf16 v[74:77], v[142:145], v[190:193], v[74:77]
	s_setprio 0
	s_setprio 1
	v_mfma_f32_16x16x32_bf16 v[118:121], v[146:149], v[162:165], v[118:121]
	v_mfma_f32_16x16x32_bf16 v[114:117], v[154:157], v[162:165], v[114:117]
	v_mfma_f32_16x16x32_bf16 v[102:105], v[146:149], v[170:173], v[102:105]
	v_mfma_f32_16x16x32_bf16 v[98:101], v[154:157], v[170:173], v[98:101]
	v_mfma_f32_16x16x32_bf16 v[86:89], v[146:149], v[178:181], v[86:89]
	v_mfma_f32_16x16x32_bf16 v[82:85], v[154:157], v[178:181], v[82:85]
	v_mfma_f32_16x16x32_bf16 v[70:73], v[146:149], v[186:189], v[70:73]
	v_mfma_f32_16x16x32_bf16 v[66:69], v[154:157], v[186:189], v[66:69]
	v_mfma_f32_16x16x32_bf16 v[118:121], v[150:153], v[166:169], v[118:121]
	v_mfma_f32_16x16x32_bf16 v[114:117], v[158:161], v[166:169], v[114:117]
	v_mfma_f32_16x16x32_bf16 v[102:105], v[150:153], v[174:177], v[102:105]
	v_mfma_f32_16x16x32_bf16 v[98:101], v[158:161], v[174:177], v[98:101]
	v_mfma_f32_16x16x32_bf16 v[86:89], v[150:153], v[182:185], v[86:89]
	v_mfma_f32_16x16x32_bf16 v[82:85], v[158:161], v[182:185], v[82:85]
	v_mfma_f32_16x16x32_bf16 v[70:73], v[150:153], v[190:193], v[70:73]
	v_mfma_f32_16x16x32_bf16 v[66:69], v[158:161], v[190:193], v[66:69]
	s_barrier
	s_setprio 0
	s_add_i32 s24, s24, s25
	v_lshl_add_u64 v[204:205], s[26:27], 0, v[0:1]
	s_mov_b32 m0, s24
	ds_read_b128 v[162:165], v232 offset:16384
	ds_read_b128 v[166:169], v232 offset:17408
	ds_read_b128 v[170:173], v232 offset:18432
	ds_read_b128 v[174:177], v232 offset:19456
	ds_read_b128 v[178:181], v232 offset:20480
	ds_read_b128 v[182:185], v232 offset:21504
	ds_read_b128 v[186:189], v232 offset:22528
	ds_read_b128 v[190:193], v232 offset:23552
	global_load_lds_dwordx4 v[204:205], off
	s_add_i32 m0, s24, 0x2000
	s_add_u32 s50, s26, 0x80000
	v_lshl_add_u64 v[206:207], s[26:27], 0, v[198:199]
	s_addc_u32 s51, s27, 0
	s_add_i32 s24, s64, s25
	global_load_lds_dwordx4 v[206:207], off
	v_lshl_add_u64 v[208:209], s[50:51], 0, v[0:1]
	s_mov_b32 m0, s24
	v_lshl_add_u64 v[210:211], s[22:23], 0, v[196:197]
	global_load_lds_dwordx4 v[208:209], off
	v_lshl_add_u64 v[208:209], s[50:51], 0, v[198:199]
	s_add_i32 m0, s24, 0x2000
	s_nop 0
	global_load_lds_dwordx4 v[208:209], off
	v_lshl_add_u64 v[208:209], s[22:23], 0, v[194:195]
	s_mov_b32 m0, s56
	s_nop 0
	global_load_lds_dwordx4 v[208:209], off
	s_mov_b32 m0, s57
	s_nop 0
	global_load_lds_dwordx4 v[210:211], off
	s_waitcnt vmcnt(8)
	s_waitcnt lgkmcnt(0)
	s_setprio 1
	s_barrier
	v_mfma_f32_16x16x32_bf16 v[62:65], v[130:133], v[162:165], v[62:65]
	v_mfma_f32_16x16x32_bf16 v[58:61], v[138:141], v[162:165], v[58:61]
	v_mfma_f32_16x16x32_bf16 v[46:49], v[130:133], v[170:173], v[46:49]
	v_mfma_f32_16x16x32_bf16 v[42:45], v[138:141], v[170:173], v[42:45]
	v_mfma_f32_16x16x32_bf16 v[30:33], v[130:133], v[178:181], v[30:33]
	v_mfma_f32_16x16x32_bf16 v[26:29], v[138:141], v[178:181], v[26:29]
	v_mfma_f32_16x16x32_bf16 v[14:17], v[130:133], v[186:189], v[14:17]
	v_mfma_f32_16x16x32_bf16 v[10:13], v[138:141], v[186:189], v[10:13]
	v_mfma_f32_16x16x32_bf16 v[62:65], v[134:137], v[166:169], v[62:65]
	v_mfma_f32_16x16x32_bf16 v[58:61], v[142:145], v[166:169], v[58:61]
	v_mfma_f32_16x16x32_bf16 v[46:49], v[134:137], v[174:177], v[46:49]
	v_mfma_f32_16x16x32_bf16 v[42:45], v[142:145], v[174:177], v[42:45]
	v_mfma_f32_16x16x32_bf16 v[30:33], v[134:137], v[182:185], v[30:33]
	v_mfma_f32_16x16x32_bf16 v[26:29], v[142:145], v[182:185], v[26:29]
	v_mfma_f32_16x16x32_bf16 v[14:17], v[134:137], v[190:193], v[14:17]
	v_mfma_f32_16x16x32_bf16 v[10:13], v[142:145], v[190:193], v[10:13]
	s_setprio 0
	s_setprio 1
	v_mfma_f32_16x16x32_bf16 v[54:57], v[146:149], v[162:165], v[54:57]
	v_mfma_f32_16x16x32_bf16 v[50:53], v[154:157], v[162:165], v[50:53]
	v_mfma_f32_16x16x32_bf16 v[38:41], v[146:149], v[170:173], v[38:41]
	v_mfma_f32_16x16x32_bf16 v[34:37], v[154:157], v[170:173], v[34:37]
	v_mfma_f32_16x16x32_bf16 v[22:25], v[146:149], v[178:181], v[22:25]
	v_mfma_f32_16x16x32_bf16 v[18:21], v[154:157], v[178:181], v[18:21]
	v_mfma_f32_16x16x32_bf16 v[6:9], v[146:149], v[186:189], v[6:9]
	v_mfma_f32_16x16x32_bf16 v[2:5], v[154:157], v[186:189], v[2:5]
	v_mfma_f32_16x16x32_bf16 v[54:57], v[150:153], v[166:169], v[54:57]
	v_mfma_f32_16x16x32_bf16 v[50:53], v[158:161], v[166:169], v[50:53]
	v_mfma_f32_16x16x32_bf16 v[38:41], v[150:153], v[174:177], v[38:41]
	v_mfma_f32_16x16x32_bf16 v[34:37], v[158:161], v[174:177], v[34:37]
	v_mfma_f32_16x16x32_bf16 v[22:25], v[150:153], v[182:185], v[22:25]
	v_mfma_f32_16x16x32_bf16 v[18:21], v[158:161], v[182:185], v[18:21]
	v_mfma_f32_16x16x32_bf16 v[6:9], v[150:153], v[190:193], v[6:9]
	v_mfma_f32_16x16x32_bf16 v[2:5], v[158:161], v[190:193], v[2:5]
	s_barrier
	s_setprio 0
	s_add_i32 s24, 0, 0x18000
	s_add_i32 s50, 0, 0x1c000
	v_add_u32_e32 v142, s24, v225
	v_add_u32_e32 v158, s50, v225
	ds_read_b128 v[130:133], v142
	ds_read_b128 v[134:137], v142 offset:1024
	ds_read_b128 v[138:141], v142 offset:2048
	ds_read_b128 v[142:145], v142 offset:3072
	ds_read_b128 v[146:149], v158
	ds_read_b128 v[150:153], v158 offset:1024
	ds_read_b128 v[154:157], v158 offset:2048
	ds_read_b128 v[158:161], v158 offset:3072
	s_add_u32 s22, s22, 0x80000
	s_addc_u32 s23, s23, 0
	s_mov_b32 m0, s60
	v_lshl_add_u64 v[212:213], s[22:23], 0, v[194:195]
	ds_read_b128 v[162:165], v232 offset:32768
	ds_read_b128 v[166:169], v232 offset:33792
	ds_read_b128 v[170:173], v232 offset:34816
	ds_read_b128 v[174:177], v232 offset:35840
	ds_read_b128 v[178:181], v232 offset:36864
	ds_read_b128 v[182:185], v232 offset:37888
	ds_read_b128 v[186:189], v232 offset:38912
	ds_read_b128 v[190:193], v232 offset:39936
	global_load_lds_dwordx4 v[212:213], off
	v_lshl_add_u64 v[212:213], s[22:23], 0, v[196:197]
	s_mov_b32 m0, s61
	s_nop 0
	global_load_lds_dwordx4 v[212:213], off
	s_waitcnt vmcnt(8)
	s_waitcnt lgkmcnt(0)
	s_setprio 1
	s_barrier
	v_mfma_f32_16x16x32_bf16 v[126:129], v[130:133], v[162:165], v[126:129]
	v_mfma_f32_16x16x32_bf16 v[122:125], v[138:141], v[162:165], v[122:125]
	v_mfma_f32_16x16x32_bf16 v[110:113], v[130:133], v[170:173], v[110:113]
	v_mfma_f32_16x16x32_bf16 v[106:109], v[138:141], v[170:173], v[106:109]
	v_mfma_f32_16x16x32_bf16 v[94:97], v[130:133], v[178:181], v[94:97]
	v_mfma_f32_16x16x32_bf16 v[90:93], v[138:141], v[178:181], v[90:93]
	v_mfma_f32_16x16x32_bf16 v[78:81], v[130:133], v[186:189], v[78:81]
	v_mfma_f32_16x16x32_bf16 v[74:77], v[138:141], v[186:189], v[74:77]
	v_mfma_f32_16x16x32_bf16 v[126:129], v[134:137], v[166:169], v[126:129]
	v_mfma_f32_16x16x32_bf16 v[122:125], v[142:145], v[166:169], v[122:125]
	v_mfma_f32_16x16x32_bf16 v[110:113], v[134:137], v[174:177], v[110:113]
	v_mfma_f32_16x16x32_bf16 v[106:109], v[142:145], v[174:177], v[106:109]
	v_mfma_f32_16x16x32_bf16 v[94:97], v[134:137], v[182:185], v[94:97]
	v_mfma_f32_16x16x32_bf16 v[90:93], v[142:145], v[182:185], v[90:93]
	v_mfma_f32_16x16x32_bf16 v[78:81], v[134:137], v[190:193], v[78:81]
	v_mfma_f32_16x16x32_bf16 v[74:77], v[142:145], v[190:193], v[74:77]
	s_setprio 0
	s_setprio 1
	v_mfma_f32_16x16x32_bf16 v[118:121], v[146:149], v[162:165], v[118:121]
	v_mfma_f32_16x16x32_bf16 v[114:117], v[154:157], v[162:165], v[114:117]
	v_mfma_f32_16x16x32_bf16 v[102:105], v[146:149], v[170:173], v[102:105]
	v_mfma_f32_16x16x32_bf16 v[98:101], v[154:157], v[170:173], v[98:101]
	v_mfma_f32_16x16x32_bf16 v[86:89], v[146:149], v[178:181], v[86:89]
	v_mfma_f32_16x16x32_bf16 v[82:85], v[154:157], v[178:181], v[82:85]
	v_mfma_f32_16x16x32_bf16 v[70:73], v[146:149], v[186:189], v[70:73]
	v_mfma_f32_16x16x32_bf16 v[66:69], v[154:157], v[186:189], v[66:69]
	v_mfma_f32_16x16x32_bf16 v[118:121], v[150:153], v[166:169], v[118:121]
	v_mfma_f32_16x16x32_bf16 v[114:117], v[158:161], v[166:169], v[114:117]
	v_mfma_f32_16x16x32_bf16 v[102:105], v[150:153], v[174:177], v[102:105]
	v_mfma_f32_16x16x32_bf16 v[98:101], v[158:161], v[174:177], v[98:101]
	v_mfma_f32_16x16x32_bf16 v[86:89], v[150:153], v[182:185], v[86:89]
	v_mfma_f32_16x16x32_bf16 v[82:85], v[158:161], v[182:185], v[82:85]
	v_mfma_f32_16x16x32_bf16 v[70:73], v[150:153], v[190:193], v[70:73]
	v_mfma_f32_16x16x32_bf16 v[66:69], v[158:161], v[190:193], v[66:69]
	s_barrier
; #define PG8_BAR __builtin_amdgcn_s_barrier()
;     ...
;     for (;;) {
;         if constexpr (NSEG > 1) {
;             const char* nA = (const char*)g.A2 + (size_t)cur.pm * tstepA + (size_t)((cur.pn >> g.ash) * g.amul) * 2; const char* nB = (const char*)g.Bt2 + (size_t)cur.pn * tstepB;
;             PG8_KLOOP();
;             if (wr == 0) PG8_BAR;
;             E.mid(acc, cur, wr, wc, fr, fq);
;             cA = nA; cB = nB;
;             if (wr == 1) PG8_BAR;
;         }
;         const bool has_next = S.next(ui + 1, nxt);
;         const char* nA = has_next ? (const char*)g.A + (size_t)nxt.pm * tstepA + (size_t)((nxt.pn >> g.ash) * g.amul) * 2 : cA; const char* nB = has_next ? (const char*)g.Bt + (size_t)nxt.pn * tstepB : cB;
;         PG8_KLOOP();
;         if (wr == 0) PG8_BAR;
	s_setprio 0
	s_add_i32 s22, s24, s25
	v_lshl_add_u64 v[204:205], v[204:205], 0, s[34:35]
	s_mov_b32 m0, s22
	ds_read_b128 v[162:165], v232 offset:49152
	ds_read_b128 v[166:169], v232 offset:50176
	ds_read_b128 v[170:173], v232 offset:51200
	ds_read_b128 v[174:177], v232 offset:52224
	ds_read_b128 v[178:181], v232 offset:53248
	ds_read_b128 v[182:185], v232 offset:54272
	ds_read_b128 v[186:189], v232 offset:55296
	ds_read_b128 v[190:193], v232 offset:56320
	global_load_lds_dwordx4 v[204:205], off
	s_add_i32 m0, s22, 0x2000
	s_add_u32 s22, s26, 0x80080
	v_lshl_add_u64 v[204:205], v[206:207], 0, s[34:35]
	s_addc_u32 s23, s27, 0
	s_add_i32 s24, s50, s25
	global_load_lds_dwordx4 v[204:205], off
	v_lshl_add_u64 v[204:205], s[22:23], 0, v[0:1]
	s_mov_b32 m0, s24
	s_nop 0
	global_load_lds_dwordx4 v[204:205], off
	v_lshl_add_u64 v[204:205], s[22:23], 0, v[198:199]
	s_add_i32 m0, s24, 0x2000
	s_nop 0
	global_load_lds_dwordx4 v[204:205], off
	v_lshl_add_u64 v[204:205], v[208:209], 0, s[34:35]
	s_mov_b32 m0, s75
	s_nop 0
	global_load_lds_dwordx4 v[204:205], off
	v_lshl_add_u64 v[204:205], v[210:211], 0, s[34:35]
	s_mov_b32 m0, s76
	s_nop 0
	global_load_lds_dwordx4 v[204:205], off
	s_waitcnt vmcnt(8)
	s_waitcnt lgkmcnt(0)
	s_setprio 1
	s_barrier
	v_mfma_f32_16x16x32_bf16 v[62:65], v[130:133], v[162:165], v[62:65]
	v_mfma_f32_16x16x32_bf16 v[58:61], v[138:141], v[162:165], v[58:61]
	v_mfma_f32_16x16x32_bf16 v[46:49], v[130:133], v[170:173], v[46:49]
	v_mfma_f32_16x16x32_bf16 v[42:45], v[138:141], v[170:173], v[42:45]
	v_mfma_f32_16x16x32_bf16 v[30:33], v[130:133], v[178:181], v[30:33]
	v_mfma_f32_16x16x32_bf16 v[26:29], v[138:141], v[178:181], v[26:29]
	v_mfma_f32_16x16x32_bf16 v[14:17], v[130:133], v[186:189], v[14:17]
	v_mfma_f32_16x16x32_bf16 v[10:13], v[138:141], v[186:189], v[10:13]
	v_mfma_f32_16x16x32_bf16 v[62:65], v[134:137], v[166:169], v[62:65]
	v_mfma_f32_16x16x32_bf16 v[58:61], v[142:145], v[166:169], v[58:61]
	v_mfma_f32_16x16x32_bf16 v[46:49], v[134:137], v[174:177], v[46:49]
	v_mfma_f32_16x16x32_bf16 v[42:45], v[142:145], v[174:177], v[42:45]
	v_mfma_f32_16x16x32_bf16 v[30:33], v[134:137], v[182:185], v[30:33]
	v_mfma_f32_16x16x32_bf16 v[26:29], v[142:145], v[182:185], v[26:29]
	v_mfma_f32_16x16x32_bf16 v[14:17], v[134:137], v[190:193], v[14:17]
	v_mfma_f32_16x16x32_bf16 v[10:13], v[142:145], v[190:193], v[10:13]
	s_setprio 0
	s_setprio 1
	v_mfma_f32_16x16x32_bf16 v[54:57], v[146:149], v[162:165], v[54:57]
	v_mfma_f32_16x16x32_bf16 v[50:53], v[154:157], v[162:165], v[50:53]
	v_mfma_f32_16x16x32_bf16 v[38:41], v[146:149], v[170:173], v[38:41]
	v_mfma_f32_16x16x32_bf16 v[34:37], v[154:157], v[170:173], v[34:37]
	v_mfma_f32_16x16x32_bf16 v[22:25], v[146:149], v[178:181], v[22:25]
	v_mfma_f32_16x16x32_bf16 v[18:21], v[154:157], v[178:181], v[18:21]
	v_mfma_f32_16x16x32_bf16 v[6:9], v[146:149], v[186:189], v[6:9]
	v_mfma_f32_16x16x32_bf16 v[2:5], v[154:157], v[186:189], v[2:5]
	v_mfma_f32_16x16x32_bf16 v[54:57], v[150:153], v[166:169], v[54:57]
	v_mfma_f32_16x16x32_bf16 v[50:53], v[158:161], v[166:169], v[50:53]
	v_mfma_f32_16x16x32_bf16 v[38:41], v[150:153], v[174:177], v[38:41]
	v_mfma_f32_16x16x32_bf16 v[34:37], v[158:161], v[174:177], v[34:37]
	v_mfma_f32_16x16x32_bf16 v[22:25], v[150:153], v[182:185], v[22:25]
	v_mfma_f32_16x16x32_bf16 v[18:21], v[158:161], v[182:185], v[18:21]
	v_mfma_f32_16x16x32_bf16 v[6:9], v[150:153], v[190:193], v[6:9]
	v_mfma_f32_16x16x32_bf16 v[2:5], v[158:161], v[190:193], v[2:5]
	s_barrier
	s_setprio 0
	s_add_i32 s47, s47, 2
	s_add_u32 s90, s90, 0x100
	s_addc_u32 s91, s91, 0
	s_add_u32 s37, s37, 0x100
	s_addc_u32 s46, s46, 0
	s_cmp_gt_u32 s47, 29
	s_cbranch_scc0 .LBB0_646
	s_and_b64 vcc, exec, s[14:15]
	s_cbranch_vccz .LBB0_649
	s_barrier

; __device__ __forceinline__ int lane_id() { int l; asm volatile("v_mbcnt_lo_u32_b32 %0, -1, 0\n\tv_mbcnt_hi_u32_b32 %0, -1, %0" : "=v"(l)); return l; }
; #define PG8_STAGE(bufoff, gbase, voff) do { _Pragma("unroll") for (int _i = 0; _i < 2; ++_i) \
;         __builtin_amdgcn_global_load_lds((const unsigned*)((const char*)(gbase) + (voff)[_i]), (LAS unsigned*)(lds + (bufoff) + ldsw + _i * 8192), 16, 0, 0); } while (0)
; #define PG8_WAIT_V(n) asm volatile("s_waitcnt vmcnt(" #n ")" ::: "memory")
;     int tid = wave_s * 64 + lane_id(); asm volatile("" : "+v"(tid));
;     const int wid = __builtin_amdgcn_readfirstlane(tid >> 6), lane = tid & 63, wr = wid >> 2, wc = wid & 3, fr = lane & 15, fq = lane >> 4;
;     const int K = g.K, nt = K / BK, lda = g.lda;
;     unsigned voffA[2], voffB[2];
; #pragma unroll
;     for (int i = 0; i < 2; ++i) { int R, C; stage_rc(tid * 16 + i * 8192, R, C); const int Rb = Epi::PERM ? ((R & ~31) + perm32(R & 31)) : R;
;         voffA[i] = (unsigned)(R * lda + C) * 2u; voffB[i] = (unsigned)(Rb * K + C) * 2u; }
;     const size_t kstep = (size_t)(BK * 2);
;     const size_t hstepA = (size_t)HALF * lda * 2, hstepB = (size_t)HALF * K * 2;
;     const size_t tstepA = 2 * hstepA, tstepB = 2 * hstepB;
;     const unsigned ldsw = (unsigned)wid * 1024u;
;     const int aoff = lds_byte(wr * 64 + fr, fq * 8), boff = lds_byte(wc * 32 + fr, fq * 8);
;     ...
;     Unit cur, nxt; int ui = 0;
;     if (!S.next(0, cur)) return;
;     f32x4 acc[2][2][4][2];
; #pragma unroll
;     for (int a = 0; a < 2; ++a)
; #pragma unroll
;         for (int b = 0; b < 2; ++b)
; #pragma unroll
;             for (int m = 0; m < 4; ++m)
; #pragma unroll
;                 for (int n = 0; n < 2; ++n) acc[a][b][m][n] = (f32x4){0.f, 0.f, 0.f, 0.f};
;     bf16x8 At[4][2], B0[2][2], B1[2][2];
;     const char* cA = (const char*)g.A + (size_t)cur.pm * tstepA + (size_t)((cur.pn >> g.ash) * g.amul) * 2; const char* cB = (const char*)g.Bt + (size_t)cur.pn * tstepB;
;     PG8_STAGE(PG8_SB(0, 0), cB, voffB); PG8_STAGE(PG8_SB(0, 1), cB + hstepB, voffB); PG8_STAGE(PG8_SA(0, 0), cA, voffA); PG8_STAGE(PG8_SA(0, 1), cA + hstepA, voffA);
;     if (wr == 1) PG8_BAR;
;     PG8_WAIT_V(2); PG8_BAR;
;     PG8_STAGE(PG8_SB(1, 0), cB + kstep, voffB); PG8_STAGE(PG8_SA(1, 0), cA + kstep, voffA); PG8_STAGE(PG8_SB(1, 1), cB + hstepB + kstep, voffB);
;     PG8_WAIT_V(6); PG8_BAR;
.LBB0_764:
	s_add_u32 s8, s10, 0x12800000
	s_addc_u32 s9, s11, 0
	s_lshl_b64 s[2:3], s[2:3], 2
	s_add_u32 s2, s10, s2
	s_addc_u32 s3, s11, s3
	v_and_b32_e32 v17, 15, v16
	v_bfe_u32 v16, v16, 4, 2
	s_add_u32 s2, s2, 0x36c00000
	v_lshlrev_b32_e32 v18, 3, v16
	v_lshlrev_b32_e32 v16, 4, v16
	v_lshlrev_b32_e32 v20, 2, v17
	s_addc_u32 s3, s3, 0
	s_lshl_b32 s50, s76, 9
	s_and_b32 s14, s14, 3
	v_lshl_or_b32 v19, v17, 6, v16
	s_lshl_b32 s10, s13, 13
	v_and_b32_e32 v21, 32, v20
	s_add_i32 m0, s38, 0x18000
	v_lshl_add_u64 v[8:9], v[8:9], 0, s[34:35]
	s_addk_i32 s50, 0x200
	v_bitop3_b32 v22, v19, s10, v21 bitop3:0xde
	s_lshl_b32 s10, s14, 12
	s_waitcnt vmcnt(2)
	s_barrier
	global_load_lds_dwordx4 v[8:9], off
	v_lshl_add_u64 v[6:7], v[6:7], 0, s[34:35]
	s_add_i32 m0, s38, 0x1a000
	s_add_i32 s51, s38, 0x8000
	s_add_i32 s56, s38, 0xa000
	v_bitop3_b32 v153, v19, s10, v21 bitop3:0xde
	global_load_lds_dwordx4 v[6:7], off
	v_lshl_add_u64 v[2:3], v[2:3], 0, s[34:35]
	s_mov_b32 m0, s51
	s_add_u32 s10, s46, 0x80080
	global_load_lds_dwordx4 v[2:3], off
	v_lshl_add_u64 v[2:3], v[4:5], 0, s[34:35]
	s_mov_b32 m0, s56
	s_addc_u32 s11, s47, 0
	global_load_lds_dwordx4 v[2:3], off
	s_add_i32 m0, s38, 0x1c000
	v_lshl_add_u64 v[2:3], s[10:11], 0, v[0:1]
	global_load_lds_dwordx4 v[2:3], off
	v_lshl_add_u64 v[2:3], s[10:11], 0, v[130:131]
	s_add_i32 m0, s38, 0x1e000
	s_cmpk_lt_u32 s12, 0x100
	global_load_lds_dwordx4 v[2:3], off
	s_cselect_b64 s[10:11], -1, 0
	s_and_b32 s12, s12, 0xffffff00
	v_lshl_or_b32 v2, s14, 6, v16
	v_or3_b32 v155, v2, s12, v17
	v_lshlrev_b32_e32 v2, 15, v14
	v_and_b32_e32 v2, 0xffff0000, v2
	v_lshl_add_u32 v2, v13, 12, v2
	v_and_b32_e32 v3, 1, v14
	v_lshl_or_b32 v152, s13, 6, v17
	s_movk_i32 s13, 0x100
	s_add_i32 s12, s12, 0
	v_lshl_or_b32 v2, v3, 6, v2
	v_cmp_gt_i32_e64 s[40:41], s13, v155
	s_add_i32 s13, s12, 0x22100
	s_add_i32 s12, s12, 0x22300
	v_lshl_add_u32 v136, v15, 1, v2
	v_lshlrev_b32_e32 v2, 15, v10
	v_add_u32_e32 v157, s13, v20
	v_add_u32_e32 v158, s12, v20
	v_and_b32_e32 v2, 0xffff0000, v2
	v_readlane_b32 s12, v254, 33
	s_waitcnt vmcnt(6)
	v_lshl_add_u32 v2, v11, 12, v2
	v_and_b32_e32 v3, 1, v10
	v_readlane_b32 s13, v254, 34
	v_lshl_or_b32 v2, v3, 6, v2
	s_mov_b32 s36, s12
	v_readlane_b32 s12, v254, 29
	v_lshl_or_b32 v154, s14, 5, v18
	s_mov_b32 s57, 0
	v_cmp_eq_u32_e64 s[42:43], 0, v155
	v_lshl_add_u32 v156, v155, 2, s0
	v_mov_b32_e32 v137, v1
	v_lshl_add_u32 v138, v12, 1, v2
	v_mov_b32_e32 v139, v1
	v_add_u32_e32 v159, 0, v22
	s_mov_b32 s37, s12
	s_barrier
	v_readlane_b32 s13, v254, 30
	s_mov_b32 s100, 0
	s_branch .LBB0_767

; #define PG8_BAR __builtin_amdgcn_s_barrier()
;     ...
;         const bool has_next = S.next(ui + 1, nxt);
;         const char* nA = has_next ? (const char*)g.A + (size_t)nxt.pm * tstepA + (size_t)((nxt.pn >> g.ash) * g.amul) * 2 : cA; const char* nB = has_next ? (const char*)g.Bt + (size_t)nxt.pn * tstepB : cB;
;         PG8_KLOOP();
;         if (wr == 0) PG8_BAR;
;         E(acc, cur, wr, wc, fr, fq);
;         if (!has_next) break;
; #pragma unroll
;         for (int a = 0; a < 2; ++a)
; #pragma unroll
;             for (int b = 0; b < 2; ++b)
; #pragma unroll
;                 for (int m = 0; m < 4; ++m)
; #pragma unroll
;                     for (int n = 0; n < 2; ++n) acc[a][b][m][n] = (f32x4){0.f, 0.f, 0.f, 0.f};
;         cur = nxt; cA = nA; cB = nB; ++ui;
;         if (wr == 1) PG8_BAR;
.LBB0_766:
	s_mov_b32 s100, 1
	s_andn2_b64 vcc, exec, s[20:21]
	s_mov_b32 s36, s12
	s_mov_b32 s37, s14
	s_mov_b64 s[46:47], s[18:19]
	s_mov_b64 s[20:21], s[16:17]
	s_cbranch_vccz .LBB0_785

.LBB0_774:
	s_add_u32 s22, s20, 0xfff80080
	s_addc_u32 s23, s21, -1
	s_add_i32 s24, 0, 0x10000
	s_cmp_eq_u32 s62, 28
	s_cselect_b32 s23, s15, s23
	s_cselect_b32 s22, s60, s22
	s_cselect_b32 s27, s13, s47
	s_cselect_b32 s26, s61, s46
	s_add_i32 s63, 0, 0x14000
	v_add_u32_e32 v160, s24, v153
	v_add_u32_e32 v176, s63, v153
	ds_read_b128 v[140:143], v160
	ds_read_b128 v[144:147], v160 offset:1024
	ds_read_b128 v[148:151], v160 offset:2048
	ds_read_b128 v[160:163], v160 offset:3072
	ds_read_b128 v[164:167], v176
	ds_read_b128 v[168:171], v176 offset:1024
	ds_read_b128 v[172:175], v176 offset:2048
	ds_read_b128 v[176:179], v176 offset:3072
	v_lshl_add_u64 v[212:213], s[20:21], 0, v[136:137]
	s_add_i32 m0, s38, 0xc000
	ds_read_b128 v[180:183], v159
	ds_read_b128 v[184:187], v159 offset:1024
	ds_read_b128 v[188:191], v159 offset:2048
	ds_read_b128 v[192:195], v159 offset:3072
	ds_read_b128 v[196:199], v159 offset:4096
	ds_read_b128 v[200:203], v159 offset:5120
	ds_read_b128 v[204:207], v159 offset:6144
	ds_read_b128 v[208:211], v159 offset:7168
	global_load_lds_dwordx4 v[212:213], off
	v_lshl_add_u64 v[212:213], s[20:21], 0, v[138:139]
	s_add_i32 m0, s38, 0xe000
	s_nop 0
	global_load_lds_dwordx4 v[212:213], off
	s_cmp_lg_u32 s100, 0
	s_cbranch_scc1 .Lcw_g6_p1
	s_waitcnt vmcnt(8)
.Lcw_g6_c1:
	s_waitcnt lgkmcnt(0)
	s_setprio 1
	s_barrier
	v_mfma_f32_16x16x32_bf16 v[126:129], v[140:143], v[180:183], v[126:129]
	v_mfma_f32_16x16x32_bf16 v[122:125], v[148:151], v[180:183], v[122:125]
	v_mfma_f32_16x16x32_bf16 v[110:113], v[140:143], v[188:191], v[110:113]
	v_mfma_f32_16x16x32_bf16 v[106:109], v[148:151], v[188:191], v[106:109]
	v_mfma_f32_16x16x32_bf16 v[94:97], v[140:143], v[196:199], v[94:97]
	v_mfma_f32_16x16x32_bf16 v[90:93], v[148:151], v[196:199], v[90:93]
	v_mfma_f32_16x16x32_bf16 v[78:81], v[140:143], v[204:207], v[78:81]
	v_mfma_f32_16x16x32_bf16 v[74:77], v[148:151], v[204:207], v[74:77]
	v_mfma_f32_16x16x32_bf16 v[126:129], v[144:147], v[184:187], v[126:129]
	v_mfma_f32_16x16x32_bf16 v[122:125], v[160:163], v[184:187], v[122:125]
	v_mfma_f32_16x16x32_bf16 v[110:113], v[144:147], v[192:195], v[110:113]
	v_mfma_f32_16x16x32_bf16 v[106:109], v[160:163], v[192:195], v[106:109]
	v_mfma_f32_16x16x32_bf16 v[94:97], v[144:147], v[200:203], v[94:97]
	v_mfma_f32_16x16x32_bf16 v[90:93], v[160:163], v[200:203], v[90:93]
	v_mfma_f32_16x16x32_bf16 v[78:81], v[144:147], v[208:211], v[78:81]
	v_mfma_f32_16x16x32_bf16 v[74:77], v[160:163], v[208:211], v[74:77]
	s_setprio 0
	s_setprio 1
	v_mfma_f32_16x16x32_bf16 v[118:121], v[164:167], v[180:183], v[118:121]
	v_mfma_f32_16x16x32_bf16 v[114:117], v[172:175], v[180:183], v[114:117]
	v_mfma_f32_16x16x32_bf16 v[102:105], v[164:167], v[188:191], v[102:105]
	v_mfma_f32_16x16x32_bf16 v[98:101], v[172:175], v[188:191], v[98:101]
	v_mfma_f32_16x16x32_bf16 v[86:89], v[164:167], v[196:199], v[86:89]
	v_mfma_f32_16x16x32_bf16 v[82:85], v[172:175], v[196:199], v[82:85]
	v_mfma_f32_16x16x32_bf16 v[70:73], v[164:167], v[204:207], v[70:73]
	v_mfma_f32_16x16x32_bf16 v[66:69], v[172:175], v[204:207], v[66:69]
	v_mfma_f32_16x16x32_bf16 v[118:121], v[168:171], v[184:187], v[118:121]
	v_mfma_f32_16x16x32_bf16 v[114:117], v[176:179], v[184:187], v[114:117]
	v_mfma_f32_16x16x32_bf16 v[102:105], v[168:171], v[192:195], v[102:105]
	v_mfma_f32_16x16x32_bf16 v[98:101], v[176:179], v[192:195], v[98:101]
	v_mfma_f32_16x16x32_bf16 v[86:89], v[168:171], v[200:203], v[86:89]
	v_mfma_f32_16x16x32_bf16 v[82:85], v[176:179], v[200:203], v[82:85]
	v_mfma_f32_16x16x32_bf16 v[70:73], v[168:171], v[208:211], v[70:73]
	v_mfma_f32_16x16x32_bf16 v[66:69], v[176:179], v[208:211], v[66:69]
	s_barrier
	s_setprio 0
	s_add_i32 s24, s24, s29
	v_lshl_add_u64 v[212:213], s[26:27], 0, v[0:1]
	s_mov_b32 m0, s24
	ds_read_b128 v[180:183], v159 offset:16384
	ds_read_b128 v[184:187], v159 offset:17408
	ds_read_b128 v[188:191], v159 offset:18432
	ds_read_b128 v[192:195], v159 offset:19456
	ds_read_b128 v[196:199], v159 offset:20480
	ds_read_b128 v[200:203], v159 offset:21504
	ds_read_b128 v[204:207], v159 offset:22528
	ds_read_b128 v[208:211], v159 offset:23552
	global_load_lds_dwordx4 v[212:213], off
	s_add_i32 m0, s24, 0x2000
	s_add_u32 s64, s26, 0x80000
	v_lshl_add_u64 v[214:215], s[26:27], 0, v[130:131]
	s_addc_u32 s65, s27, 0
	s_add_i32 s24, s63, s29
	global_load_lds_dwordx4 v[214:215], off
	v_lshl_add_u64 v[216:217], s[64:65], 0, v[0:1]
	s_mov_b32 m0, s24
	v_lshl_add_u64 v[218:219], s[22:23], 0, v[132:133]
	global_load_lds_dwordx4 v[216:217], off
	v_lshl_add_u64 v[216:217], s[64:65], 0, v[130:131]
	s_add_i32 m0, s24, 0x2000
	s_nop 0
	global_load_lds_dwordx4 v[216:217], off
	v_lshl_add_u64 v[216:217], s[22:23], 0, v[134:135]
	s_mov_b32 m0, s38
	s_nop 0
	global_load_lds_dwordx4 v[216:217], off
	s_mov_b32 m0, s39
	s_nop 0
	global_load_lds_dwordx4 v[218:219], off
	s_cmp_lg_u32 s100, 0
	s_cbranch_scc1 .Lcw_g6_p2
	s_waitcnt vmcnt(8)
.Lcw_g6_c2:
	s_waitcnt lgkmcnt(0)
	s_setprio 1
	s_barrier
	v_mfma_f32_16x16x32_bf16 v[62:65], v[140:143], v[180:183], v[62:65]
	v_mfma_f32_16x16x32_bf16 v[58:61], v[148:151], v[180:183], v[58:61]
	v_mfma_f32_16x16x32_bf16 v[46:49], v[140:143], v[188:191], v[46:49]
	v_mfma_f32_16x16x32_bf16 v[42:45], v[148:151], v[188:191], v[42:45]
	v_mfma_f32_16x16x32_bf16 v[30:33], v[140:143], v[196:199], v[30:33]
	v_mfma_f32_16x16x32_bf16 v[26:29], v[148:151], v[196:199], v[26:29]
	v_mfma_f32_16x16x32_bf16 v[14:17], v[140:143], v[204:207], v[14:17]
	v_mfma_f32_16x16x32_bf16 v[10:13], v[148:151], v[204:207], v[10:13]
	v_mfma_f32_16x16x32_bf16 v[62:65], v[144:147], v[184:187], v[62:65]
	v_mfma_f32_16x16x32_bf16 v[58:61], v[160:163], v[184:187], v[58:61]
	v_mfma_f32_16x16x32_bf16 v[46:49], v[144:147], v[192:195], v[46:49]
	v_mfma_f32_16x16x32_bf16 v[42:45], v[160:163], v[192:195], v[42:45]
	v_mfma_f32_16x16x32_bf16 v[30:33], v[144:147], v[200:203], v[30:33]
	v_mfma_f32_16x16x32_bf16 v[26:29], v[160:163], v[200:203], v[26:29]
	v_mfma_f32_16x16x32_bf16 v[14:17], v[144:147], v[208:211], v[14:17]
	v_mfma_f32_16x16x32_bf16 v[10:13], v[160:163], v[208:211], v[10:13]
	s_setprio 0
	s_setprio 1
	v_mfma_f32_16x16x32_bf16 v[54:57], v[164:167], v[180:183], v[54:57]
	v_mfma_f32_16x16x32_bf16 v[50:53], v[172:175], v[180:183], v[50:53]
	v_mfma_f32_16x16x32_bf16 v[38:41], v[164:167], v[188:191], v[38:41]
	v_mfma_f32_16x16x32_bf16 v[34:37], v[172:175], v[188:191], v[34:37]
	v_mfma_f32_16x16x32_bf16 v[22:25], v[164:167], v[196:199], v[22:25]
	v_mfma_f32_16x16x32_bf16 v[18:21], v[172:175], v[196:199], v[18:21]
	v_mfma_f32_16x16x32_bf16 v[6:9], v[164:167], v[204:207], v[6:9]
	v_mfma_f32_16x16x32_bf16 v[2:5], v[172:175], v[204:207], v[2:5]
	v_mfma_f32_16x16x32_bf16 v[54:57], v[168:171], v[184:187], v[54:57]
	v_mfma_f32_16x16x32_bf16 v[50:53], v[176:179], v[184:187], v[50:53]
	v_mfma_f32_16x16x32_bf16 v[38:41], v[168:171], v[192:195], v[38:41]
	v_mfma_f32_16x16x32_bf16 v[34:37], v[176:179], v[192:195], v[34:37]
	v_mfma_f32_16x16x32_bf16 v[22:25], v[168:171], v[200:203], v[22:25]
	v_mfma_f32_16x16x32_bf16 v[18:21], v[176:179], v[200:203], v[18:21]
	v_mfma_f32_16x16x32_bf16 v[6:9], v[168:171], v[208:211], v[6:9]
	v_mfma_f32_16x16x32_bf16 v[2:5], v[176:179], v[208:211], v[2:5]
	s_barrier
	s_setprio 0
	s_add_i32 s24, 0, 0x18000
	s_add_i32 s63, 0, 0x1c000
	v_add_u32_e32 v160, s24, v153
	v_add_u32_e32 v176, s63, v153
	ds_read_b128 v[140:143], v160
	ds_read_b128 v[144:147], v160 offset:1024
	ds_read_b128 v[148:151], v160 offset:2048
	ds_read_b128 v[160:163], v160 offset:3072
	ds_read_b128 v[164:167], v176
	ds_read_b128 v[168:171], v176 offset:1024
	ds_read_b128 v[172:175], v176 offset:2048
	ds_read_b128 v[176:179], v176 offset:3072
	s_add_u32 s22, s22, 0x80000
	s_addc_u32 s23, s23, 0
	s_mov_b32 m0, s48
	v_lshl_add_u64 v[220:221], s[22:23], 0, v[134:135]
	ds_read_b128 v[180:183], v159 offset:32768
	ds_read_b128 v[184:187], v159 offset:33792
	ds_read_b128 v[188:191], v159 offset:34816
	ds_read_b128 v[192:195], v159 offset:35840
	ds_read_b128 v[196:199], v159 offset:36864
	ds_read_b128 v[200:203], v159 offset:37888
	ds_read_b128 v[204:207], v159 offset:38912
	ds_read_b128 v[208:211], v159 offset:39936
	global_load_lds_dwordx4 v[220:221], off
	v_lshl_add_u64 v[220:221], s[22:23], 0, v[132:133]
	s_mov_b32 m0, s49
	s_nop 0
	global_load_lds_dwordx4 v[220:221], off
	s_waitcnt vmcnt(8)
	s_waitcnt lgkmcnt(0)
	s_setprio 1
	s_barrier
	v_mfma_f32_16x16x32_bf16 v[126:129], v[140:143], v[180:183], v[126:129]
	v_mfma_f32_16x16x32_bf16 v[122:125], v[148:151], v[180:183], v[122:125]
	v_mfma_f32_16x16x32_bf16 v[110:113], v[140:143], v[188:191], v[110:113]
	v_mfma_f32_16x16x32_bf16 v[106:109], v[148:151], v[188:191], v[106:109]
	v_mfma_f32_16x16x32_bf16 v[94:97], v[140:143], v[196:199], v[94:97]
	v_mfma_f32_16x16x32_bf16 v[90:93], v[148:151], v[196:199], v[90:93]
	v_mfma_f32_16x16x32_bf16 v[78:81], v[140:143], v[204:207], v[78:81]
	v_mfma_f32_16x16x32_bf16 v[74:77], v[148:151], v[204:207], v[74:77]
	v_mfma_f32_16x16x32_bf16 v[126:129], v[144:147], v[184:187], v[126:129]
	v_mfma_f32_16x16x32_bf16 v[122:125], v[160:163], v[184:187], v[122:125]
	v_mfma_f32_16x16x32_bf16 v[110:113], v[144:147], v[192:195], v[110:113]
	v_mfma_f32_16x16x32_bf16 v[106:109], v[160:163], v[192:195], v[106:109]
	v_mfma_f32_16x16x32_bf16 v[94:97], v[144:147], v[200:203], v[94:97]
	v_mfma_f32_16x16x32_bf16 v[90:93], v[160:163], v[200:203], v[90:93]
	v_mfma_f32_16x16x32_bf16 v[78:81], v[144:147], v[208:211], v[78:81]
	v_mfma_f32_16x16x32_bf16 v[74:77], v[160:163], v[208:211], v[74:77]
	s_setprio 0
	s_setprio 1
	v_mfma_f32_16x16x32_bf16 v[118:121], v[164:167], v[180:183], v[118:121]
	v_mfma_f32_16x16x32_bf16 v[114:117], v[172:175], v[180:183], v[114:117]
	v_mfma_f32_16x16x32_bf16 v[102:105], v[164:167], v[188:191], v[102:105]
	v_mfma_f32_16x16x32_bf16 v[98:101], v[172:175], v[188:191], v[98:101]
	v_mfma_f32_16x16x32_bf16 v[86:89], v[164:167], v[196:199], v[86:89]
	v_mfma_f32_16x16x32_bf16 v[82:85], v[172:175], v[196:199], v[82:85]
	v_mfma_f32_16x16x32_bf16 v[70:73], v[164:167], v[204:207], v[70:73]
	v_mfma_f32_16x16x32_bf16 v[66:69], v[172:175], v[204:207], v[66:69]
	v_mfma_f32_16x16x32_bf16 v[118:121], v[168:171], v[184:187], v[118:121]
	v_mfma_f32_16x16x32_bf16 v[114:117], v[176:179], v[184:187], v[114:117]
	v_mfma_f32_16x16x32_bf16 v[102:105], v[168:171], v[192:195], v[102:105]
	v_mfma_f32_16x16x32_bf16 v[98:101], v[176:179], v[192:195], v[98:101]
	v_mfma_f32_16x16x32_bf16 v[86:89], v[168:171], v[200:203], v[86:89]
	v_mfma_f32_16x16x32_bf16 v[82:85], v[176:179], v[200:203], v[82:85]
	v_mfma_f32_16x16x32_bf16 v[70:73], v[168:171], v[208:211], v[70:73]
	v_mfma_f32_16x16x32_bf16 v[66:69], v[176:179], v[208:211], v[66:69]
	s_barrier
; #define PG8_BAR __builtin_amdgcn_s_barrier()
;     ...
;     for (;;) {
;         if constexpr (NSEG > 1) {
;             const char* nA = (const char*)g.A2 + (size_t)cur.pm * tstepA + (size_t)((cur.pn >> g.ash) * g.amul) * 2; const char* nB = (const char*)g.Bt2 + (size_t)cur.pn * tstepB;
;             PG8_KLOOP();
;             if (wr == 0) PG8_BAR;
;             E.mid(acc, cur, wr, wc, fr, fq);
;             cA = nA; cB = nB;
;             if (wr == 1) PG8_BAR;
;         }
;         const bool has_next = S.next(ui + 1, nxt);
;         const char* nA = has_next ? (const char*)g.A + (size_t)nxt.pm * tstepA + (size_t)((nxt.pn >> g.ash) * g.amul) * 2 : cA; const char* nB = has_next ? (const char*)g.Bt + (size_t)nxt.pn * tstepB : cB;
;         PG8_KLOOP();
;         if (wr == 0) PG8_BAR;
	s_setprio 0
	s_add_i32 s22, s24, s29
	v_lshl_add_u64 v[212:213], v[212:213], 0, s[34:35]
	s_mov_b32 m0, s22
	ds_read_b128 v[180:183], v159 offset:49152
	ds_read_b128 v[184:187], v159 offset:50176
	ds_read_b128 v[188:191], v159 offset:51200
	ds_read_b128 v[192:195], v159 offset:52224
	ds_read_b128 v[196:199], v159 offset:53248
	ds_read_b128 v[200:203], v159 offset:54272
	ds_read_b128 v[204:207], v159 offset:55296
	ds_read_b128 v[208:211], v159 offset:56320
	global_load_lds_dwordx4 v[212:213], off
	s_add_i32 m0, s22, 0x2000
	s_add_u32 s22, s26, 0x80080
	v_lshl_add_u64 v[212:213], v[214:215], 0, s[34:35]
	s_addc_u32 s23, s27, 0
	s_add_i32 s24, s63, s29
	global_load_lds_dwordx4 v[212:213], off
	v_lshl_add_u64 v[212:213], s[22:23], 0, v[0:1]
	s_mov_b32 m0, s24
	s_nop 0
	global_load_lds_dwordx4 v[212:213], off
	v_lshl_add_u64 v[212:213], s[22:23], 0, v[130:131]
	s_add_i32 m0, s24, 0x2000
	s_nop 0
	global_load_lds_dwordx4 v[212:213], off
	v_lshl_add_u64 v[212:213], v[216:217], 0, s[34:35]
	s_mov_b32 m0, s51
	s_nop 0
	global_load_lds_dwordx4 v[212:213], off
	v_lshl_add_u64 v[212:213], v[218:219], 0, s[34:35]
	s_mov_b32 m0, s56
	s_nop 0
	global_load_lds_dwordx4 v[212:213], off
	s_waitcnt vmcnt(8)
	s_waitcnt lgkmcnt(0)
	s_setprio 1
	s_barrier
	v_mfma_f32_16x16x32_bf16 v[62:65], v[140:143], v[180:183], v[62:65]
	v_mfma_f32_16x16x32_bf16 v[58:61], v[148:151], v[180:183], v[58:61]
	v_mfma_f32_16x16x32_bf16 v[46:49], v[140:143], v[188:191], v[46:49]
	v_mfma_f32_16x16x32_bf16 v[42:45], v[148:151], v[188:191], v[42:45]
	v_mfma_f32_16x16x32_bf16 v[30:33], v[140:143], v[196:199], v[30:33]
	v_mfma_f32_16x16x32_bf16 v[26:29], v[148:151], v[196:199], v[26:29]
	v_mfma_f32_16x16x32_bf16 v[14:17], v[140:143], v[204:207], v[14:17]
	v_mfma_f32_16x16x32_bf16 v[10:13], v[148:151], v[204:207], v[10:13]
	v_mfma_f32_16x16x32_bf16 v[62:65], v[144:147], v[184:187], v[62:65]
	v_mfma_f32_16x16x32_bf16 v[58:61], v[160:163], v[184:187], v[58:61]
	v_mfma_f32_16x16x32_bf16 v[46:49], v[144:147], v[192:195], v[46:49]
	v_mfma_f32_16x16x32_bf16 v[42:45], v[160:163], v[192:195], v[42:45]
	v_mfma_f32_16x16x32_bf16 v[30:33], v[144:147], v[200:203], v[30:33]
	v_mfma_f32_16x16x32_bf16 v[26:29], v[160:163], v[200:203], v[26:29]
	v_mfma_f32_16x16x32_bf16 v[14:17], v[144:147], v[208:211], v[14:17]
	v_mfma_f32_16x16x32_bf16 v[10:13], v[160:163], v[208:211], v[10:13]
	s_setprio 0
	s_setprio 1
	v_mfma_f32_16x16x32_bf16 v[54:57], v[164:167], v[180:183], v[54:57]
	v_mfma_f32_16x16x32_bf16 v[50:53], v[172:175], v[180:183], v[50:53]
	v_mfma_f32_16x16x32_bf16 v[38:41], v[164:167], v[188:191], v[38:41]
	v_mfma_f32_16x16x32_bf16 v[34:37], v[172:175], v[188:191], v[34:37]
	v_mfma_f32_16x16x32_bf16 v[22:25], v[164:167], v[196:199], v[22:25]
	v_mfma_f32_16x16x32_bf16 v[18:21], v[172:175], v[196:199], v[18:21]
	v_mfma_f32_16x16x32_bf16 v[6:9], v[164:167], v[204:207], v[6:9]
	v_mfma_f32_16x16x32_bf16 v[2:5], v[172:175], v[204:207], v[2:5]
	v_mfma_f32_16x16x32_bf16 v[54:57], v[168:171], v[184:187], v[54:57]
	v_mfma_f32_16x16x32_bf16 v[50:53], v[176:179], v[184:187], v[50:53]
	v_mfma_f32_16x16x32_bf16 v[38:41], v[168:171], v[192:195], v[38:41]
	v_mfma_f32_16x16x32_bf16 v[34:37], v[176:179], v[192:195], v[34:37]
	v_mfma_f32_16x16x32_bf16 v[22:25], v[168:171], v[200:203], v[22:25]
	v_mfma_f32_16x16x32_bf16 v[18:21], v[176:179], v[200:203], v[18:21]
	v_mfma_f32_16x16x32_bf16 v[6:9], v[168:171], v[208:211], v[6:9]
	v_mfma_f32_16x16x32_bf16 v[2:5], v[176:179], v[208:211], v[2:5]
	s_barrier
	s_setprio 0
	s_add_i32 s62, s62, 2
	s_add_u32 s20, s20, 0x100
	s_addc_u32 s21, s21, 0
	s_add_u32 s46, s46, 0x100
	s_addc_u32 s47, s47, 0
	s_cmp_gt_u32 s62, 29
	s_cbranch_scc0 .LBB0_774
	s_and_b64 vcc, exec, s[10:11]
	s_cbranch_vccz .LBB0_777
	s_barrier

.LBB0_882:
	s_add_u32 s22, s46, 0xffe00080
	s_addc_u32 s23, s47, -1
	s_add_i32 s24, 0, 0x10000
	s_cmpk_eq_i32 s39, 0x7c
	s_cselect_b32 s23, s13, s23
	s_cselect_b32 s22, s19, s22
	s_cselect_b32 s27, s11, s37
	s_cselect_b32 s26, s21, s36
	s_add_i32 s64, 0, 0x14000
	v_add_u32_e32 v142, s24, v209
	v_add_u32_e32 v168, s64, v209
	ds_read_b128 v[130:133], v142
	ds_read_b128 v[134:137], v142 offset:1024
	ds_read_b128 v[138:141], v142 offset:2048
	ds_read_b128 v[142:145], v142 offset:3072
	ds_read_b128 v[146:149], v168
	ds_read_b128 v[150:153], v168 offset:1024
	ds_read_b128 v[154:157], v168 offset:2048
	ds_read_b128 v[168:171], v168 offset:3072
	v_lshl_add_u64 v[204:205], s[46:47], 0, v[164:165]
	s_add_i32 m0, s60, 0xc000
	ds_read_b128 v[172:175], v224
	ds_read_b128 v[176:179], v224 offset:1024
	ds_read_b128 v[180:183], v224 offset:2048
	ds_read_b128 v[184:187], v224 offset:3072
	ds_read_b128 v[188:191], v224 offset:4096
	ds_read_b128 v[192:195], v224 offset:5120
	ds_read_b128 v[196:199], v224 offset:6144
	ds_read_b128 v[200:203], v224 offset:7168
	global_load_lds_dwordx4 v[204:205], off
	v_lshl_add_u64 v[204:205], s[46:47], 0, v[166:167]
	s_add_i32 m0, s60, 0xe000
	s_nop 0
	global_load_lds_dwordx4 v[204:205], off
	s_waitcnt vmcnt(8)
	s_waitcnt lgkmcnt(0)
	s_setprio 1
	s_barrier
	v_mfma_f32_16x16x32_bf16 v[126:129], v[130:133], v[172:175], v[126:129]
	v_mfma_f32_16x16x32_bf16 v[122:125], v[138:141], v[172:175], v[122:125]
	v_mfma_f32_16x16x32_bf16 v[110:113], v[130:133], v[180:183], v[110:113]
	v_mfma_f32_16x16x32_bf16 v[106:109], v[138:141], v[180:183], v[106:109]
	v_mfma_f32_16x16x32_bf16 v[94:97], v[130:133], v[188:191], v[94:97]
	v_mfma_f32_16x16x32_bf16 v[90:93], v[138:141], v[188:191], v[90:93]
	v_mfma_f32_16x16x32_bf16 v[78:81], v[130:133], v[196:199], v[78:81]
	v_mfma_f32_16x16x32_bf16 v[74:77], v[138:141], v[196:199], v[74:77]
	v_mfma_f32_16x16x32_bf16 v[126:129], v[134:137], v[176:179], v[126:129]
	v_mfma_f32_16x16x32_bf16 v[122:125], v[142:145], v[176:179], v[122:125]
	v_mfma_f32_16x16x32_bf16 v[110:113], v[134:137], v[184:187], v[110:113]
	v_mfma_f32_16x16x32_bf16 v[106:109], v[142:145], v[184:187], v[106:109]
	v_mfma_f32_16x16x32_bf16 v[94:97], v[134:137], v[192:195], v[94:97]
	v_mfma_f32_16x16x32_bf16 v[90:93], v[142:145], v[192:195], v[90:93]
	v_mfma_f32_16x16x32_bf16 v[78:81], v[134:137], v[200:203], v[78:81]
	v_mfma_f32_16x16x32_bf16 v[74:77], v[142:145], v[200:203], v[74:77]
	s_setprio 0
	s_setprio 1
	v_mfma_f32_16x16x32_bf16 v[118:121], v[146:149], v[172:175], v[118:121]
	v_mfma_f32_16x16x32_bf16 v[114:117], v[154:157], v[172:175], v[114:117]
	v_mfma_f32_16x16x32_bf16 v[102:105], v[146:149], v[180:183], v[102:105]
	v_mfma_f32_16x16x32_bf16 v[98:101], v[154:157], v[180:183], v[98:101]
	v_mfma_f32_16x16x32_bf16 v[86:89], v[146:149], v[188:191], v[86:89]
	v_mfma_f32_16x16x32_bf16 v[82:85], v[154:157], v[188:191], v[82:85]
	v_mfma_f32_16x16x32_bf16 v[70:73], v[146:149], v[196:199], v[70:73]
	v_mfma_f32_16x16x32_bf16 v[66:69], v[154:157], v[196:199], v[66:69]
	v_mfma_f32_16x16x32_bf16 v[118:121], v[150:153], v[176:179], v[118:121]
	v_mfma_f32_16x16x32_bf16 v[114:117], v[168:171], v[176:179], v[114:117]
	v_mfma_f32_16x16x32_bf16 v[102:105], v[150:153], v[184:187], v[102:105]
	v_mfma_f32_16x16x32_bf16 v[98:101], v[168:171], v[184:187], v[98:101]
	v_mfma_f32_16x16x32_bf16 v[86:89], v[150:153], v[192:195], v[86:89]
	v_mfma_f32_16x16x32_bf16 v[82:85], v[168:171], v[192:195], v[82:85]
	v_mfma_f32_16x16x32_bf16 v[70:73], v[150:153], v[200:203], v[70:73]
	v_mfma_f32_16x16x32_bf16 v[66:69], v[168:171], v[200:203], v[66:69]
	s_barrier
	s_setprio 0
	s_add_i32 s24, s24, s57
	v_lshl_add_u64 v[204:205], s[26:27], 0, v[0:1]
	s_mov_b32 m0, s24
	ds_read_b128 v[172:175], v224 offset:16384
	ds_read_b128 v[176:179], v224 offset:17408
	ds_read_b128 v[180:183], v224 offset:18432
	ds_read_b128 v[184:187], v224 offset:19456
	ds_read_b128 v[188:191], v224 offset:20480
	ds_read_b128 v[192:195], v224 offset:21504
	ds_read_b128 v[196:199], v224 offset:22528
	ds_read_b128 v[200:203], v224 offset:23552
	global_load_lds_dwordx4 v[204:205], off
	s_add_i32 m0, s24, 0x2000
	s_add_u32 s62, s26, 0x200000
	v_lshl_add_u64 v[214:215], s[26:27], 0, v[162:163]
	s_addc_u32 s63, s27, 0
	s_add_i32 s24, s64, s57
	global_load_lds_dwordx4 v[214:215], off
	v_lshl_add_u64 v[230:231], s[62:63], 0, v[0:1]
	s_mov_b32 m0, s24
	v_lshl_add_u64 v[232:233], s[22:23], 0, v[160:161]
	global_load_lds_dwordx4 v[230:231], off
	v_lshl_add_u64 v[230:231], s[62:63], 0, v[162:163]
	s_add_i32 m0, s24, 0x2000
	s_nop 0
	global_load_lds_dwordx4 v[230:231], off
	v_lshl_add_u64 v[230:231], s[22:23], 0, v[158:159]
	s_mov_b32 m0, s60
	s_nop 0
	global_load_lds_dwordx4 v[230:231], off
	s_mov_b32 m0, s61
	s_nop 0
	global_load_lds_dwordx4 v[232:233], off
	s_waitcnt vmcnt(8)
	s_waitcnt lgkmcnt(0)
	s_setprio 1
	s_barrier
	v_mfma_f32_16x16x32_bf16 v[62:65], v[130:133], v[172:175], v[62:65]
	v_mfma_f32_16x16x32_bf16 v[58:61], v[138:141], v[172:175], v[58:61]
	v_mfma_f32_16x16x32_bf16 v[46:49], v[130:133], v[180:183], v[46:49]
	v_mfma_f32_16x16x32_bf16 v[42:45], v[138:141], v[180:183], v[42:45]
	v_mfma_f32_16x16x32_bf16 v[30:33], v[130:133], v[188:191], v[30:33]
	v_mfma_f32_16x16x32_bf16 v[26:29], v[138:141], v[188:191], v[26:29]
	v_mfma_f32_16x16x32_bf16 v[14:17], v[130:133], v[196:199], v[14:17]
	v_mfma_f32_16x16x32_bf16 v[10:13], v[138:141], v[196:199], v[10:13]
	v_mfma_f32_16x16x32_bf16 v[62:65], v[134:137], v[176:179], v[62:65]
	v_mfma_f32_16x16x32_bf16 v[58:61], v[142:145], v[176:179], v[58:61]
	v_mfma_f32_16x16x32_bf16 v[46:49], v[134:137], v[184:187], v[46:49]
	v_mfma_f32_16x16x32_bf16 v[42:45], v[142:145], v[184:187], v[42:45]
	v_mfma_f32_16x16x32_bf16 v[30:33], v[134:137], v[192:195], v[30:33]
	v_mfma_f32_16x16x32_bf16 v[26:29], v[142:145], v[192:195], v[26:29]
	v_mfma_f32_16x16x32_bf16 v[14:17], v[134:137], v[200:203], v[14:17]
	v_mfma_f32_16x16x32_bf16 v[10:13], v[142:145], v[200:203], v[10:13]
	s_setprio 0
	s_setprio 1
	v_mfma_f32_16x16x32_bf16 v[54:57], v[146:149], v[172:175], v[54:57]
	v_mfma_f32_16x16x32_bf16 v[50:53], v[154:157], v[172:175], v[50:53]
	v_mfma_f32_16x16x32_bf16 v[38:41], v[146:149], v[180:183], v[38:41]
	v_mfma_f32_16x16x32_bf16 v[34:37], v[154:157], v[180:183], v[34:37]
	v_mfma_f32_16x16x32_bf16 v[22:25], v[146:149], v[188:191], v[22:25]
	v_mfma_f32_16x16x32_bf16 v[18:21], v[154:157], v[188:191], v[18:21]
	v_mfma_f32_16x16x32_bf16 v[6:9], v[146:149], v[196:199], v[6:9]
	v_mfma_f32_16x16x32_bf16 v[2:5], v[154:157], v[196:199], v[2:5]
	v_mfma_f32_16x16x32_bf16 v[54:57], v[150:153], v[176:179], v[54:57]
	v_mfma_f32_16x16x32_bf16 v[50:53], v[168:171], v[176:179], v[50:53]
	v_mfma_f32_16x16x32_bf16 v[38:41], v[150:153], v[184:187], v[38:41]
	v_mfma_f32_16x16x32_bf16 v[34:37], v[168:171], v[184:187], v[34:37]
	v_mfma_f32_16x16x32_bf16 v[22:25], v[150:153], v[192:195], v[22:25]
	v_mfma_f32_16x16x32_bf16 v[18:21], v[168:171], v[192:195], v[18:21]
	v_mfma_f32_16x16x32_bf16 v[6:9], v[150:153], v[200:203], v[6:9]
	v_mfma_f32_16x16x32_bf16 v[2:5], v[168:171], v[200:203], v[2:5]
	s_barrier
	s_setprio 0
	s_add_i32 s24, 0, 0x18000
	s_add_i32 s62, 0, 0x1c000
	v_add_u32_e32 v142, s24, v209
	v_add_u32_e32 v168, s62, v209
	ds_read_b128 v[130:133], v142
	ds_read_b128 v[134:137], v142 offset:1024
	ds_read_b128 v[138:141], v142 offset:2048
	ds_read_b128 v[142:145], v142 offset:3072
	ds_read_b128 v[146:149], v168
	ds_read_b128 v[150:153], v168 offset:1024
	ds_read_b128 v[154:157], v168 offset:2048
	ds_read_b128 v[168:171], v168 offset:3072
	s_add_u32 s22, s22, 0x200000
	s_addc_u32 s23, s23, 0
	s_mov_b32 m0, s76
	v_lshl_add_u64 v[234:235], s[22:23], 0, v[158:159]
	ds_read_b128 v[172:175], v224 offset:32768
	ds_read_b128 v[176:179], v224 offset:33792
	ds_read_b128 v[180:183], v224 offset:34816
	ds_read_b128 v[184:187], v224 offset:35840
	ds_read_b128 v[188:191], v224 offset:36864
	ds_read_b128 v[192:195], v224 offset:37888
	ds_read_b128 v[196:199], v224 offset:38912
	ds_read_b128 v[200:203], v224 offset:39936
	global_load_lds_dwordx4 v[234:235], off
	v_lshl_add_u64 v[234:235], s[22:23], 0, v[160:161]
	s_mov_b32 m0, s77
	s_nop 0
	global_load_lds_dwordx4 v[234:235], off
	s_waitcnt vmcnt(8)
	s_waitcnt lgkmcnt(0)
	s_setprio 1
	s_barrier
	v_mfma_f32_16x16x32_bf16 v[126:129], v[130:133], v[172:175], v[126:129]
	v_mfma_f32_16x16x32_bf16 v[122:125], v[138:141], v[172:175], v[122:125]
	v_mfma_f32_16x16x32_bf16 v[110:113], v[130:133], v[180:183], v[110:113]
	v_mfma_f32_16x16x32_bf16 v[106:109], v[138:141], v[180:183], v[106:109]
	v_mfma_f32_16x16x32_bf16 v[94:97], v[130:133], v[188:191], v[94:97]
	v_mfma_f32_16x16x32_bf16 v[90:93], v[138:141], v[188:191], v[90:93]
	v_mfma_f32_16x16x32_bf16 v[78:81], v[130:133], v[196:199], v[78:81]
	v_mfma_f32_16x16x32_bf16 v[74:77], v[138:141], v[196:199], v[74:77]
	v_mfma_f32_16x16x32_bf16 v[126:129], v[134:137], v[176:179], v[126:129]
	v_mfma_f32_16x16x32_bf16 v[122:125], v[142:145], v[176:179], v[122:125]
	v_mfma_f32_16x16x32_bf16 v[110:113], v[134:137], v[184:187], v[110:113]
	v_mfma_f32_16x16x32_bf16 v[106:109], v[142:145], v[184:187], v[106:109]
	v_mfma_f32_16x16x32_bf16 v[94:97], v[134:137], v[192:195], v[94:97]
	v_mfma_f32_16x16x32_bf16 v[90:93], v[142:145], v[192:195], v[90:93]
	v_mfma_f32_16x16x32_bf16 v[78:81], v[134:137], v[200:203], v[78:81]
	v_mfma_f32_16x16x32_bf16 v[74:77], v[142:145], v[200:203], v[74:77]
	s_setprio 0
	s_setprio 1
	v_mfma_f32_16x16x32_bf16 v[118:121], v[146:149], v[172:175], v[118:121]
	v_mfma_f32_16x16x32_bf16 v[114:117], v[154:157], v[172:175], v[114:117]
	v_mfma_f32_16x16x32_bf16 v[102:105], v[146:149], v[180:183], v[102:105]
	v_mfma_f32_16x16x32_bf16 v[98:101], v[154:157], v[180:183], v[98:101]
	v_mfma_f32_16x16x32_bf16 v[86:89], v[146:149], v[188:191], v[86:89]
	v_mfma_f32_16x16x32_bf16 v[82:85], v[154:157], v[188:191], v[82:85]
	v_mfma_f32_16x16x32_bf16 v[70:73], v[146:149], v[196:199], v[70:73]
	v_mfma_f32_16x16x32_bf16 v[66:69], v[154:157], v[196:199], v[66:69]
	v_mfma_f32_16x16x32_bf16 v[118:121], v[150:153], v[176:179], v[118:121]
	v_mfma_f32_16x16x32_bf16 v[114:117], v[168:171], v[176:179], v[114:117]
	v_mfma_f32_16x16x32_bf16 v[102:105], v[150:153], v[184:187], v[102:105]
	v_mfma_f32_16x16x32_bf16 v[98:101], v[168:171], v[184:187], v[98:101]
	v_mfma_f32_16x16x32_bf16 v[86:89], v[150:153], v[192:195], v[86:89]
	v_mfma_f32_16x16x32_bf16 v[82:85], v[168:171], v[192:195], v[82:85]
	v_mfma_f32_16x16x32_bf16 v[70:73], v[150:153], v[200:203], v[70:73]
	v_mfma_f32_16x16x32_bf16 v[66:69], v[168:171], v[200:203], v[66:69]
	s_barrier
; #define PG8_BAR __builtin_amdgcn_s_barrier()
;     ...
;     for (;;) {
;         if constexpr (NSEG > 1) {
;             const char* nA = (const char*)g.A2 + (size_t)cur.pm * tstepA + (size_t)((cur.pn >> g.ash) * g.amul) * 2; const char* nB = (const char*)g.Bt2 + (size_t)cur.pn * tstepB;
;             PG8_KLOOP();
;             if (wr == 0) PG8_BAR;
;             E.mid(acc, cur, wr, wc, fr, fq);
;             cA = nA; cB = nB;
;             if (wr == 1) PG8_BAR;
;         }
;         const bool has_next = S.next(ui + 1, nxt);
;         const char* nA = has_next ? (const char*)g.A + (size_t)nxt.pm * tstepA + (size_t)((nxt.pn >> g.ash) * g.amul) * 2 : cA; const char* nB = has_next ? (const char*)g.Bt + (size_t)nxt.pn * tstepB : cB;
;         PG8_KLOOP();
;         if (wr == 0) PG8_BAR;
	s_setprio 0
	s_add_i32 s22, s24, s57
	v_lshl_add_u64 v[204:205], v[204:205], 0, s[34:35]
	s_mov_b32 m0, s22
	ds_read_b128 v[172:175], v224 offset:49152
	ds_read_b128 v[176:179], v224 offset:50176
	ds_read_b128 v[180:183], v224 offset:51200
	ds_read_b128 v[184:187], v224 offset:52224
	ds_read_b128 v[188:191], v224 offset:53248
	ds_read_b128 v[192:195], v224 offset:54272
	ds_read_b128 v[196:199], v224 offset:55296
	ds_read_b128 v[200:203], v224 offset:56320
	global_load_lds_dwordx4 v[204:205], off
	s_add_i32 m0, s22, 0x2000
	s_add_u32 s22, s26, 0x200080
	v_lshl_add_u64 v[204:205], v[214:215], 0, s[34:35]
	s_addc_u32 s23, s27, 0
	s_add_i32 s24, s62, s57
	global_load_lds_dwordx4 v[204:205], off
	v_lshl_add_u64 v[204:205], s[22:23], 0, v[0:1]
	s_mov_b32 m0, s24
	s_nop 0
	global_load_lds_dwordx4 v[204:205], off
	v_lshl_add_u64 v[204:205], s[22:23], 0, v[162:163]
	s_add_i32 m0, s24, 0x2000
	s_nop 0
	global_load_lds_dwordx4 v[204:205], off
	v_lshl_add_u64 v[204:205], v[230:231], 0, s[34:35]
	s_mov_b32 m0, s81
	s_nop 0
	global_load_lds_dwordx4 v[204:205], off
	v_lshl_add_u64 v[204:205], v[232:233], 0, s[34:35]
	s_mov_b32 m0, s82
	s_nop 0
	global_load_lds_dwordx4 v[204:205], off
	s_waitcnt vmcnt(8)
	s_waitcnt lgkmcnt(0)
	s_setprio 1
	s_barrier
	v_mfma_f32_16x16x32_bf16 v[62:65], v[130:133], v[172:175], v[62:65]
	v_mfma_f32_16x16x32_bf16 v[58:61], v[138:141], v[172:175], v[58:61]
	v_mfma_f32_16x16x32_bf16 v[46:49], v[130:133], v[180:183], v[46:49]
	v_mfma_f32_16x16x32_bf16 v[42:45], v[138:141], v[180:183], v[42:45]
	v_mfma_f32_16x16x32_bf16 v[30:33], v[130:133], v[188:191], v[30:33]
	v_mfma_f32_16x16x32_bf16 v[26:29], v[138:141], v[188:191], v[26:29]
	v_mfma_f32_16x16x32_bf16 v[14:17], v[130:133], v[196:199], v[14:17]
	v_mfma_f32_16x16x32_bf16 v[10:13], v[138:141], v[196:199], v[10:13]
	v_mfma_f32_16x16x32_bf16 v[62:65], v[134:137], v[176:179], v[62:65]
	v_mfma_f32_16x16x32_bf16 v[58:61], v[142:145], v[176:179], v[58:61]
	v_mfma_f32_16x16x32_bf16 v[46:49], v[134:137], v[184:187], v[46:49]
	v_mfma_f32_16x16x32_bf16 v[42:45], v[142:145], v[184:187], v[42:45]
	v_mfma_f32_16x16x32_bf16 v[30:33], v[134:137], v[192:195], v[30:33]
	v_mfma_f32_16x16x32_bf16 v[26:29], v[142:145], v[192:195], v[26:29]
	v_mfma_f32_16x16x32_bf16 v[14:17], v[134:137], v[200:203], v[14:17]
	v_mfma_f32_16x16x32_bf16 v[10:13], v[142:145], v[200:203], v[10:13]
	s_setprio 0
	s_setprio 1
	v_mfma_f32_16x16x32_bf16 v[54:57], v[146:149], v[172:175], v[54:57]
	v_mfma_f32_16x16x32_bf16 v[50:53], v[154:157], v[172:175], v[50:53]
	v_mfma_f32_16x16x32_bf16 v[38:41], v[146:149], v[180:183], v[38:41]
	v_mfma_f32_16x16x32_bf16 v[34:37], v[154:157], v[180:183], v[34:37]
	v_mfma_f32_16x16x32_bf16 v[22:25], v[146:149], v[188:191], v[22:25]
	v_mfma_f32_16x16x32_bf16 v[18:21], v[154:157], v[188:191], v[18:21]
	v_mfma_f32_16x16x32_bf16 v[6:9], v[146:149], v[196:199], v[6:9]
	v_mfma_f32_16x16x32_bf16 v[2:5], v[154:157], v[196:199], v[2:5]
	v_mfma_f32_16x16x32_bf16 v[54:57], v[150:153], v[176:179], v[54:57]
	v_mfma_f32_16x16x32_bf16 v[50:53], v[168:171], v[176:179], v[50:53]
	v_mfma_f32_16x16x32_bf16 v[38:41], v[150:153], v[184:187], v[38:41]
	v_mfma_f32_16x16x32_bf16 v[34:37], v[168:171], v[184:187], v[34:37]
	v_mfma_f32_16x16x32_bf16 v[22:25], v[150:153], v[192:195], v[22:25]
	v_mfma_f32_16x16x32_bf16 v[18:21], v[168:171], v[192:195], v[18:21]
	v_mfma_f32_16x16x32_bf16 v[6:9], v[150:153], v[200:203], v[6:9]
	v_mfma_f32_16x16x32_bf16 v[2:5], v[168:171], v[200:203], v[2:5]
	s_barrier
	s_setprio 0
	s_add_i32 s39, s39, 2
	s_add_u32 s46, s46, 0x100
	s_addc_u32 s47, s47, 0
	s_add_u32 s36, s36, 0x100
	s_addc_u32 s37, s37, 0
	s_cmpk_gt_u32 s39, 0x7d
	s_cbranch_scc0 .LBB0_882
	s_and_b64 vcc, exec, s[8:9]
	s_cbranch_vccz .LBB0_885
	s_barrier

.LBB0_1004:
	s_add_u32 s22, s46, 0xffe00080
	s_addc_u32 s23, s47, -1
	s_add_i32 s24, 0, 0x10000
	s_cmpk_eq_i32 s48, 0x7c
	s_cselect_b32 s23, s3, s23
	s_cselect_b32 s22, s15, s22
	s_cselect_b32 s27, s13, s37
	s_cselect_b32 s26, s21, s36
	s_add_i32 s49, 0, 0x14000
	v_add_u32_e32 v142, s24, v177
	v_add_u32_e32 v168, s49, v177
	ds_read_b128 v[130:133], v142
	ds_read_b128 v[134:137], v142 offset:1024
	ds_read_b128 v[138:141], v142 offset:2048
	ds_read_b128 v[142:145], v142 offset:3072
	ds_read_b128 v[146:149], v168
	ds_read_b128 v[150:153], v168 offset:1024
	ds_read_b128 v[164:167], v168 offset:2048
	ds_read_b128 v[168:171], v168 offset:3072
	v_lshl_add_u64 v[212:213], s[46:47], 0, v[160:161]
	s_add_i32 m0, s60, 0xc000
	ds_read_b128 v[172:175], v181
	ds_read_b128 v[184:187], v181 offset:1024
	ds_read_b128 v[188:191], v181 offset:2048
	ds_read_b128 v[192:195], v181 offset:3072
	ds_read_b128 v[196:199], v181 offset:4096
	ds_read_b128 v[200:203], v181 offset:5120
	ds_read_b128 v[204:207], v181 offset:6144
	ds_read_b128 v[208:211], v181 offset:7168
	global_load_lds_dwordx4 v[212:213], off
	v_lshl_add_u64 v[212:213], s[46:47], 0, v[162:163]
	s_add_i32 m0, s60, 0xe000
	s_nop 0
	global_load_lds_dwordx4 v[212:213], off
	s_waitcnt vmcnt(8)
	s_waitcnt lgkmcnt(0)
	s_setprio 1
	s_barrier
	v_mfma_f32_16x16x32_bf16 v[126:129], v[130:133], v[172:175], v[126:129]
	v_mfma_f32_16x16x32_bf16 v[122:125], v[138:141], v[172:175], v[122:125]
	v_mfma_f32_16x16x32_bf16 v[110:113], v[130:133], v[188:191], v[110:113]
	v_mfma_f32_16x16x32_bf16 v[106:109], v[138:141], v[188:191], v[106:109]
	v_mfma_f32_16x16x32_bf16 v[94:97], v[130:133], v[196:199], v[94:97]
	v_mfma_f32_16x16x32_bf16 v[90:93], v[138:141], v[196:199], v[90:93]
	v_mfma_f32_16x16x32_bf16 v[78:81], v[130:133], v[204:207], v[78:81]
	v_mfma_f32_16x16x32_bf16 v[74:77], v[138:141], v[204:207], v[74:77]
	v_mfma_f32_16x16x32_bf16 v[126:129], v[134:137], v[184:187], v[126:129]
	v_mfma_f32_16x16x32_bf16 v[122:125], v[142:145], v[184:187], v[122:125]
	v_mfma_f32_16x16x32_bf16 v[110:113], v[134:137], v[192:195], v[110:113]
	v_mfma_f32_16x16x32_bf16 v[106:109], v[142:145], v[192:195], v[106:109]
	v_mfma_f32_16x16x32_bf16 v[94:97], v[134:137], v[200:203], v[94:97]
	v_mfma_f32_16x16x32_bf16 v[90:93], v[142:145], v[200:203], v[90:93]
	v_mfma_f32_16x16x32_bf16 v[78:81], v[134:137], v[208:211], v[78:81]
	v_mfma_f32_16x16x32_bf16 v[74:77], v[142:145], v[208:211], v[74:77]
	s_setprio 0
	s_setprio 1
	v_mfma_f32_16x16x32_bf16 v[118:121], v[146:149], v[172:175], v[118:121]
	v_mfma_f32_16x16x32_bf16 v[114:117], v[164:167], v[172:175], v[114:117]
	v_mfma_f32_16x16x32_bf16 v[102:105], v[146:149], v[188:191], v[102:105]
	v_mfma_f32_16x16x32_bf16 v[98:101], v[164:167], v[188:191], v[98:101]
	v_mfma_f32_16x16x32_bf16 v[86:89], v[146:149], v[196:199], v[86:89]
	v_mfma_f32_16x16x32_bf16 v[82:85], v[164:167], v[196:199], v[82:85]
	v_mfma_f32_16x16x32_bf16 v[70:73], v[146:149], v[204:207], v[70:73]
	v_mfma_f32_16x16x32_bf16 v[66:69], v[164:167], v[204:207], v[66:69]
	v_mfma_f32_16x16x32_bf16 v[118:121], v[150:153], v[184:187], v[118:121]
	v_mfma_f32_16x16x32_bf16 v[114:117], v[168:171], v[184:187], v[114:117]
	v_mfma_f32_16x16x32_bf16 v[102:105], v[150:153], v[192:195], v[102:105]
	v_mfma_f32_16x16x32_bf16 v[98:101], v[168:171], v[192:195], v[98:101]
	v_mfma_f32_16x16x32_bf16 v[86:89], v[150:153], v[200:203], v[86:89]
	v_mfma_f32_16x16x32_bf16 v[82:85], v[168:171], v[200:203], v[82:85]
	v_mfma_f32_16x16x32_bf16 v[70:73], v[150:153], v[208:211], v[70:73]
	v_mfma_f32_16x16x32_bf16 v[66:69], v[168:171], v[208:211], v[66:69]
	s_barrier
	s_setprio 0
	s_add_i32 s24, s24, s57
	v_lshl_add_u64 v[212:213], s[26:27], 0, v[0:1]
	s_mov_b32 m0, s24
	ds_read_b128 v[172:175], v181 offset:16384
	ds_read_b128 v[184:187], v181 offset:17408
	ds_read_b128 v[188:191], v181 offset:18432
	ds_read_b128 v[192:195], v181 offset:19456
	ds_read_b128 v[196:199], v181 offset:20480
	ds_read_b128 v[200:203], v181 offset:21504
	ds_read_b128 v[204:207], v181 offset:22528
	ds_read_b128 v[208:211], v181 offset:23552
	global_load_lds_dwordx4 v[212:213], off
	s_add_i32 m0, s24, 0x2000
	s_add_u32 s50, s26, 0x200000
	v_lshl_add_u64 v[214:215], s[26:27], 0, v[158:159]
	s_addc_u32 s51, s27, 0
	s_add_i32 s24, s49, s57
	global_load_lds_dwordx4 v[214:215], off
	v_lshl_add_u64 v[216:217], s[50:51], 0, v[0:1]
	s_mov_b32 m0, s24
	v_lshl_add_u64 v[218:219], s[22:23], 0, v[156:157]
	global_load_lds_dwordx4 v[216:217], off
	v_lshl_add_u64 v[216:217], s[50:51], 0, v[158:159]
	s_add_i32 m0, s24, 0x2000
	s_nop 0
	global_load_lds_dwordx4 v[216:217], off
	v_lshl_add_u64 v[216:217], s[22:23], 0, v[154:155]
	s_mov_b32 m0, s60
	s_nop 0
	global_load_lds_dwordx4 v[216:217], off
	s_mov_b32 m0, s61
	s_nop 0
	global_load_lds_dwordx4 v[218:219], off
	s_waitcnt vmcnt(8)
	s_waitcnt lgkmcnt(0)
	s_setprio 1
	s_barrier
	v_mfma_f32_16x16x32_bf16 v[62:65], v[130:133], v[172:175], v[62:65]
	v_mfma_f32_16x16x32_bf16 v[58:61], v[138:141], v[172:175], v[58:61]
	v_mfma_f32_16x16x32_bf16 v[46:49], v[130:133], v[188:191], v[46:49]
	v_mfma_f32_16x16x32_bf16 v[42:45], v[138:141], v[188:191], v[42:45]
	v_mfma_f32_16x16x32_bf16 v[30:33], v[130:133], v[196:199], v[30:33]
	v_mfma_f32_16x16x32_bf16 v[26:29], v[138:141], v[196:199], v[26:29]
	v_mfma_f32_16x16x32_bf16 v[14:17], v[130:133], v[204:207], v[14:17]
	v_mfma_f32_16x16x32_bf16 v[10:13], v[138:141], v[204:207], v[10:13]
	v_mfma_f32_16x16x32_bf16 v[62:65], v[134:137], v[184:187], v[62:65]
	v_mfma_f32_16x16x32_bf16 v[58:61], v[142:145], v[184:187], v[58:61]
	v_mfma_f32_16x16x32_bf16 v[46:49], v[134:137], v[192:195], v[46:49]
	v_mfma_f32_16x16x32_bf16 v[42:45], v[142:145], v[192:195], v[42:45]
	v_mfma_f32_16x16x32_bf16 v[30:33], v[134:137], v[200:203], v[30:33]
	v_mfma_f32_16x16x32_bf16 v[26:29], v[142:145], v[200:203], v[26:29]
	v_mfma_f32_16x16x32_bf16 v[14:17], v[134:137], v[208:211], v[14:17]
	v_mfma_f32_16x16x32_bf16 v[10:13], v[142:145], v[208:211], v[10:13]
	s_setprio 0
	s_setprio 1
	v_mfma_f32_16x16x32_bf16 v[54:57], v[146:149], v[172:175], v[54:57]
	v_mfma_f32_16x16x32_bf16 v[50:53], v[164:167], v[172:175], v[50:53]
	v_mfma_f32_16x16x32_bf16 v[38:41], v[146:149], v[188:191], v[38:41]
	v_mfma_f32_16x16x32_bf16 v[34:37], v[164:167], v[188:191], v[34:37]
	v_mfma_f32_16x16x32_bf16 v[22:25], v[146:149], v[196:199], v[22:25]
	v_mfma_f32_16x16x32_bf16 v[18:21], v[164:167], v[196:199], v[18:21]
	v_mfma_f32_16x16x32_bf16 v[6:9], v[146:149], v[204:207], v[6:9]
	v_mfma_f32_16x16x32_bf16 v[2:5], v[164:167], v[204:207], v[2:5]
	v_mfma_f32_16x16x32_bf16 v[54:57], v[150:153], v[184:187], v[54:57]
	v_mfma_f32_16x16x32_bf16 v[50:53], v[168:171], v[184:187], v[50:53]
	v_mfma_f32_16x16x32_bf16 v[38:41], v[150:153], v[192:195], v[38:41]
	v_mfma_f32_16x16x32_bf16 v[34:37], v[168:171], v[192:195], v[34:37]
	v_mfma_f32_16x16x32_bf16 v[22:25], v[150:153], v[200:203], v[22:25]
	v_mfma_f32_16x16x32_bf16 v[18:21], v[168:171], v[200:203], v[18:21]
	v_mfma_f32_16x16x32_bf16 v[6:9], v[150:153], v[208:211], v[6:9]
	v_mfma_f32_16x16x32_bf16 v[2:5], v[168:171], v[208:211], v[2:5]
	s_barrier
	s_setprio 0
	s_add_i32 s24, 0, 0x18000
	s_add_i32 s49, 0, 0x1c000
	v_add_u32_e32 v142, s24, v177
	v_add_u32_e32 v168, s49, v177
	ds_read_b128 v[130:133], v142
	ds_read_b128 v[134:137], v142 offset:1024
	ds_read_b128 v[138:141], v142 offset:2048
	ds_read_b128 v[142:145], v142 offset:3072
	ds_read_b128 v[146:149], v168
	ds_read_b128 v[150:153], v168 offset:1024
	ds_read_b128 v[164:167], v168 offset:2048
	ds_read_b128 v[168:171], v168 offset:3072
	s_add_u32 s22, s22, 0x200000
	s_addc_u32 s23, s23, 0
	s_mov_b32 m0, s62
	v_lshl_add_u64 v[220:221], s[22:23], 0, v[154:155]
	ds_read_b128 v[172:175], v181 offset:32768
	ds_read_b128 v[184:187], v181 offset:33792
	ds_read_b128 v[188:191], v181 offset:34816
	ds_read_b128 v[192:195], v181 offset:35840
	ds_read_b128 v[196:199], v181 offset:36864
	ds_read_b128 v[200:203], v181 offset:37888
	ds_read_b128 v[204:207], v181 offset:38912
	ds_read_b128 v[208:211], v181 offset:39936
	global_load_lds_dwordx4 v[220:221], off
	v_lshl_add_u64 v[220:221], s[22:23], 0, v[156:157]
	s_mov_b32 m0, s63
	s_nop 0
	global_load_lds_dwordx4 v[220:221], off
	s_waitcnt vmcnt(8)
	s_waitcnt lgkmcnt(0)
	s_setprio 1
	s_barrier
	v_mfma_f32_16x16x32_bf16 v[126:129], v[130:133], v[172:175], v[126:129]
	v_mfma_f32_16x16x32_bf16 v[122:125], v[138:141], v[172:175], v[122:125]
	v_mfma_f32_16x16x32_bf16 v[110:113], v[130:133], v[188:191], v[110:113]
	v_mfma_f32_16x16x32_bf16 v[106:109], v[138:141], v[188:191], v[106:109]
	v_mfma_f32_16x16x32_bf16 v[94:97], v[130:133], v[196:199], v[94:97]
	v_mfma_f32_16x16x32_bf16 v[90:93], v[138:141], v[196:199], v[90:93]
	v_mfma_f32_16x16x32_bf16 v[78:81], v[130:133], v[204:207], v[78:81]
	v_mfma_f32_16x16x32_bf16 v[74:77], v[138:141], v[204:207], v[74:77]
	v_mfma_f32_16x16x32_bf16 v[126:129], v[134:137], v[184:187], v[126:129]
	v_mfma_f32_16x16x32_bf16 v[122:125], v[142:145], v[184:187], v[122:125]
	v_mfma_f32_16x16x32_bf16 v[110:113], v[134:137], v[192:195], v[110:113]
	v_mfma_f32_16x16x32_bf16 v[106:109], v[142:145], v[192:195], v[106:109]
	v_mfma_f32_16x16x32_bf16 v[94:97], v[134:137], v[200:203], v[94:97]
	v_mfma_f32_16x16x32_bf16 v[90:93], v[142:145], v[200:203], v[90:93]
	v_mfma_f32_16x16x32_bf16 v[78:81], v[134:137], v[208:211], v[78:81]
	v_mfma_f32_16x16x32_bf16 v[74:77], v[142:145], v[208:211], v[74:77]
	s_setprio 0
	s_setprio 1
	v_mfma_f32_16x16x32_bf16 v[118:121], v[146:149], v[172:175], v[118:121]
	v_mfma_f32_16x16x32_bf16 v[114:117], v[164:167], v[172:175], v[114:117]
	v_mfma_f32_16x16x32_bf16 v[102:105], v[146:149], v[188:191], v[102:105]
	v_mfma_f32_16x16x32_bf16 v[98:101], v[164:167], v[188:191], v[98:101]
	v_mfma_f32_16x16x32_bf16 v[86:89], v[146:149], v[196:199], v[86:89]
	v_mfma_f32_16x16x32_bf16 v[82:85], v[164:167], v[196:199], v[82:85]
	v_mfma_f32_16x16x32_bf16 v[70:73], v[146:149], v[204:207], v[70:73]
	v_mfma_f32_16x16x32_bf16 v[66:69], v[164:167], v[204:207], v[66:69]
	v_mfma_f32_16x16x32_bf16 v[118:121], v[150:153], v[184:187], v[118:121]
	v_mfma_f32_16x16x32_bf16 v[114:117], v[168:171], v[184:187], v[114:117]
	v_mfma_f32_16x16x32_bf16 v[102:105], v[150:153], v[192:195], v[102:105]
	v_mfma_f32_16x16x32_bf16 v[98:101], v[168:171], v[192:195], v[98:101]
	v_mfma_f32_16x16x32_bf16 v[86:89], v[150:153], v[200:203], v[86:89]
	v_mfma_f32_16x16x32_bf16 v[82:85], v[168:171], v[200:203], v[82:85]
	v_mfma_f32_16x16x32_bf16 v[70:73], v[150:153], v[208:211], v[70:73]
	v_mfma_f32_16x16x32_bf16 v[66:69], v[168:171], v[208:211], v[66:69]
	s_barrier
	s_setprio 0
	s_add_i32 s22, s24, s57
	v_lshl_add_u64 v[212:213], v[212:213], 0, s[34:35]
	s_mov_b32 m0, s22
	ds_read_b128 v[172:175], v181 offset:49152
	ds_read_b128 v[184:187], v181 offset:50176
	ds_read_b128 v[188:191], v181 offset:51200
	ds_read_b128 v[192:195], v181 offset:52224
	ds_read_b128 v[196:199], v181 offset:53248
	ds_read_b128 v[200:203], v181 offset:54272
	ds_read_b128 v[204:207], v181 offset:55296
	ds_read_b128 v[208:211], v181 offset:56320
	global_load_lds_dwordx4 v[212:213], off
	s_add_i32 m0, s22, 0x2000
	s_add_u32 s22, s26, 0x200080
	v_lshl_add_u64 v[212:213], v[214:215], 0, s[34:35]
	s_addc_u32 s23, s27, 0
	s_add_i32 s24, s49, s57
	global_load_lds_dwordx4 v[212:213], off
	v_lshl_add_u64 v[212:213], s[22:23], 0, v[0:1]
	s_mov_b32 m0, s24
	s_nop 0
	global_load_lds_dwordx4 v[212:213], off
	v_lshl_add_u64 v[212:213], s[22:23], 0, v[158:159]
	s_add_i32 m0, s24, 0x2000
	s_nop 0
	global_load_lds_dwordx4 v[212:213], off
	v_lshl_add_u64 v[212:213], v[216:217], 0, s[34:35]
	s_mov_b32 m0, s74
	s_nop 0
	global_load_lds_dwordx4 v[212:213], off
	v_lshl_add_u64 v[212:213], v[218:219], 0, s[34:35]
	s_mov_b32 m0, s75
	s_nop 0
	global_load_lds_dwordx4 v[212:213], off
	s_waitcnt vmcnt(8)
	s_waitcnt lgkmcnt(0)
	s_setprio 1
	s_barrier
	v_mfma_f32_16x16x32_bf16 v[62:65], v[130:133], v[172:175], v[62:65]
	v_mfma_f32_16x16x32_bf16 v[58:61], v[138:141], v[172:175], v[58:61]
	v_mfma_f32_16x16x32_bf16 v[46:49], v[130:133], v[188:191], v[46:49]
	v_mfma_f32_16x16x32_bf16 v[42:45], v[138:141], v[188:191], v[42:45]
	v_mfma_f32_16x16x32_bf16 v[30:33], v[130:133], v[196:199], v[30:33]
	v_mfma_f32_16x16x32_bf16 v[26:29], v[138:141], v[196:199], v[26:29]
	v_mfma_f32_16x16x32_bf16 v[14:17], v[130:133], v[204:207], v[14:17]
	v_mfma_f32_16x16x32_bf16 v[10:13], v[138:141], v[204:207], v[10:13]
	v_mfma_f32_16x16x32_bf16 v[62:65], v[134:137], v[184:187], v[62:65]
	v_mfma_f32_16x16x32_bf16 v[58:61], v[142:145], v[184:187], v[58:61]
	v_mfma_f32_16x16x32_bf16 v[46:49], v[134:137], v[192:195], v[46:49]
	v_mfma_f32_16x16x32_bf16 v[42:45], v[142:145], v[192:195], v[42:45]
	v_mfma_f32_16x16x32_bf16 v[30:33], v[134:137], v[200:203], v[30:33]
	v_mfma_f32_16x16x32_bf16 v[26:29], v[142:145], v[200:203], v[26:29]
	v_mfma_f32_16x16x32_bf16 v[14:17], v[134:137], v[208:211], v[14:17]
	v_mfma_f32_16x16x32_bf16 v[10:13], v[142:145], v[208:211], v[10:13]
	s_setprio 0
	s_setprio 1
	v_mfma_f32_16x16x32_bf16 v[54:57], v[146:149], v[172:175], v[54:57]
	v_mfma_f32_16x16x32_bf16 v[50:53], v[164:167], v[172:175], v[50:53]
	v_mfma_f32_16x16x32_bf16 v[38:41], v[146:149], v[188:191], v[38:41]
	v_mfma_f32_16x16x32_bf16 v[34:37], v[164:167], v[188:191], v[34:37]
	v_mfma_f32_16x16x32_bf16 v[22:25], v[146:149], v[196:199], v[22:25]
	v_mfma_f32_16x16x32_bf16 v[18:21], v[164:167], v[196:199], v[18:21]
	v_mfma_f32_16x16x32_bf16 v[6:9], v[146:149], v[204:207], v[6:9]
	v_mfma_f32_16x16x32_bf16 v[2:5], v[164:167], v[204:207], v[2:5]
	v_mfma_f32_16x16x32_bf16 v[54:57], v[150:153], v[184:187], v[54:57]
	v_mfma_f32_16x16x32_bf16 v[50:53], v[168:171], v[184:187], v[50:53]
	v_mfma_f32_16x16x32_bf16 v[38:41], v[150:153], v[192:195], v[38:41]
	v_mfma_f32_16x16x32_bf16 v[34:37], v[168:171], v[192:195], v[34:37]
	v_mfma_f32_16x16x32_bf16 v[22:25], v[150:153], v[200:203], v[22:25]
	v_mfma_f32_16x16x32_bf16 v[18:21], v[168:171], v[200:203], v[18:21]
	v_mfma_f32_16x16x32_bf16 v[6:9], v[150:153], v[208:211], v[6:9]
	v_mfma_f32_16x16x32_bf16 v[2:5], v[168:171], v[208:211], v[2:5]
	s_barrier
	s_setprio 0
	s_add_i32 s48, s48, 2
	s_add_u32 s46, s46, 0x100
	s_addc_u32 s47, s47, 0
	s_add_u32 s36, s36, 0x100
	s_addc_u32 s37, s37, 0
	s_cmpk_gt_u32 s48, 0x7d
	s_cbranch_scc0 .LBB0_1004
	s_and_b64 vcc, exec, s[10:11]
	s_cbranch_vccz .LBB0_1007
	s_barrier

; __global__ void __launch_bounds__(512, 2) fwd_megakernel(Args a_unused) {
	.amdhsa_kernel _Z14fwd_megakernel4Args
		.amdhsa_group_segment_fixed_size 0
		.amdhsa_private_segment_fixed_size 0
		.amdhsa_kernarg_size 424
		.amdhsa_user_sgpr_count 2
		.amdhsa_user_sgpr_dispatch_ptr 0
		.amdhsa_user_sgpr_queue_ptr 0
		.amdhsa_user_sgpr_kernarg_segment_ptr 1
		.amdhsa_user_sgpr_dispatch_id 0
		.amdhsa_user_sgpr_kernarg_preload_length 0
		.amdhsa_user_sgpr_kernarg_preload_offset 0
		.amdhsa_user_sgpr_private_segment_size 0
		.amdhsa_uses_dynamic_stack 0
		.amdhsa_enable_private_segment 0
		.amdhsa_system_sgpr_workgroup_id_x 1
		.amdhsa_system_sgpr_workgroup_id_y 0
		.amdhsa_system_sgpr_workgroup_id_z 0
		.amdhsa_system_sgpr_workgroup_info 0
		.amdhsa_system_vgpr_workitem_id 2
		.amdhsa_next_free_vgpr 255
		.amdhsa_next_free_sgpr 102
		.amdhsa_accum_offset 256
		.amdhsa_reserve_vcc 1
		.amdhsa_float_round_mode_32 0
		.amdhsa_float_round_mode_16_64 0
		.amdhsa_float_denorm_mode_32 3
		.amdhsa_float_denorm_mode_16_64 3
		.amdhsa_dx10_clamp 1
		.amdhsa_ieee_mode 1
		.amdhsa_fp16_overflow 0
		.amdhsa_tg_split 0
		.amdhsa_exception_fp_ieee_invalid_op 0
		.amdhsa_exception_fp_denorm_src 0
		.amdhsa_exception_fp_ieee_div_zero 0
		.amdhsa_exception_fp_ieee_overflow 0
		.amdhsa_exception_fp_ieee_underflow 0
		.amdhsa_exception_fp_ieee_inexact 0
		.amdhsa_exception_int_div_zero 0
	.end_amdhsa_kernel

; __global__ void __launch_bounds__(512, 2) fwd_megakernel(Args a_unused) {
amdhsa.kernels:
  - .agpr_count:     0
    .args:
      - .offset:         0
        .size:           168
        .value_kind:     by_value
      - .offset:         168
        .size:           4
        .value_kind:     hidden_block_count_x
      - .offset:         172
        .size:           4
        .value_kind:     hidden_block_count_y
      - .offset:         176
        .size:           4
        .value_kind:     hidden_block_count_z
      - .offset:         180
        .size:           2
        .value_kind:     hidden_group_size_x
      - .offset:         182
        .size:           2
        .value_kind:     hidden_group_size_y
      - .offset:         184
        .size:           2
        .value_kind:     hidden_group_size_z
      - .offset:         186
        .size:           2
        .value_kind:     hidden_remainder_x
      - .offset:         188
        .size:           2
        .value_kind:     hidden_remainder_y
      - .offset:         190
        .size:           2
        .value_kind:     hidden_remainder_z
      - .offset:         208
        .size:           8
        .value_kind:     hidden_global_offset_x
      - .offset:         216
        .size:           8
        .value_kind:     hidden_global_offset_y
      - .offset:         224
        .size:           8
        .value_kind:     hidden_global_offset_z
      - .offset:         232
        .size:           2
        .value_kind:     hidden_grid_dims
      - .offset:         256
        .size:           8
        .value_kind:     hidden_multigrid_sync_arg
      - .offset:         288
        .size:           4
        .value_kind:     hidden_dynamic_lds_size
    .group_segment_fixed_size: 0
    .kernarg_segment_align: 8
    .kernarg_segment_size: 424
    .language:       OpenCL C
    .language_version:
      - 2
      - 0
    .max_flat_workgroup_size: 512
    .name:           _Z14fwd_megakernel4Args
    .private_segment_fixed_size: 0
    .sgpr_count:     108
    .sgpr_spill_count: 132
    .symbol:         _Z14fwd_megakernel4Args.kd
    .uniform_work_group_size: 1
    .uses_dynamic_stack: false
    .vgpr_count:     255
    .vgpr_spill_count: 0
    .wavefront_size: 64
